# combo32: combo23 + the 28 redundant s_waitcnt lgkmcnt(0) that follow each compute segment's barrier in the GEMM K-loops deleted (an identical wait already precedes the barrier)
# baseline (speedup 1.0000x reference)
; #define PG8_STAGE(bufoff, gbase, voff) do { _Pragma("unroll") for (int _i = 0; _i < 2; ++_i) \
;         __builtin_amdgcn_global_load_lds((const unsigned*)((const char*)(gbase) + (voff)[_i]), (PG8_LAS unsigned*)(lds + (bufoff) + ldsw + _i * 8192), 16, 0, 0); } while (0)
; #define PG8_LDA(dst, b, h) do { _Pragma("unroll") for (int m = 0; m < 4; ++m) _Pragma("unroll") for (int k = 0; k < 2; ++k) dst[m][k] = *(const PG8_LAS bf16x8*)(lds + PG8_SA(b, h) + aoff + m * 2048 + k * 1024); } while (0)
; #define PG8_LDB(dst, b, h) do { _Pragma("unroll") for (int n = 0; n < 2; ++n) _Pragma("unroll") for (int k = 0; k < 2; ++k) dst[n][k] = *(const PG8_LAS bf16x8*)(lds + PG8_SB(b, h) + boff + n * 2048 + k * 1024); } while (0)
; #define PG8_MMA(ai, bj, At, Bt) do { __builtin_amdgcn_s_setprio(1); _Pragma("unroll") for (int m = 0; m < 4; ++m) _Pragma("unroll") for (int n = 0; n < 2; ++n) _Pragma("unroll") for (int k = 0; k < 2; ++k) \
;         acc[ai][bj][m][n] = __builtin_amdgcn_mfma_f32_16x16x32_bf16(Bt[n][k], At[m][k], acc[ai][bj][m][n], 0, 0, 0); __builtin_amdgcn_s_setprio(0); } while (0)
; #define PG8_WAIT_V(n) asm volatile("s_waitcnt vmcnt(" #n ")" ::: "memory")
; #define PG8_WAIT_L(n) asm volatile("s_waitcnt lgkmcnt(" #n ")" ::: "memory")
; template <class Epi, class Sched, bool ALIGN_EPI = false, bool SP2 = false>
; __device__ __forceinline__ void gemm_phase(PG8_LAS unsigned char* lds, const Gemm g, const Sched& S, const Epi& E) {
;     ...
;             const bool last = (t == nt - 2);
;             const char* a1 = cA + (size_t)(t + 1) * kstep;
;             const char* a2 = last ? nA : cA + (size_t)(t + 2) * kstep; const char* b2 = last ? nB : cB + (size_t)(t + 2) * kstep;
;             const char* a3 = a2 + kstep; const char* b3 = b2 + kstep;
;             if (last && has_next) S.a_ready(nxt);
;             if constexpr (SP2) {
;             PG8_LDB(B0, 0, 0); PG8_LDB(B1, 0, 1); PG8_SCHED; PG8_LDA(At, 0, 0); PG8_STAGE(PG8_SA(1, 1), a1 + hstep, voffA);
;             PG8_WAIT_V(8); PG8_WAIT_L(0); PG8_BAR; PG8_MMA(0, 0, At, B0); PG8_MMA(0, 1, At, B1); PG8_BAR; PG8_SCHED;
;             PG8_LDA(At, 0, 1); PG8_STAGE(PG8_SB(0, 0), b2, voffB); PG8_STAGE(PG8_SB(0, 1), b2 + hstep, voffB); PG8_STAGE(PG8_SA(0, 0), a2, voffA);
;             PG8_WAIT_V(8); PG8_WAIT_L(0); PG8_BAR; PG8_MMA(1, 0, At, B0); PG8_MMA(1, 1, At, B1); PG8_BAR; PG8_SCHED;
.LBB0_212:
	s_add_u32 s18, s2, 0xfffc0080
	s_addc_u32 s19, s3, -1
	s_add_i32 s41, 0, 0x10000
	s_cmp_eq_u32 s40, 12
	s_cselect_b32 s21, s11, s19
	s_cselect_b32 s20, s34, s18
	s_cselect_b32 s19, s13, s37
	s_cselect_b32 s18, s35, s36
	s_add_i32 s44, 0, 0x14000
	v_add_u32_e32 v140, s41, v169
	v_add_u32_e32 v158, s44, v169
	ds_read_b128 v[128:131], v140
	ds_read_b128 v[132:135], v140 offset:1024
	ds_read_b128 v[136:139], v140 offset:2048
	ds_read_b128 v[140:143], v140 offset:3072
	ds_read_b128 v[154:157], v158
	ds_read_b128 v[172:175], v158 offset:1024
	ds_read_b128 v[176:179], v158 offset:2048
	ds_read_b128 v[180:183], v158 offset:3072
	v_lshl_add_u64 v[158:159], s[2:3], 0, v[150:151]
	s_add_i32 m0, s23, 0xc000
	ds_read_b128 v[184:187], v171
	ds_read_b128 v[206:209], v171 offset:1024
	ds_read_b128 v[210:213], v171 offset:2048
	ds_read_b128 v[214:217], v171 offset:3072
	ds_read_b128 v[218:221], v171 offset:4096
	ds_read_b128 v[222:225], v171 offset:5120
	ds_read_b128 v[226:229], v171 offset:6144
	ds_read_b128 v[230:233], v171 offset:7168
	global_load_lds_dwordx4 v[158:159], off
	v_lshl_add_u64 v[158:159], s[2:3], 0, v[152:153]
	s_add_i32 m0, s23, 0xe000
	s_nop 0
	global_load_lds_dwordx4 v[158:159], off
	s_waitcnt vmcnt(8)
	s_waitcnt lgkmcnt(0)
	s_barrier
	s_setprio 1
	v_mfma_f32_16x16x32_bf16 v[124:127], v[128:131], v[184:187], v[124:127]
	v_mfma_f32_16x16x32_bf16 v[120:123], v[136:139], v[184:187], v[120:123]
	v_mfma_f32_16x16x32_bf16 v[108:111], v[128:131], v[210:213], v[108:111]
	v_mfma_f32_16x16x32_bf16 v[104:107], v[136:139], v[210:213], v[104:107]
	v_mfma_f32_16x16x32_bf16 v[92:95], v[128:131], v[218:221], v[92:95]
	v_mfma_f32_16x16x32_bf16 v[88:91], v[136:139], v[218:221], v[88:91]
	v_mfma_f32_16x16x32_bf16 v[76:79], v[128:131], v[226:229], v[76:79]
	v_mfma_f32_16x16x32_bf16 v[72:75], v[136:139], v[226:229], v[72:75]
	v_mfma_f32_16x16x32_bf16 v[124:127], v[132:135], v[206:209], v[124:127]
	v_mfma_f32_16x16x32_bf16 v[120:123], v[140:143], v[206:209], v[120:123]
	v_mfma_f32_16x16x32_bf16 v[108:111], v[132:135], v[214:217], v[108:111]
	v_mfma_f32_16x16x32_bf16 v[104:107], v[140:143], v[214:217], v[104:107]
	v_mfma_f32_16x16x32_bf16 v[92:95], v[132:135], v[222:225], v[92:95]
	v_mfma_f32_16x16x32_bf16 v[88:91], v[140:143], v[222:225], v[88:91]
	v_mfma_f32_16x16x32_bf16 v[76:79], v[132:135], v[230:233], v[76:79]
	v_mfma_f32_16x16x32_bf16 v[72:75], v[140:143], v[230:233], v[72:75]
	s_setprio 0
	s_setprio 1
	v_mfma_f32_16x16x32_bf16 v[116:119], v[154:157], v[184:187], v[116:119]
	v_mfma_f32_16x16x32_bf16 v[112:115], v[176:179], v[184:187], v[112:115]
	v_mfma_f32_16x16x32_bf16 v[100:103], v[154:157], v[210:213], v[100:103]
	v_mfma_f32_16x16x32_bf16 v[96:99], v[176:179], v[210:213], v[96:99]
	v_mfma_f32_16x16x32_bf16 v[84:87], v[154:157], v[218:221], v[84:87]
	v_mfma_f32_16x16x32_bf16 v[80:83], v[176:179], v[218:221], v[80:83]
	v_mfma_f32_16x16x32_bf16 v[68:71], v[154:157], v[226:229], v[68:71]
	v_mfma_f32_16x16x32_bf16 v[64:67], v[176:179], v[226:229], v[64:67]
	v_mfma_f32_16x16x32_bf16 v[116:119], v[172:175], v[206:209], v[116:119]
	v_mfma_f32_16x16x32_bf16 v[112:115], v[180:183], v[206:209], v[112:115]
	v_mfma_f32_16x16x32_bf16 v[100:103], v[172:175], v[214:217], v[100:103]
	v_mfma_f32_16x16x32_bf16 v[96:99], v[180:183], v[214:217], v[96:99]
	v_mfma_f32_16x16x32_bf16 v[84:87], v[172:175], v[222:225], v[84:87]
	v_mfma_f32_16x16x32_bf16 v[80:83], v[180:183], v[222:225], v[80:83]
	v_mfma_f32_16x16x32_bf16 v[68:71], v[172:175], v[230:233], v[68:71]
	v_mfma_f32_16x16x32_bf16 v[64:67], v[180:183], v[230:233], v[64:67]
	s_setprio 0
	s_barrier
	s_add_i32 s41, s41, s22
	v_lshl_add_u64 v[158:159], s[18:19], 0, v[160:161]
	s_mov_b32 m0, s41
	ds_read_b128 v[184:187], v171 offset:16384
	ds_read_b128 v[206:209], v171 offset:17408
	ds_read_b128 v[210:213], v171 offset:18432
	ds_read_b128 v[214:217], v171 offset:19456
	ds_read_b128 v[218:221], v171 offset:20480
	ds_read_b128 v[222:225], v171 offset:21504
	ds_read_b128 v[226:229], v171 offset:22528
	ds_read_b128 v[230:233], v171 offset:23552
	global_load_lds_dwordx4 v[158:159], off
	s_add_i32 m0, s41, 0x2000
	s_add_u32 s42, s18, 0x40000
	v_lshl_add_u64 v[162:163], s[18:19], 0, v[144:145]
	s_addc_u32 s43, s19, 0
	s_add_i32 s41, s44, s22
	global_load_lds_dwordx4 v[162:163], off
	v_lshl_add_u64 v[164:165], s[42:43], 0, v[160:161]
	s_mov_b32 m0, s41
	v_lshl_add_u64 v[188:189], s[20:21], 0, v[146:147]
	global_load_lds_dwordx4 v[164:165], off
	v_lshl_add_u64 v[164:165], s[42:43], 0, v[144:145]
	s_add_i32 m0, s41, 0x2000
	s_nop 0
	global_load_lds_dwordx4 v[164:165], off
	v_lshl_add_u64 v[164:165], s[20:21], 0, v[148:149]
	s_mov_b32 m0, s23
	s_nop 0
	global_load_lds_dwordx4 v[164:165], off
	s_mov_b32 m0, s24
	s_nop 0
	global_load_lds_dwordx4 v[188:189], off
	s_waitcnt vmcnt(8)
	s_waitcnt lgkmcnt(0)
	s_barrier
; #define PG8_STAGE(bufoff, gbase, voff) do { _Pragma("unroll") for (int _i = 0; _i < 2; ++_i) \
;         __builtin_amdgcn_global_load_lds((const unsigned*)((const char*)(gbase) + (voff)[_i]), (PG8_LAS unsigned*)(lds + (bufoff) + ldsw + _i * 8192), 16, 0, 0); } while (0)
; #define PG8_LDA(dst, b, h) do { _Pragma("unroll") for (int m = 0; m < 4; ++m) _Pragma("unroll") for (int k = 0; k < 2; ++k) dst[m][k] = *(const PG8_LAS bf16x8*)(lds + PG8_SA(b, h) + aoff + m * 2048 + k * 1024); } while (0)
; #define PG8_LDB(dst, b, h) do { _Pragma("unroll") for (int n = 0; n < 2; ++n) _Pragma("unroll") for (int k = 0; k < 2; ++k) dst[n][k] = *(const PG8_LAS bf16x8*)(lds + PG8_SB(b, h) + boff + n * 2048 + k * 1024); } while (0)
; #define PG8_MMA(ai, bj, At, Bt) do { __builtin_amdgcn_s_setprio(1); _Pragma("unroll") for (int m = 0; m < 4; ++m) _Pragma("unroll") for (int n = 0; n < 2; ++n) _Pragma("unroll") for (int k = 0; k < 2; ++k) \
;         acc[ai][bj][m][n] = __builtin_amdgcn_mfma_f32_16x16x32_bf16(Bt[n][k], At[m][k], acc[ai][bj][m][n], 0, 0, 0); __builtin_amdgcn_s_setprio(0); } while (0)
; #define PG8_WAIT_V(n) asm volatile("s_waitcnt vmcnt(" #n ")" ::: "memory")
; #define PG8_WAIT_L(n) asm volatile("s_waitcnt lgkmcnt(" #n ")" ::: "memory")
; #define PG8_BAR __builtin_amdgcn_s_barrier()
; #define PG8_SCHED __builtin_amdgcn_sched_barrier(0)
; template <class Epi, class Sched, bool ALIGN_EPI = false, bool SP2 = false>
; __device__ __forceinline__ void gemm_phase(PG8_LAS unsigned char* lds, const Gemm g, const Sched& S, const Epi& E) {
;     ...
;             PG8_WAIT_V(8); PG8_WAIT_L(0); PG8_BAR; PG8_MMA(1, 0, At, B0); PG8_MMA(1, 1, At, B1); PG8_BAR; PG8_SCHED;
;             PG8_LDB(B0, 1, 0); PG8_LDB(B1, 1, 1); PG8_SCHED; PG8_LDA(At, 1, 0); PG8_STAGE(PG8_SA(0, 1), a2 + hstep, voffA);
;             PG8_WAIT_V(8); PG8_WAIT_L(0); PG8_BAR; PG8_MMA(0, 0, At, B0); PG8_MMA(0, 1, At, B1); PG8_BAR; PG8_SCHED;
	s_setprio 1
	v_mfma_f32_16x16x32_bf16 v[60:63], v[128:131], v[184:187], v[60:63]
	v_mfma_f32_16x16x32_bf16 v[56:59], v[136:139], v[184:187], v[56:59]
	v_mfma_f32_16x16x32_bf16 v[44:47], v[128:131], v[210:213], v[44:47]
	v_mfma_f32_16x16x32_bf16 v[40:43], v[136:139], v[210:213], v[40:43]
	v_mfma_f32_16x16x32_bf16 v[28:31], v[128:131], v[218:221], v[28:31]
	v_mfma_f32_16x16x32_bf16 v[24:27], v[136:139], v[218:221], v[24:27]
	v_mfma_f32_16x16x32_bf16 v[12:15], v[128:131], v[226:229], v[12:15]
	v_mfma_f32_16x16x32_bf16 v[8:11], v[136:139], v[226:229], v[8:11]
	v_mfma_f32_16x16x32_bf16 v[60:63], v[132:135], v[206:209], v[60:63]
	v_mfma_f32_16x16x32_bf16 v[56:59], v[140:143], v[206:209], v[56:59]
	v_mfma_f32_16x16x32_bf16 v[44:47], v[132:135], v[214:217], v[44:47]
	v_mfma_f32_16x16x32_bf16 v[40:43], v[140:143], v[214:217], v[40:43]
	v_mfma_f32_16x16x32_bf16 v[28:31], v[132:135], v[222:225], v[28:31]
	v_mfma_f32_16x16x32_bf16 v[24:27], v[140:143], v[222:225], v[24:27]
	v_mfma_f32_16x16x32_bf16 v[12:15], v[132:135], v[230:233], v[12:15]
	v_mfma_f32_16x16x32_bf16 v[8:11], v[140:143], v[230:233], v[8:11]
	s_setprio 0
	s_setprio 1
	v_mfma_f32_16x16x32_bf16 v[52:55], v[154:157], v[184:187], v[52:55]
	v_mfma_f32_16x16x32_bf16 v[48:51], v[176:179], v[184:187], v[48:51]
	v_mfma_f32_16x16x32_bf16 v[36:39], v[154:157], v[210:213], v[36:39]
	v_mfma_f32_16x16x32_bf16 v[32:35], v[176:179], v[210:213], v[32:35]
	v_mfma_f32_16x16x32_bf16 v[20:23], v[154:157], v[218:221], v[20:23]
	v_mfma_f32_16x16x32_bf16 v[16:19], v[176:179], v[218:221], v[16:19]
	v_mfma_f32_16x16x32_bf16 v[4:7], v[154:157], v[226:229], v[4:7]
	v_mfma_f32_16x16x32_bf16 v[0:3], v[176:179], v[226:229], v[0:3]
	v_mfma_f32_16x16x32_bf16 v[52:55], v[172:175], v[206:209], v[52:55]
	v_mfma_f32_16x16x32_bf16 v[48:51], v[180:183], v[206:209], v[48:51]
	v_mfma_f32_16x16x32_bf16 v[36:39], v[172:175], v[214:217], v[36:39]
	v_mfma_f32_16x16x32_bf16 v[32:35], v[180:183], v[214:217], v[32:35]
	v_mfma_f32_16x16x32_bf16 v[20:23], v[172:175], v[222:225], v[20:23]
	v_mfma_f32_16x16x32_bf16 v[16:19], v[180:183], v[222:225], v[16:19]
	v_mfma_f32_16x16x32_bf16 v[4:7], v[172:175], v[230:233], v[4:7]
	v_mfma_f32_16x16x32_bf16 v[0:3], v[180:183], v[230:233], v[0:3]
	s_setprio 0
	s_barrier
	s_add_i32 s41, 0, 0x18000
	s_add_i32 s42, 0, 0x1c000
	v_add_u32_e32 v140, s41, v169
	v_add_u32_e32 v166, s42, v169
	ds_read_b128 v[128:131], v140
	ds_read_b128 v[132:135], v140 offset:1024
	ds_read_b128 v[136:139], v140 offset:2048
	ds_read_b128 v[140:143], v140 offset:3072
	ds_read_b128 v[154:157], v166
	ds_read_b128 v[172:175], v166 offset:1024
	ds_read_b128 v[176:179], v166 offset:2048
	ds_read_b128 v[180:183], v166 offset:3072
	s_add_u32 s20, s20, 0x40000
	s_addc_u32 s21, s21, 0
	s_mov_b32 m0, s25
	v_lshl_add_u64 v[194:195], s[20:21], 0, v[148:149]
	ds_read_b128 v[184:187], v171 offset:32768
	ds_read_b128 v[206:209], v171 offset:33792
	ds_read_b128 v[210:213], v171 offset:34816
	ds_read_b128 v[214:217], v171 offset:35840
	ds_read_b128 v[218:221], v171 offset:36864
	ds_read_b128 v[222:225], v171 offset:37888
	ds_read_b128 v[226:229], v171 offset:38912
	ds_read_b128 v[230:233], v171 offset:39936
	global_load_lds_dwordx4 v[194:195], off
	v_lshl_add_u64 v[194:195], s[20:21], 0, v[146:147]
	s_mov_b32 m0, s26
	s_nop 0
	global_load_lds_dwordx4 v[194:195], off
	s_waitcnt vmcnt(8)
	s_waitcnt lgkmcnt(0)
	s_barrier
	s_setprio 1
	v_mfma_f32_16x16x32_bf16 v[124:127], v[128:131], v[184:187], v[124:127]
	v_mfma_f32_16x16x32_bf16 v[120:123], v[136:139], v[184:187], v[120:123]
	v_mfma_f32_16x16x32_bf16 v[108:111], v[128:131], v[210:213], v[108:111]
	v_mfma_f32_16x16x32_bf16 v[104:107], v[136:139], v[210:213], v[104:107]
	v_mfma_f32_16x16x32_bf16 v[92:95], v[128:131], v[218:221], v[92:95]
	v_mfma_f32_16x16x32_bf16 v[88:91], v[136:139], v[218:221], v[88:91]
	v_mfma_f32_16x16x32_bf16 v[76:79], v[128:131], v[226:229], v[76:79]
	v_mfma_f32_16x16x32_bf16 v[72:75], v[136:139], v[226:229], v[72:75]
	v_mfma_f32_16x16x32_bf16 v[124:127], v[132:135], v[206:209], v[124:127]
	v_mfma_f32_16x16x32_bf16 v[120:123], v[140:143], v[206:209], v[120:123]
	v_mfma_f32_16x16x32_bf16 v[108:111], v[132:135], v[214:217], v[108:111]
	v_mfma_f32_16x16x32_bf16 v[104:107], v[140:143], v[214:217], v[104:107]
	v_mfma_f32_16x16x32_bf16 v[92:95], v[132:135], v[222:225], v[92:95]
	v_mfma_f32_16x16x32_bf16 v[88:91], v[140:143], v[222:225], v[88:91]
	v_mfma_f32_16x16x32_bf16 v[76:79], v[132:135], v[230:233], v[76:79]
	v_mfma_f32_16x16x32_bf16 v[72:75], v[140:143], v[230:233], v[72:75]
	s_setprio 0
	s_setprio 1
	v_mfma_f32_16x16x32_bf16 v[116:119], v[154:157], v[184:187], v[116:119]
	v_mfma_f32_16x16x32_bf16 v[112:115], v[176:179], v[184:187], v[112:115]
	v_mfma_f32_16x16x32_bf16 v[100:103], v[154:157], v[210:213], v[100:103]
	v_mfma_f32_16x16x32_bf16 v[96:99], v[176:179], v[210:213], v[96:99]
	v_mfma_f32_16x16x32_bf16 v[84:87], v[154:157], v[218:221], v[84:87]
	v_mfma_f32_16x16x32_bf16 v[80:83], v[176:179], v[218:221], v[80:83]
	v_mfma_f32_16x16x32_bf16 v[68:71], v[154:157], v[226:229], v[68:71]
	v_mfma_f32_16x16x32_bf16 v[64:67], v[176:179], v[226:229], v[64:67]
	v_mfma_f32_16x16x32_bf16 v[116:119], v[172:175], v[206:209], v[116:119]
	v_mfma_f32_16x16x32_bf16 v[112:115], v[180:183], v[206:209], v[112:115]
	v_mfma_f32_16x16x32_bf16 v[100:103], v[172:175], v[214:217], v[100:103]
	v_mfma_f32_16x16x32_bf16 v[96:99], v[180:183], v[214:217], v[96:99]
	v_mfma_f32_16x16x32_bf16 v[84:87], v[172:175], v[222:225], v[84:87]
	v_mfma_f32_16x16x32_bf16 v[80:83], v[180:183], v[222:225], v[80:83]
	v_mfma_f32_16x16x32_bf16 v[68:71], v[172:175], v[230:233], v[68:71]
	v_mfma_f32_16x16x32_bf16 v[64:67], v[180:183], v[230:233], v[64:67]
	s_setprio 0
	s_barrier
; #define PG8_STAGE(bufoff, gbase, voff) do { _Pragma("unroll") for (int _i = 0; _i < 2; ++_i) \
;         __builtin_amdgcn_global_load_lds((const unsigned*)((const char*)(gbase) + (voff)[_i]), (PG8_LAS unsigned*)(lds + (bufoff) + ldsw + _i * 8192), 16, 0, 0); } while (0)
; #define PG8_LDA(dst, b, h) do { _Pragma("unroll") for (int m = 0; m < 4; ++m) _Pragma("unroll") for (int k = 0; k < 2; ++k) dst[m][k] = *(const PG8_LAS bf16x8*)(lds + PG8_SA(b, h) + aoff + m * 2048 + k * 1024); } while (0)
; #define PG8_MMA(ai, bj, At, Bt) do { __builtin_amdgcn_s_setprio(1); _Pragma("unroll") for (int m = 0; m < 4; ++m) _Pragma("unroll") for (int n = 0; n < 2; ++n) _Pragma("unroll") for (int k = 0; k < 2; ++k) \
;         acc[ai][bj][m][n] = __builtin_amdgcn_mfma_f32_16x16x32_bf16(Bt[n][k], At[m][k], acc[ai][bj][m][n], 0, 0, 0); __builtin_amdgcn_s_setprio(0); } while (0)
; #define PG8_WAIT_V(n) asm volatile("s_waitcnt vmcnt(" #n ")" ::: "memory")
; #define PG8_WAIT_L(n) asm volatile("s_waitcnt lgkmcnt(" #n ")" ::: "memory")
; #define PG8_BAR __builtin_amdgcn_s_barrier()
; #define PG8_SCHED __builtin_amdgcn_sched_barrier(0)
; template <class Epi, class Sched, bool ALIGN_EPI = false, bool SP2 = false>
; __device__ __forceinline__ void gemm_phase(PG8_LAS unsigned char* lds, const Gemm g, const Sched& S, const Epi& E) {
;     ...
;             PG8_LDA(At, 1, 1); PG8_STAGE(PG8_SB(1, 0), b3, voffB); PG8_STAGE(PG8_SB(1, 1), b3 + hstep, voffB); PG8_STAGE(PG8_SA(1, 0), a3, voffA);
;             PG8_WAIT_V(8); PG8_WAIT_L(0); PG8_BAR; PG8_MMA(1, 0, At, B0); PG8_MMA(1, 1, At, B1); PG8_BAR; PG8_SCHED;
	s_add_i32 s20, s41, s22
	v_lshl_add_u64 v[158:159], v[158:159], 0, s[38:39]
	s_mov_b32 m0, s20
	ds_read_b128 v[184:187], v171 offset:49152
	ds_read_b128 v[206:209], v171 offset:50176
	ds_read_b128 v[210:213], v171 offset:51200
	ds_read_b128 v[214:217], v171 offset:52224
	ds_read_b128 v[218:221], v171 offset:53248
	ds_read_b128 v[222:225], v171 offset:54272
	ds_read_b128 v[226:229], v171 offset:55296
	ds_read_b128 v[230:233], v171 offset:56320
	global_load_lds_dwordx4 v[158:159], off
	s_add_i32 m0, s20, 0x2000
	s_add_u32 s18, s18, 0x40080
	v_lshl_add_u64 v[158:159], v[162:163], 0, s[38:39]
	s_addc_u32 s19, s19, 0
	s_add_i32 s20, s42, s22
	global_load_lds_dwordx4 v[158:159], off
	v_lshl_add_u64 v[158:159], s[18:19], 0, v[160:161]
	s_mov_b32 m0, s20
	s_nop 0
	global_load_lds_dwordx4 v[158:159], off
	v_lshl_add_u64 v[158:159], s[18:19], 0, v[144:145]
	s_add_i32 m0, s20, 0x2000
	s_nop 0
	global_load_lds_dwordx4 v[158:159], off
	v_lshl_add_u64 v[158:159], v[164:165], 0, s[38:39]
	s_mov_b32 m0, s29
	s_nop 0
	global_load_lds_dwordx4 v[158:159], off
	v_lshl_add_u64 v[158:159], v[188:189], 0, s[38:39]
	s_mov_b32 m0, s30
	s_nop 0
	global_load_lds_dwordx4 v[158:159], off
	s_waitcnt vmcnt(8)
	s_waitcnt lgkmcnt(0)
	s_barrier
	s_setprio 1
	v_mfma_f32_16x16x32_bf16 v[60:63], v[128:131], v[184:187], v[60:63]
	v_mfma_f32_16x16x32_bf16 v[56:59], v[136:139], v[184:187], v[56:59]
	v_mfma_f32_16x16x32_bf16 v[44:47], v[128:131], v[210:213], v[44:47]
	v_mfma_f32_16x16x32_bf16 v[40:43], v[136:139], v[210:213], v[40:43]
	v_mfma_f32_16x16x32_bf16 v[28:31], v[128:131], v[218:221], v[28:31]
	v_mfma_f32_16x16x32_bf16 v[24:27], v[136:139], v[218:221], v[24:27]
	v_mfma_f32_16x16x32_bf16 v[12:15], v[128:131], v[226:229], v[12:15]
	v_mfma_f32_16x16x32_bf16 v[8:11], v[136:139], v[226:229], v[8:11]
	v_mfma_f32_16x16x32_bf16 v[60:63], v[132:135], v[206:209], v[60:63]
	v_mfma_f32_16x16x32_bf16 v[56:59], v[140:143], v[206:209], v[56:59]
	v_mfma_f32_16x16x32_bf16 v[44:47], v[132:135], v[214:217], v[44:47]
	v_mfma_f32_16x16x32_bf16 v[40:43], v[140:143], v[214:217], v[40:43]
	v_mfma_f32_16x16x32_bf16 v[28:31], v[132:135], v[222:225], v[28:31]
	v_mfma_f32_16x16x32_bf16 v[24:27], v[140:143], v[222:225], v[24:27]
	v_mfma_f32_16x16x32_bf16 v[12:15], v[132:135], v[230:233], v[12:15]
	v_mfma_f32_16x16x32_bf16 v[8:11], v[140:143], v[230:233], v[8:11]
	s_setprio 0
	s_setprio 1
	v_mfma_f32_16x16x32_bf16 v[52:55], v[154:157], v[184:187], v[52:55]
	v_mfma_f32_16x16x32_bf16 v[48:51], v[176:179], v[184:187], v[48:51]
	v_mfma_f32_16x16x32_bf16 v[36:39], v[154:157], v[210:213], v[36:39]
	v_mfma_f32_16x16x32_bf16 v[32:35], v[176:179], v[210:213], v[32:35]
	v_mfma_f32_16x16x32_bf16 v[20:23], v[154:157], v[218:221], v[20:23]
	v_mfma_f32_16x16x32_bf16 v[16:19], v[176:179], v[218:221], v[16:19]
	v_mfma_f32_16x16x32_bf16 v[4:7], v[154:157], v[226:229], v[4:7]
	v_mfma_f32_16x16x32_bf16 v[0:3], v[176:179], v[226:229], v[0:3]
	v_mfma_f32_16x16x32_bf16 v[52:55], v[172:175], v[206:209], v[52:55]
	v_mfma_f32_16x16x32_bf16 v[48:51], v[180:183], v[206:209], v[48:51]
	v_mfma_f32_16x16x32_bf16 v[36:39], v[172:175], v[214:217], v[36:39]
	v_mfma_f32_16x16x32_bf16 v[32:35], v[180:183], v[214:217], v[32:35]
	v_mfma_f32_16x16x32_bf16 v[20:23], v[172:175], v[222:225], v[20:23]
	v_mfma_f32_16x16x32_bf16 v[16:19], v[180:183], v[222:225], v[16:19]
	v_mfma_f32_16x16x32_bf16 v[4:7], v[172:175], v[230:233], v[4:7]
	v_mfma_f32_16x16x32_bf16 v[0:3], v[180:183], v[230:233], v[0:3]
	s_setprio 0
	s_barrier
	s_add_i32 s40, s40, 2
	s_add_u32 s2, s2, 0x100
	s_addc_u32 s3, s3, 0
	s_add_u32 s36, s36, 0x100
	s_addc_u32 s37, s37, 0
	s_cmp_gt_u32 s40, 13
	s_cbranch_scc0 .LBB0_212
	s_and_b64 vcc, exec, s[8:9]
	s_cbranch_vccz .LBB0_215
	s_barrier

; #define PG8_STAGE(bufoff, gbase, voff) do { _Pragma("unroll") for (int _i = 0; _i < 2; ++_i) \
;         __builtin_amdgcn_global_load_lds((const unsigned*)((const char*)(gbase) + (voff)[_i]), (PG8_LAS unsigned*)(lds + (bufoff) + ldsw + _i * 8192), 16, 0, 0); } while (0)
; #define PG8_LDA(dst, b, h) do { _Pragma("unroll") for (int m = 0; m < 4; ++m) _Pragma("unroll") for (int k = 0; k < 2; ++k) dst[m][k] = *(const PG8_LAS bf16x8*)(lds + PG8_SA(b, h) + aoff + m * 2048 + k * 1024); } while (0)
; #define PG8_LDB(dst, b, h) do { _Pragma("unroll") for (int n = 0; n < 2; ++n) _Pragma("unroll") for (int k = 0; k < 2; ++k) dst[n][k] = *(const PG8_LAS bf16x8*)(lds + PG8_SB(b, h) + boff + n * 2048 + k * 1024); } while (0)
; #define PG8_MMA(ai, bj, At, Bt) do { __builtin_amdgcn_s_setprio(1); _Pragma("unroll") for (int m = 0; m < 4; ++m) _Pragma("unroll") for (int n = 0; n < 2; ++n) _Pragma("unroll") for (int k = 0; k < 2; ++k) \
;         acc[ai][bj][m][n] = __builtin_amdgcn_mfma_f32_16x16x32_bf16(Bt[n][k], At[m][k], acc[ai][bj][m][n], 0, 0, 0); __builtin_amdgcn_s_setprio(0); } while (0)
; #define PG8_WAIT_V(n) asm volatile("s_waitcnt vmcnt(" #n ")" ::: "memory")
; #define PG8_WAIT_L(n) asm volatile("s_waitcnt lgkmcnt(" #n ")" ::: "memory")
; template <class Epi, class Sched, bool ALIGN_EPI = false, bool SP2 = false>
; __device__ __forceinline__ void gemm_phase(PG8_LAS unsigned char* lds, const Gemm g, const Sched& S, const Epi& E) {
;     ...
;             const bool last = (t == nt - 2);
;             const char* a1 = cA + (size_t)(t + 1) * kstep;
;             const char* a2 = last ? nA : cA + (size_t)(t + 2) * kstep; const char* b2 = last ? nB : cB + (size_t)(t + 2) * kstep;
;             const char* a3 = a2 + kstep; const char* b3 = b2 + kstep;
;             if (last && has_next) S.a_ready(nxt);
;             if constexpr (SP2) {
;             PG8_LDB(B0, 0, 0); PG8_LDB(B1, 0, 1); PG8_SCHED; PG8_LDA(At, 0, 0); PG8_STAGE(PG8_SA(1, 1), a1 + hstep, voffA);
;             PG8_WAIT_V(8); PG8_WAIT_L(0); PG8_BAR; PG8_MMA(0, 0, At, B0); PG8_MMA(0, 1, At, B1); PG8_BAR; PG8_SCHED;
;             PG8_LDA(At, 0, 1); PG8_STAGE(PG8_SB(0, 0), b2, voffB); PG8_STAGE(PG8_SB(0, 1), b2 + hstep, voffB); PG8_STAGE(PG8_SA(0, 0), a2, voffA);
;             PG8_WAIT_V(8); PG8_WAIT_L(0); PG8_BAR; PG8_MMA(1, 0, At, B0); PG8_MMA(1, 1, At, B1); PG8_BAR; PG8_SCHED;
.LBB0_373:
	s_add_i32 s46, s24, 2
	s_add_u32 s47, s0, 0x80
	s_addc_u32 s25, s1, 0
	s_add_i32 s50, 0, 0x10000
	s_cmp_eq_u32 s42, s24
	s_cselect_b32 s25, s21, s25
	s_cselect_b32 s24, s20, s47
	v_add_u32_e32 v140, s50, v141
	s_cselect_b32 s49, s23, s27
	s_cselect_b32 s48, s22, s26
	s_add_i32 s47, 0, 0x14000
	ds_read_b128 v[146:149], v140
	ds_read_b128 v[150:153], v140 offset:1024
	ds_read_b128 v[154:157], v140 offset:2048
	ds_read_b128 v[162:165], v140 offset:3072
	v_add_u32_e32 v140, s47, v141
	ds_read_b128 v[166:169], v140
	ds_read_b128 v[170:173], v140 offset:1024
	ds_read_b128 v[174:177], v140 offset:2048
	ds_read_b128 v[178:181], v140 offset:3072
	v_lshl_add_u64 v[142:143], s[0:1], 0, v[136:137]
	s_add_i32 m0, s31, 0xc000
	ds_read_b128 v[182:185], v145
	ds_read_b128 v[186:189], v145 offset:1024
	ds_read_b128 v[194:197], v145 offset:2048
	ds_read_b128 v[206:209], v145 offset:3072
	ds_read_b128 v[210:213], v145 offset:4096
	ds_read_b128 v[214:217], v145 offset:5120
	ds_read_b128 v[218:221], v145 offset:6144
	ds_read_b128 v[222:225], v145 offset:7168
	global_load_lds_dwordx4 v[142:143], off
	v_lshl_add_u64 v[142:143], s[0:1], 0, v[138:139]
	s_add_i32 m0, s31, 0xe000
	s_nop 0
	global_load_lds_dwordx4 v[142:143], off
	s_waitcnt vmcnt(8)
	s_waitcnt lgkmcnt(0)
	s_barrier
	s_setprio 1
	v_mfma_f32_16x16x32_bf16 v[124:127], v[146:149], v[182:185], v[124:127]
	v_mfma_f32_16x16x32_bf16 v[120:123], v[154:157], v[182:185], v[120:123]
	v_mfma_f32_16x16x32_bf16 v[108:111], v[146:149], v[194:197], v[108:111]
	v_mfma_f32_16x16x32_bf16 v[104:107], v[154:157], v[194:197], v[104:107]
	v_mfma_f32_16x16x32_bf16 v[92:95], v[146:149], v[210:213], v[92:95]
	v_mfma_f32_16x16x32_bf16 v[88:91], v[154:157], v[210:213], v[88:91]
	v_mfma_f32_16x16x32_bf16 v[76:79], v[146:149], v[218:221], v[76:79]
	v_mfma_f32_16x16x32_bf16 v[72:75], v[154:157], v[218:221], v[72:75]
	v_mfma_f32_16x16x32_bf16 v[124:127], v[150:153], v[186:189], v[124:127]
	v_mfma_f32_16x16x32_bf16 v[120:123], v[162:165], v[186:189], v[120:123]
	v_mfma_f32_16x16x32_bf16 v[108:111], v[150:153], v[206:209], v[108:111]
	v_mfma_f32_16x16x32_bf16 v[104:107], v[162:165], v[206:209], v[104:107]
	v_mfma_f32_16x16x32_bf16 v[92:95], v[150:153], v[214:217], v[92:95]
	v_mfma_f32_16x16x32_bf16 v[88:91], v[162:165], v[214:217], v[88:91]
	v_mfma_f32_16x16x32_bf16 v[76:79], v[150:153], v[222:225], v[76:79]
	v_mfma_f32_16x16x32_bf16 v[72:75], v[162:165], v[222:225], v[72:75]
	s_setprio 0
	s_setprio 1
	v_mfma_f32_16x16x32_bf16 v[116:119], v[166:169], v[182:185], v[116:119]
	v_mfma_f32_16x16x32_bf16 v[112:115], v[174:177], v[182:185], v[112:115]
	v_mfma_f32_16x16x32_bf16 v[100:103], v[166:169], v[194:197], v[100:103]
	v_mfma_f32_16x16x32_bf16 v[96:99], v[174:177], v[194:197], v[96:99]
	v_mfma_f32_16x16x32_bf16 v[84:87], v[166:169], v[210:213], v[84:87]
	v_mfma_f32_16x16x32_bf16 v[80:83], v[174:177], v[210:213], v[80:83]
	v_mfma_f32_16x16x32_bf16 v[68:71], v[166:169], v[218:221], v[68:71]
	v_mfma_f32_16x16x32_bf16 v[64:67], v[174:177], v[218:221], v[64:67]
	v_mfma_f32_16x16x32_bf16 v[116:119], v[170:173], v[186:189], v[116:119]
	v_mfma_f32_16x16x32_bf16 v[112:115], v[178:181], v[186:189], v[112:115]
	v_mfma_f32_16x16x32_bf16 v[100:103], v[170:173], v[206:209], v[100:103]
	v_mfma_f32_16x16x32_bf16 v[96:99], v[178:181], v[206:209], v[96:99]
	v_mfma_f32_16x16x32_bf16 v[84:87], v[170:173], v[214:217], v[84:87]
	v_mfma_f32_16x16x32_bf16 v[80:83], v[178:181], v[214:217], v[80:83]
	v_mfma_f32_16x16x32_bf16 v[68:71], v[170:173], v[222:225], v[68:71]
	v_mfma_f32_16x16x32_bf16 v[64:67], v[178:181], v[222:225], v[64:67]
	s_setprio 0
	s_barrier
	s_add_i32 s50, s50, s30
	v_lshl_add_u64 v[142:143], s[48:49], 0, v[132:133]
	s_mov_b32 m0, s50
	ds_read_b128 v[182:185], v145 offset:16384
	ds_read_b128 v[186:189], v145 offset:17408
	ds_read_b128 v[194:197], v145 offset:18432
	ds_read_b128 v[206:209], v145 offset:19456
	ds_read_b128 v[210:213], v145 offset:20480
	ds_read_b128 v[214:217], v145 offset:21504
	ds_read_b128 v[218:221], v145 offset:22528
	ds_read_b128 v[222:225], v145 offset:23552
	global_load_lds_dwordx4 v[142:143], off
	s_add_i32 m0, s50, 0x2000
	v_lshl_add_u64 v[158:159], s[48:49], 0, v[128:129]
	s_add_u32 s48, s48, s8
	s_addc_u32 s49, s49, s9
	s_add_i32 s47, s47, s30
	global_load_lds_dwordx4 v[158:159], off
	v_lshl_add_u64 v[226:227], s[48:49], 0, v[132:133]
	s_mov_b32 m0, s47
	v_lshl_add_u64 v[228:229], s[48:49], 0, v[128:129]
	global_load_lds_dwordx4 v[226:227], off
	s_add_i32 m0, s47, 0x2000
	v_lshl_add_u64 v[230:231], s[24:25], 0, v[134:135]
	global_load_lds_dwordx4 v[228:229], off
	s_mov_b32 m0, s31
	v_lshl_add_u64 v[232:233], s[24:25], 0, v[130:131]
	global_load_lds_dwordx4 v[230:231], off
	s_mov_b32 m0, s34
	s_nop 0
	global_load_lds_dwordx4 v[232:233], off
	s_waitcnt vmcnt(8)
	s_waitcnt lgkmcnt(0)
	s_barrier
; #define PG8_STAGE(bufoff, gbase, voff) do { _Pragma("unroll") for (int _i = 0; _i < 2; ++_i) \
;         __builtin_amdgcn_global_load_lds((const unsigned*)((const char*)(gbase) + (voff)[_i]), (PG8_LAS unsigned*)(lds + (bufoff) + ldsw + _i * 8192), 16, 0, 0); } while (0)
; #define PG8_LDA(dst, b, h) do { _Pragma("unroll") for (int m = 0; m < 4; ++m) _Pragma("unroll") for (int k = 0; k < 2; ++k) dst[m][k] = *(const PG8_LAS bf16x8*)(lds + PG8_SA(b, h) + aoff + m * 2048 + k * 1024); } while (0)
; #define PG8_LDB(dst, b, h) do { _Pragma("unroll") for (int n = 0; n < 2; ++n) _Pragma("unroll") for (int k = 0; k < 2; ++k) dst[n][k] = *(const PG8_LAS bf16x8*)(lds + PG8_SB(b, h) + boff + n * 2048 + k * 1024); } while (0)
; #define PG8_MMA(ai, bj, At, Bt) do { __builtin_amdgcn_s_setprio(1); _Pragma("unroll") for (int m = 0; m < 4; ++m) _Pragma("unroll") for (int n = 0; n < 2; ++n) _Pragma("unroll") for (int k = 0; k < 2; ++k) \
;         acc[ai][bj][m][n] = __builtin_amdgcn_mfma_f32_16x16x32_bf16(Bt[n][k], At[m][k], acc[ai][bj][m][n], 0, 0, 0); __builtin_amdgcn_s_setprio(0); } while (0)
; #define PG8_WAIT_V(n) asm volatile("s_waitcnt vmcnt(" #n ")" ::: "memory")
; #define PG8_WAIT_L(n) asm volatile("s_waitcnt lgkmcnt(" #n ")" ::: "memory")
; #define PG8_BAR __builtin_amdgcn_s_barrier()
; #define PG8_SCHED __builtin_amdgcn_sched_barrier(0)
; template <class Epi, class Sched, bool ALIGN_EPI = false, bool SP2 = false>
; __device__ __forceinline__ void gemm_phase(PG8_LAS unsigned char* lds, const Gemm g, const Sched& S, const Epi& E) {
;     ...
;             PG8_WAIT_V(8); PG8_WAIT_L(0); PG8_BAR; PG8_MMA(1, 0, At, B0); PG8_MMA(1, 1, At, B1); PG8_BAR; PG8_SCHED;
;             PG8_LDB(B0, 1, 0); PG8_LDB(B1, 1, 1); PG8_SCHED; PG8_LDA(At, 1, 0); PG8_STAGE(PG8_SA(0, 1), a2 + hstep, voffA);
;             PG8_WAIT_V(8); PG8_WAIT_L(0); PG8_BAR; PG8_MMA(0, 0, At, B0); PG8_MMA(0, 1, At, B1); PG8_BAR; PG8_SCHED;
	s_setprio 1
	v_mfma_f32_16x16x32_bf16 v[60:63], v[146:149], v[182:185], v[60:63]
	v_mfma_f32_16x16x32_bf16 v[56:59], v[154:157], v[182:185], v[56:59]
	v_mfma_f32_16x16x32_bf16 v[44:47], v[146:149], v[194:197], v[44:47]
	v_mfma_f32_16x16x32_bf16 v[40:43], v[154:157], v[194:197], v[40:43]
	v_mfma_f32_16x16x32_bf16 v[28:31], v[146:149], v[210:213], v[28:31]
	v_mfma_f32_16x16x32_bf16 v[24:27], v[154:157], v[210:213], v[24:27]
	v_mfma_f32_16x16x32_bf16 v[12:15], v[146:149], v[218:221], v[12:15]
	v_mfma_f32_16x16x32_bf16 v[8:11], v[154:157], v[218:221], v[8:11]
	v_mfma_f32_16x16x32_bf16 v[60:63], v[150:153], v[186:189], v[60:63]
	v_mfma_f32_16x16x32_bf16 v[56:59], v[162:165], v[186:189], v[56:59]
	v_mfma_f32_16x16x32_bf16 v[44:47], v[150:153], v[206:209], v[44:47]
	v_mfma_f32_16x16x32_bf16 v[40:43], v[162:165], v[206:209], v[40:43]
	v_mfma_f32_16x16x32_bf16 v[28:31], v[150:153], v[214:217], v[28:31]
	v_mfma_f32_16x16x32_bf16 v[24:27], v[162:165], v[214:217], v[24:27]
	v_mfma_f32_16x16x32_bf16 v[12:15], v[150:153], v[222:225], v[12:15]
	v_mfma_f32_16x16x32_bf16 v[8:11], v[162:165], v[222:225], v[8:11]
	s_setprio 0
	s_setprio 1
	v_mfma_f32_16x16x32_bf16 v[52:55], v[166:169], v[182:185], v[52:55]
	v_mfma_f32_16x16x32_bf16 v[48:51], v[174:177], v[182:185], v[48:51]
	v_mfma_f32_16x16x32_bf16 v[36:39], v[166:169], v[194:197], v[36:39]
	v_mfma_f32_16x16x32_bf16 v[32:35], v[174:177], v[194:197], v[32:35]
	v_mfma_f32_16x16x32_bf16 v[20:23], v[166:169], v[210:213], v[20:23]
	v_mfma_f32_16x16x32_bf16 v[16:19], v[174:177], v[210:213], v[16:19]
	v_mfma_f32_16x16x32_bf16 v[4:7], v[166:169], v[218:221], v[4:7]
	v_mfma_f32_16x16x32_bf16 v[0:3], v[174:177], v[218:221], v[0:3]
	v_mfma_f32_16x16x32_bf16 v[52:55], v[170:173], v[186:189], v[52:55]
	v_mfma_f32_16x16x32_bf16 v[48:51], v[178:181], v[186:189], v[48:51]
	v_mfma_f32_16x16x32_bf16 v[36:39], v[170:173], v[206:209], v[36:39]
	v_mfma_f32_16x16x32_bf16 v[32:35], v[178:181], v[206:209], v[32:35]
	v_mfma_f32_16x16x32_bf16 v[20:23], v[170:173], v[214:217], v[20:23]
	v_mfma_f32_16x16x32_bf16 v[16:19], v[178:181], v[214:217], v[16:19]
	v_mfma_f32_16x16x32_bf16 v[4:7], v[170:173], v[222:225], v[4:7]
	v_mfma_f32_16x16x32_bf16 v[0:3], v[178:181], v[222:225], v[0:3]
	s_setprio 0
	s_barrier
	s_add_i32 s47, 0, 0x18000
	v_add_u32_e32 v140, s47, v141
	s_add_i32 s48, 0, 0x1c000
	ds_read_b128 v[146:149], v140
	ds_read_b128 v[150:153], v140 offset:1024
	ds_read_b128 v[154:157], v140 offset:2048
	ds_read_b128 v[162:165], v140 offset:3072
	v_add_u32_e32 v140, s48, v141
	ds_read_b128 v[166:169], v140
	ds_read_b128 v[170:173], v140 offset:1024
	ds_read_b128 v[174:177], v140 offset:2048
	ds_read_b128 v[178:181], v140 offset:3072
	s_add_u32 s24, s24, s8
	s_addc_u32 s25, s25, s9
	s_mov_b32 m0, s35
	v_lshl_add_u64 v[234:235], s[24:25], 0, v[134:135]
	ds_read_b128 v[182:185], v145 offset:32768
	ds_read_b128 v[186:189], v145 offset:33792
	ds_read_b128 v[194:197], v145 offset:34816
	ds_read_b128 v[206:209], v145 offset:35840
	ds_read_b128 v[210:213], v145 offset:36864
	ds_read_b128 v[214:217], v145 offset:37888
	ds_read_b128 v[218:221], v145 offset:38912
	ds_read_b128 v[222:225], v145 offset:39936
	global_load_lds_dwordx4 v[234:235], off
	v_lshl_add_u64 v[234:235], s[24:25], 0, v[130:131]
	s_mov_b32 m0, s36
	s_nop 0
	global_load_lds_dwordx4 v[234:235], off
	s_waitcnt vmcnt(8)
	s_waitcnt lgkmcnt(0)
	s_barrier
	s_setprio 1
	v_mfma_f32_16x16x32_bf16 v[124:127], v[146:149], v[182:185], v[124:127]
	v_mfma_f32_16x16x32_bf16 v[120:123], v[154:157], v[182:185], v[120:123]
	v_mfma_f32_16x16x32_bf16 v[108:111], v[146:149], v[194:197], v[108:111]
	v_mfma_f32_16x16x32_bf16 v[104:107], v[154:157], v[194:197], v[104:107]
	v_mfma_f32_16x16x32_bf16 v[92:95], v[146:149], v[210:213], v[92:95]
	v_mfma_f32_16x16x32_bf16 v[88:91], v[154:157], v[210:213], v[88:91]
	v_mfma_f32_16x16x32_bf16 v[76:79], v[146:149], v[218:221], v[76:79]
	v_mfma_f32_16x16x32_bf16 v[72:75], v[154:157], v[218:221], v[72:75]
	v_mfma_f32_16x16x32_bf16 v[124:127], v[150:153], v[186:189], v[124:127]
	v_mfma_f32_16x16x32_bf16 v[120:123], v[162:165], v[186:189], v[120:123]
	v_mfma_f32_16x16x32_bf16 v[108:111], v[150:153], v[206:209], v[108:111]
	v_mfma_f32_16x16x32_bf16 v[104:107], v[162:165], v[206:209], v[104:107]
	v_mfma_f32_16x16x32_bf16 v[92:95], v[150:153], v[214:217], v[92:95]
	v_mfma_f32_16x16x32_bf16 v[88:91], v[162:165], v[214:217], v[88:91]
	v_mfma_f32_16x16x32_bf16 v[76:79], v[150:153], v[222:225], v[76:79]
	v_mfma_f32_16x16x32_bf16 v[72:75], v[162:165], v[222:225], v[72:75]
	s_setprio 0
	s_setprio 1
	v_mfma_f32_16x16x32_bf16 v[116:119], v[166:169], v[182:185], v[116:119]
	v_mfma_f32_16x16x32_bf16 v[112:115], v[174:177], v[182:185], v[112:115]
	v_mfma_f32_16x16x32_bf16 v[100:103], v[166:169], v[194:197], v[100:103]
	v_mfma_f32_16x16x32_bf16 v[96:99], v[174:177], v[194:197], v[96:99]
	v_mfma_f32_16x16x32_bf16 v[84:87], v[166:169], v[210:213], v[84:87]
	v_mfma_f32_16x16x32_bf16 v[80:83], v[174:177], v[210:213], v[80:83]
	v_mfma_f32_16x16x32_bf16 v[68:71], v[166:169], v[218:221], v[68:71]
	v_mfma_f32_16x16x32_bf16 v[64:67], v[174:177], v[218:221], v[64:67]
	v_mfma_f32_16x16x32_bf16 v[116:119], v[170:173], v[186:189], v[116:119]
	v_mfma_f32_16x16x32_bf16 v[112:115], v[178:181], v[186:189], v[112:115]
	v_mfma_f32_16x16x32_bf16 v[100:103], v[170:173], v[206:209], v[100:103]
	v_mfma_f32_16x16x32_bf16 v[96:99], v[178:181], v[206:209], v[96:99]
	v_mfma_f32_16x16x32_bf16 v[84:87], v[170:173], v[214:217], v[84:87]
	v_mfma_f32_16x16x32_bf16 v[80:83], v[178:181], v[214:217], v[80:83]
	v_mfma_f32_16x16x32_bf16 v[68:71], v[170:173], v[222:225], v[68:71]
	v_mfma_f32_16x16x32_bf16 v[64:67], v[178:181], v[222:225], v[64:67]
	s_setprio 0
	s_barrier
; #define PG8_STAGE(bufoff, gbase, voff) do { _Pragma("unroll") for (int _i = 0; _i < 2; ++_i) \
;         __builtin_amdgcn_global_load_lds((const unsigned*)((const char*)(gbase) + (voff)[_i]), (PG8_LAS unsigned*)(lds + (bufoff) + ldsw + _i * 8192), 16, 0, 0); } while (0)
; #define PG8_LDA(dst, b, h) do { _Pragma("unroll") for (int m = 0; m < 4; ++m) _Pragma("unroll") for (int k = 0; k < 2; ++k) dst[m][k] = *(const PG8_LAS bf16x8*)(lds + PG8_SA(b, h) + aoff + m * 2048 + k * 1024); } while (0)
; #define PG8_MMA(ai, bj, At, Bt) do { __builtin_amdgcn_s_setprio(1); _Pragma("unroll") for (int m = 0; m < 4; ++m) _Pragma("unroll") for (int n = 0; n < 2; ++n) _Pragma("unroll") for (int k = 0; k < 2; ++k) \
;         acc[ai][bj][m][n] = __builtin_amdgcn_mfma_f32_16x16x32_bf16(Bt[n][k], At[m][k], acc[ai][bj][m][n], 0, 0, 0); __builtin_amdgcn_s_setprio(0); } while (0)
; #define PG8_WAIT_V(n) asm volatile("s_waitcnt vmcnt(" #n ")" ::: "memory")
; #define PG8_WAIT_L(n) asm volatile("s_waitcnt lgkmcnt(" #n ")" ::: "memory")
; #define PG8_BAR __builtin_amdgcn_s_barrier()
; #define PG8_SCHED __builtin_amdgcn_sched_barrier(0)
; template <class Epi, class Sched, bool ALIGN_EPI = false, bool SP2 = false>
; __device__ __forceinline__ void gemm_phase(PG8_LAS unsigned char* lds, const Gemm g, const Sched& S, const Epi& E) {
;     ...
;             PG8_LDA(At, 1, 1); PG8_STAGE(PG8_SB(1, 0), b3, voffB); PG8_STAGE(PG8_SB(1, 1), b3 + hstep, voffB); PG8_STAGE(PG8_SA(1, 0), a3, voffA);
;             PG8_WAIT_V(8); PG8_WAIT_L(0); PG8_BAR; PG8_MMA(1, 0, At, B0); PG8_MMA(1, 1, At, B1); PG8_BAR; PG8_SCHED;
	s_add_i32 s24, s47, s30
	v_lshl_add_u64 v[142:143], v[142:143], 0, s[38:39]
	s_mov_b32 m0, s24
	ds_read_b128 v[182:185], v145 offset:49152
	ds_read_b128 v[186:189], v145 offset:50176
	ds_read_b128 v[194:197], v145 offset:51200
	ds_read_b128 v[206:209], v145 offset:52224
	ds_read_b128 v[210:213], v145 offset:53248
	ds_read_b128 v[214:217], v145 offset:54272
	ds_read_b128 v[218:221], v145 offset:55296
	ds_read_b128 v[222:225], v145 offset:56320
	global_load_lds_dwordx4 v[142:143], off
	v_lshl_add_u64 v[142:143], v[158:159], 0, s[38:39]
	s_add_i32 m0, s24, 0x2000
	s_add_i32 s24, s48, s30
	global_load_lds_dwordx4 v[142:143], off
	v_lshl_add_u64 v[142:143], v[226:227], 0, s[38:39]
	s_mov_b32 m0, s24
	s_nop 0
	global_load_lds_dwordx4 v[142:143], off
	v_lshl_add_u64 v[142:143], v[228:229], 0, s[38:39]
	s_add_i32 m0, s24, 0x2000
	s_nop 0
	global_load_lds_dwordx4 v[142:143], off
	v_lshl_add_u64 v[142:143], v[230:231], 0, s[38:39]
	s_mov_b32 m0, s37
	s_nop 0
	global_load_lds_dwordx4 v[142:143], off
	v_lshl_add_u64 v[142:143], v[232:233], 0, s[38:39]
	s_mov_b32 m0, s40
	s_nop 0
	global_load_lds_dwordx4 v[142:143], off
	s_waitcnt vmcnt(8)
	s_waitcnt lgkmcnt(0)
	s_barrier
	s_setprio 1
	v_mfma_f32_16x16x32_bf16 v[60:63], v[146:149], v[182:185], v[60:63]
	v_mfma_f32_16x16x32_bf16 v[56:59], v[154:157], v[182:185], v[56:59]
	v_mfma_f32_16x16x32_bf16 v[44:47], v[146:149], v[194:197], v[44:47]
	v_mfma_f32_16x16x32_bf16 v[40:43], v[154:157], v[194:197], v[40:43]
	v_mfma_f32_16x16x32_bf16 v[28:31], v[146:149], v[210:213], v[28:31]
	v_mfma_f32_16x16x32_bf16 v[24:27], v[154:157], v[210:213], v[24:27]
	v_mfma_f32_16x16x32_bf16 v[12:15], v[146:149], v[218:221], v[12:15]
	v_mfma_f32_16x16x32_bf16 v[8:11], v[154:157], v[218:221], v[8:11]
	v_mfma_f32_16x16x32_bf16 v[60:63], v[150:153], v[186:189], v[60:63]
	v_mfma_f32_16x16x32_bf16 v[56:59], v[162:165], v[186:189], v[56:59]
	v_mfma_f32_16x16x32_bf16 v[44:47], v[150:153], v[206:209], v[44:47]
	v_mfma_f32_16x16x32_bf16 v[40:43], v[162:165], v[206:209], v[40:43]
	v_mfma_f32_16x16x32_bf16 v[28:31], v[150:153], v[214:217], v[28:31]
	v_mfma_f32_16x16x32_bf16 v[24:27], v[162:165], v[214:217], v[24:27]
	v_mfma_f32_16x16x32_bf16 v[12:15], v[150:153], v[222:225], v[12:15]
	v_mfma_f32_16x16x32_bf16 v[8:11], v[162:165], v[222:225], v[8:11]
	s_setprio 0
	s_setprio 1
	v_mfma_f32_16x16x32_bf16 v[52:55], v[166:169], v[182:185], v[52:55]
	v_mfma_f32_16x16x32_bf16 v[48:51], v[174:177], v[182:185], v[48:51]
	v_mfma_f32_16x16x32_bf16 v[36:39], v[166:169], v[194:197], v[36:39]
	v_mfma_f32_16x16x32_bf16 v[32:35], v[174:177], v[194:197], v[32:35]
	v_mfma_f32_16x16x32_bf16 v[20:23], v[166:169], v[210:213], v[20:23]
	v_mfma_f32_16x16x32_bf16 v[16:19], v[174:177], v[210:213], v[16:19]
	v_mfma_f32_16x16x32_bf16 v[4:7], v[166:169], v[218:221], v[4:7]
	v_mfma_f32_16x16x32_bf16 v[0:3], v[174:177], v[218:221], v[0:3]
	v_mfma_f32_16x16x32_bf16 v[52:55], v[170:173], v[186:189], v[52:55]
	v_mfma_f32_16x16x32_bf16 v[48:51], v[178:181], v[186:189], v[48:51]
	v_mfma_f32_16x16x32_bf16 v[36:39], v[170:173], v[206:209], v[36:39]
	v_mfma_f32_16x16x32_bf16 v[32:35], v[178:181], v[206:209], v[32:35]
	v_mfma_f32_16x16x32_bf16 v[20:23], v[170:173], v[214:217], v[20:23]
	v_mfma_f32_16x16x32_bf16 v[16:19], v[178:181], v[214:217], v[16:19]
	v_mfma_f32_16x16x32_bf16 v[4:7], v[170:173], v[222:225], v[4:7]
	v_mfma_f32_16x16x32_bf16 v[0:3], v[178:181], v[222:225], v[0:3]
	s_setprio 0
	s_barrier
	s_add_u32 s0, s0, 0x100
	s_addc_u32 s1, s1, 0
	s_add_u32 s26, s26, 0x100
	s_addc_u32 s27, s27, 0
	s_cmp_ge_i32 s46, s41
	s_mov_b32 s24, s46
	s_cbranch_scc0 .LBB0_373
	s_movk_i32 s49, 0x4000

; #define PG8_STAGE(bufoff, gbase, voff) do { _Pragma("unroll") for (int _i = 0; _i < 2; ++_i) \
;         __builtin_amdgcn_global_load_lds((const unsigned*)((const char*)(gbase) + (voff)[_i]), (PG8_LAS unsigned*)(lds + (bufoff) + ldsw + _i * 8192), 16, 0, 0); } while (0)
; #define PG8_LDA(dst, b, h) do { _Pragma("unroll") for (int m = 0; m < 4; ++m) _Pragma("unroll") for (int k = 0; k < 2; ++k) dst[m][k] = *(const PG8_LAS bf16x8*)(lds + PG8_SA(b, h) + aoff + m * 2048 + k * 1024); } while (0)
; #define PG8_LDB(dst, b, h) do { _Pragma("unroll") for (int n = 0; n < 2; ++n) _Pragma("unroll") for (int k = 0; k < 2; ++k) dst[n][k] = *(const PG8_LAS bf16x8*)(lds + PG8_SB(b, h) + boff + n * 2048 + k * 1024); } while (0)
; #define PG8_MMA(ai, bj, At, Bt) do { __builtin_amdgcn_s_setprio(1); _Pragma("unroll") for (int m = 0; m < 4; ++m) _Pragma("unroll") for (int n = 0; n < 2; ++n) _Pragma("unroll") for (int k = 0; k < 2; ++k) \
;         acc[ai][bj][m][n] = __builtin_amdgcn_mfma_f32_16x16x32_bf16(Bt[n][k], At[m][k], acc[ai][bj][m][n], 0, 0, 0); __builtin_amdgcn_s_setprio(0); } while (0)
; #define PG8_WAIT_V(n) asm volatile("s_waitcnt vmcnt(" #n ")" ::: "memory")
; #define PG8_WAIT_L(n) asm volatile("s_waitcnt lgkmcnt(" #n ")" ::: "memory")
; template <class Epi, class Sched, bool ALIGN_EPI = false, bool SP2 = false>
; __device__ __forceinline__ void gemm_phase(PG8_LAS unsigned char* lds, const Gemm g, const Sched& S, const Epi& E) {
;     ...
;             const bool last = (t == nt - 2);
;             const char* a1 = cA + (size_t)(t + 1) * kstep;
;             const char* a2 = last ? nA : cA + (size_t)(t + 2) * kstep; const char* b2 = last ? nB : cB + (size_t)(t + 2) * kstep;
;             const char* a3 = a2 + kstep; const char* b3 = b2 + kstep;
;             if (last && has_next) S.a_ready(nxt);
;             if constexpr (SP2) {
;             PG8_LDB(B0, 0, 0); PG8_LDB(B1, 0, 1); PG8_SCHED; PG8_LDA(At, 0, 0); PG8_STAGE(PG8_SA(1, 1), a1 + hstep, voffA);
;             PG8_WAIT_V(8); PG8_WAIT_L(0); PG8_BAR; PG8_MMA(0, 0, At, B0); PG8_MMA(0, 1, At, B1); PG8_BAR; PG8_SCHED;
;             PG8_LDA(At, 0, 1); PG8_STAGE(PG8_SB(0, 0), b2, voffB); PG8_STAGE(PG8_SB(0, 1), b2 + hstep, voffB); PG8_STAGE(PG8_SA(0, 0), a2, voffA);
;             PG8_WAIT_V(8); PG8_WAIT_L(0); PG8_BAR; PG8_MMA(1, 0, At, B0); PG8_MMA(1, 1, At, B1); PG8_BAR; PG8_SCHED;
.LBB0_429:
	s_add_i32 s78, s0, 2
	s_or_b32 s42, s0, 1
	s_lshl_b64 s[44:45], s[78:79], 7
	s_add_u32 s33, s26, s44
	s_addc_u32 s1, s27, s45
	s_add_i32 s46, 0, 0x10000
	s_cmp_eq_u32 s0, s40
	s_cselect_b32 s43, 0, s44
	s_cselect_b32 s1, s23, s1
	s_cselect_b32 s0, s22, s33
	s_cselect_b32 s33, 0, s45
	s_add_u32 s44, s8, s43
	s_addc_u32 s45, s9, s33
	s_add_i32 s33, 0, 0x14000
	v_add_u32_e32 v148, s46, v156
	v_add_u32_e32 v158, s33, v156
	ds_read_b128 v[128:131], v148
	ds_read_b128 v[132:135], v148 offset:1024
	ds_read_b128 v[144:147], v148 offset:2048
	ds_read_b128 v[148:151], v148 offset:3072
	ds_read_b128 v[152:155], v158
	ds_read_b128 v[162:165], v158 offset:1024
	ds_read_b128 v[166:169], v158 offset:2048
	ds_read_b128 v[170:173], v158 offset:3072
	s_mov_b32 s43, s79
	s_lshl_b64 s[42:43], s[42:43], 7
	s_add_u32 s42, s19, s42
	s_addc_u32 s43, s25, s43
	v_lshl_add_u64 v[158:159], s[42:43], 0, v[142:143]
	s_add_i32 m0, s29, 0xc000
	ds_read_b128 v[174:177], v157
	ds_read_b128 v[178:181], v157 offset:1024
	ds_read_b128 v[182:185], v157 offset:2048
	ds_read_b128 v[186:189], v157 offset:3072
	ds_read_b128 v[194:197], v157 offset:4096
	ds_read_b128 v[206:209], v157 offset:5120
	ds_read_b128 v[210:213], v157 offset:6144
	ds_read_b128 v[214:217], v157 offset:7168
	global_load_lds_dwordx4 v[158:159], off
	v_lshl_add_u64 v[158:159], s[42:43], 0, v[138:139]
	s_add_i32 m0, s29, 0xe000
	s_nop 0
	global_load_lds_dwordx4 v[158:159], off
	s_waitcnt vmcnt(8)
	s_waitcnt lgkmcnt(0)
	s_barrier
	s_setprio 1
	v_mfma_f32_16x16x32_bf16 v[124:127], v[128:131], v[174:177], v[124:127]
	v_mfma_f32_16x16x32_bf16 v[116:119], v[144:147], v[174:177], v[116:119]
	v_mfma_f32_16x16x32_bf16 v[108:111], v[128:131], v[182:185], v[108:111]
	v_mfma_f32_16x16x32_bf16 v[100:103], v[144:147], v[182:185], v[100:103]
	v_mfma_f32_16x16x32_bf16 v[92:95], v[128:131], v[194:197], v[92:95]
	v_mfma_f32_16x16x32_bf16 v[84:87], v[144:147], v[194:197], v[84:87]
	v_mfma_f32_16x16x32_bf16 v[76:79], v[128:131], v[210:213], v[76:79]
	v_mfma_f32_16x16x32_bf16 v[68:71], v[144:147], v[210:213], v[68:71]
	v_mfma_f32_16x16x32_bf16 v[124:127], v[132:135], v[178:181], v[124:127]
	v_mfma_f32_16x16x32_bf16 v[116:119], v[148:151], v[178:181], v[116:119]
	v_mfma_f32_16x16x32_bf16 v[108:111], v[132:135], v[186:189], v[108:111]
	v_mfma_f32_16x16x32_bf16 v[100:103], v[148:151], v[186:189], v[100:103]
	v_mfma_f32_16x16x32_bf16 v[92:95], v[132:135], v[206:209], v[92:95]
	v_mfma_f32_16x16x32_bf16 v[84:87], v[148:151], v[206:209], v[84:87]
	v_mfma_f32_16x16x32_bf16 v[76:79], v[132:135], v[214:217], v[76:79]
	v_mfma_f32_16x16x32_bf16 v[68:71], v[148:151], v[214:217], v[68:71]
	s_setprio 0
	s_setprio 1
	v_mfma_f32_16x16x32_bf16 v[120:123], v[152:155], v[174:177], v[120:123]
	v_mfma_f32_16x16x32_bf16 v[112:115], v[166:169], v[174:177], v[112:115]
	v_mfma_f32_16x16x32_bf16 v[104:107], v[152:155], v[182:185], v[104:107]
	v_mfma_f32_16x16x32_bf16 v[96:99], v[166:169], v[182:185], v[96:99]
	v_mfma_f32_16x16x32_bf16 v[88:91], v[152:155], v[194:197], v[88:91]
	v_mfma_f32_16x16x32_bf16 v[80:83], v[166:169], v[194:197], v[80:83]
	v_mfma_f32_16x16x32_bf16 v[72:75], v[152:155], v[210:213], v[72:75]
	v_mfma_f32_16x16x32_bf16 v[64:67], v[166:169], v[210:213], v[64:67]
	v_mfma_f32_16x16x32_bf16 v[120:123], v[162:165], v[178:181], v[120:123]
	v_mfma_f32_16x16x32_bf16 v[112:115], v[170:173], v[178:181], v[112:115]
	v_mfma_f32_16x16x32_bf16 v[104:107], v[162:165], v[186:189], v[104:107]
	v_mfma_f32_16x16x32_bf16 v[96:99], v[170:173], v[186:189], v[96:99]
	v_mfma_f32_16x16x32_bf16 v[88:91], v[162:165], v[206:209], v[88:91]
	v_mfma_f32_16x16x32_bf16 v[80:83], v[170:173], v[206:209], v[80:83]
	v_mfma_f32_16x16x32_bf16 v[72:75], v[162:165], v[214:217], v[72:75]
	v_mfma_f32_16x16x32_bf16 v[64:67], v[170:173], v[214:217], v[64:67]
	s_setprio 0
	s_barrier
	s_add_i32 s42, s46, s28
	v_lshl_add_u64 v[158:159], s[44:45], 0, v[140:141]
	s_mov_b32 m0, s42
	ds_read_b128 v[174:177], v157 offset:16384
	ds_read_b128 v[178:181], v157 offset:17408
	ds_read_b128 v[182:185], v157 offset:18432
	ds_read_b128 v[186:189], v157 offset:19456
	ds_read_b128 v[194:197], v157 offset:20480
	ds_read_b128 v[206:209], v157 offset:21504
	ds_read_b128 v[210:213], v157 offset:22528
	ds_read_b128 v[214:217], v157 offset:23552
	global_load_lds_dwordx4 v[158:159], off
	s_add_i32 m0, s42, 0x2000
	s_add_u32 s42, s44, s10
	v_lshl_add_u64 v[218:219], s[44:45], 0, v[136:137]
	s_addc_u32 s43, s45, s11
	s_add_i32 s33, s33, s28
	global_load_lds_dwordx4 v[218:219], off
	v_lshl_add_u64 v[220:221], s[42:43], 0, v[140:141]
	s_mov_b32 m0, s33
	v_lshl_add_u64 v[222:223], s[42:43], 0, v[136:137]
	global_load_lds_dwordx4 v[220:221], off
	s_add_i32 m0, s33, 0x2000
	v_lshl_add_u64 v[224:225], s[0:1], 0, v[142:143]
	global_load_lds_dwordx4 v[222:223], off
	s_mov_b32 m0, s29
	v_lshl_add_u64 v[226:227], s[0:1], 0, v[138:139]
	global_load_lds_dwordx4 v[224:225], off
	s_mov_b32 m0, s30
	s_nop 0
	global_load_lds_dwordx4 v[226:227], off
	s_waitcnt vmcnt(8)
	s_waitcnt lgkmcnt(0)
	s_barrier
; #define PG8_STAGE(bufoff, gbase, voff) do { _Pragma("unroll") for (int _i = 0; _i < 2; ++_i) \
;         __builtin_amdgcn_global_load_lds((const unsigned*)((const char*)(gbase) + (voff)[_i]), (PG8_LAS unsigned*)(lds + (bufoff) + ldsw + _i * 8192), 16, 0, 0); } while (0)
; #define PG8_LDA(dst, b, h) do { _Pragma("unroll") for (int m = 0; m < 4; ++m) _Pragma("unroll") for (int k = 0; k < 2; ++k) dst[m][k] = *(const PG8_LAS bf16x8*)(lds + PG8_SA(b, h) + aoff + m * 2048 + k * 1024); } while (0)
; #define PG8_LDB(dst, b, h) do { _Pragma("unroll") for (int n = 0; n < 2; ++n) _Pragma("unroll") for (int k = 0; k < 2; ++k) dst[n][k] = *(const PG8_LAS bf16x8*)(lds + PG8_SB(b, h) + boff + n * 2048 + k * 1024); } while (0)
; #define PG8_MMA(ai, bj, At, Bt) do { __builtin_amdgcn_s_setprio(1); _Pragma("unroll") for (int m = 0; m < 4; ++m) _Pragma("unroll") for (int n = 0; n < 2; ++n) _Pragma("unroll") for (int k = 0; k < 2; ++k) \
;         acc[ai][bj][m][n] = __builtin_amdgcn_mfma_f32_16x16x32_bf16(Bt[n][k], At[m][k], acc[ai][bj][m][n], 0, 0, 0); __builtin_amdgcn_s_setprio(0); } while (0)
; #define PG8_WAIT_V(n) asm volatile("s_waitcnt vmcnt(" #n ")" ::: "memory")
; #define PG8_WAIT_L(n) asm volatile("s_waitcnt lgkmcnt(" #n ")" ::: "memory")
; #define PG8_BAR __builtin_amdgcn_s_barrier()
; #define PG8_SCHED __builtin_amdgcn_sched_barrier(0)
; template <class Epi, class Sched, bool ALIGN_EPI = false, bool SP2 = false>
; __device__ __forceinline__ void gemm_phase(PG8_LAS unsigned char* lds, const Gemm g, const Sched& S, const Epi& E) {
;     ...
;             PG8_WAIT_V(8); PG8_WAIT_L(0); PG8_BAR; PG8_MMA(1, 0, At, B0); PG8_MMA(1, 1, At, B1); PG8_BAR; PG8_SCHED;
;             PG8_LDB(B0, 1, 0); PG8_LDB(B1, 1, 1); PG8_SCHED; PG8_LDA(At, 1, 0); PG8_STAGE(PG8_SA(0, 1), a2 + hstep, voffA);
;             PG8_WAIT_V(8); PG8_WAIT_L(0); PG8_BAR; PG8_MMA(0, 0, At, B0); PG8_MMA(0, 1, At, B1); PG8_BAR; PG8_SCHED;
	s_setprio 1
	v_mfma_f32_16x16x32_bf16 v[60:63], v[128:131], v[174:177], v[60:63]
	v_mfma_f32_16x16x32_bf16 v[52:55], v[144:147], v[174:177], v[52:55]
	v_mfma_f32_16x16x32_bf16 v[44:47], v[128:131], v[182:185], v[44:47]
	v_mfma_f32_16x16x32_bf16 v[36:39], v[144:147], v[182:185], v[36:39]
	v_mfma_f32_16x16x32_bf16 v[28:31], v[128:131], v[194:197], v[28:31]
	v_mfma_f32_16x16x32_bf16 v[20:23], v[144:147], v[194:197], v[20:23]
	v_mfma_f32_16x16x32_bf16 v[12:15], v[128:131], v[210:213], v[12:15]
	v_mfma_f32_16x16x32_bf16 v[4:7], v[144:147], v[210:213], v[4:7]
	v_mfma_f32_16x16x32_bf16 v[60:63], v[132:135], v[178:181], v[60:63]
	v_mfma_f32_16x16x32_bf16 v[52:55], v[148:151], v[178:181], v[52:55]
	v_mfma_f32_16x16x32_bf16 v[44:47], v[132:135], v[186:189], v[44:47]
	v_mfma_f32_16x16x32_bf16 v[36:39], v[148:151], v[186:189], v[36:39]
	v_mfma_f32_16x16x32_bf16 v[28:31], v[132:135], v[206:209], v[28:31]
	v_mfma_f32_16x16x32_bf16 v[20:23], v[148:151], v[206:209], v[20:23]
	v_mfma_f32_16x16x32_bf16 v[12:15], v[132:135], v[214:217], v[12:15]
	v_mfma_f32_16x16x32_bf16 v[4:7], v[148:151], v[214:217], v[4:7]
	s_setprio 0
	s_setprio 1
	v_mfma_f32_16x16x32_bf16 v[56:59], v[152:155], v[174:177], v[56:59]
	v_mfma_f32_16x16x32_bf16 v[48:51], v[166:169], v[174:177], v[48:51]
	v_mfma_f32_16x16x32_bf16 v[40:43], v[152:155], v[182:185], v[40:43]
	v_mfma_f32_16x16x32_bf16 v[32:35], v[166:169], v[182:185], v[32:35]
	v_mfma_f32_16x16x32_bf16 v[24:27], v[152:155], v[194:197], v[24:27]
	v_mfma_f32_16x16x32_bf16 v[16:19], v[166:169], v[194:197], v[16:19]
	v_mfma_f32_16x16x32_bf16 v[8:11], v[152:155], v[210:213], v[8:11]
	v_mfma_f32_16x16x32_bf16 v[0:3], v[166:169], v[210:213], v[0:3]
	v_mfma_f32_16x16x32_bf16 v[56:59], v[162:165], v[178:181], v[56:59]
	v_mfma_f32_16x16x32_bf16 v[48:51], v[170:173], v[178:181], v[48:51]
	v_mfma_f32_16x16x32_bf16 v[40:43], v[162:165], v[186:189], v[40:43]
	v_mfma_f32_16x16x32_bf16 v[32:35], v[170:173], v[186:189], v[32:35]
	v_mfma_f32_16x16x32_bf16 v[24:27], v[162:165], v[206:209], v[24:27]
	v_mfma_f32_16x16x32_bf16 v[16:19], v[170:173], v[206:209], v[16:19]
	v_mfma_f32_16x16x32_bf16 v[8:11], v[162:165], v[214:217], v[8:11]
	v_mfma_f32_16x16x32_bf16 v[0:3], v[170:173], v[214:217], v[0:3]
	s_setprio 0
	s_barrier
	s_add_i32 s33, 0, 0x18000
	s_add_i32 s42, 0, 0x1c000
	v_add_u32_e32 v148, s33, v156
	v_add_u32_e32 v160, s42, v156
	ds_read_b128 v[128:131], v148
	ds_read_b128 v[132:135], v148 offset:1024
	ds_read_b128 v[144:147], v148 offset:2048
	ds_read_b128 v[148:151], v148 offset:3072
	ds_read_b128 v[152:155], v160
	ds_read_b128 v[162:165], v160 offset:1024
	ds_read_b128 v[166:169], v160 offset:2048
	ds_read_b128 v[170:173], v160 offset:3072
	s_add_u32 s0, s0, s10
	s_addc_u32 s1, s1, s11
	s_mov_b32 m0, s31
	v_lshl_add_u64 v[228:229], s[0:1], 0, v[142:143]
	ds_read_b128 v[174:177], v157 offset:32768
	ds_read_b128 v[178:181], v157 offset:33792
	ds_read_b128 v[182:185], v157 offset:34816
	ds_read_b128 v[186:189], v157 offset:35840
	ds_read_b128 v[194:197], v157 offset:36864
	ds_read_b128 v[206:209], v157 offset:37888
	ds_read_b128 v[210:213], v157 offset:38912
	ds_read_b128 v[214:217], v157 offset:39936
	global_load_lds_dwordx4 v[228:229], off
	v_lshl_add_u64 v[228:229], s[0:1], 0, v[138:139]
	s_mov_b32 m0, s34
	s_nop 0
	global_load_lds_dwordx4 v[228:229], off
	s_waitcnt vmcnt(8)
	s_waitcnt lgkmcnt(0)
	s_barrier
	s_setprio 1
	v_mfma_f32_16x16x32_bf16 v[124:127], v[128:131], v[174:177], v[124:127]
	v_mfma_f32_16x16x32_bf16 v[116:119], v[144:147], v[174:177], v[116:119]
	v_mfma_f32_16x16x32_bf16 v[108:111], v[128:131], v[182:185], v[108:111]
	v_mfma_f32_16x16x32_bf16 v[100:103], v[144:147], v[182:185], v[100:103]
	v_mfma_f32_16x16x32_bf16 v[92:95], v[128:131], v[194:197], v[92:95]
	v_mfma_f32_16x16x32_bf16 v[84:87], v[144:147], v[194:197], v[84:87]
	v_mfma_f32_16x16x32_bf16 v[76:79], v[128:131], v[210:213], v[76:79]
	v_mfma_f32_16x16x32_bf16 v[68:71], v[144:147], v[210:213], v[68:71]
	v_mfma_f32_16x16x32_bf16 v[124:127], v[132:135], v[178:181], v[124:127]
	v_mfma_f32_16x16x32_bf16 v[116:119], v[148:151], v[178:181], v[116:119]
	v_mfma_f32_16x16x32_bf16 v[108:111], v[132:135], v[186:189], v[108:111]
	v_mfma_f32_16x16x32_bf16 v[100:103], v[148:151], v[186:189], v[100:103]
	v_mfma_f32_16x16x32_bf16 v[92:95], v[132:135], v[206:209], v[92:95]
	v_mfma_f32_16x16x32_bf16 v[84:87], v[148:151], v[206:209], v[84:87]
	v_mfma_f32_16x16x32_bf16 v[76:79], v[132:135], v[214:217], v[76:79]
	v_mfma_f32_16x16x32_bf16 v[68:71], v[148:151], v[214:217], v[68:71]
	s_setprio 0
	s_setprio 1
	v_mfma_f32_16x16x32_bf16 v[120:123], v[152:155], v[174:177], v[120:123]
	v_mfma_f32_16x16x32_bf16 v[112:115], v[166:169], v[174:177], v[112:115]
	v_mfma_f32_16x16x32_bf16 v[104:107], v[152:155], v[182:185], v[104:107]
	v_mfma_f32_16x16x32_bf16 v[96:99], v[166:169], v[182:185], v[96:99]
	v_mfma_f32_16x16x32_bf16 v[88:91], v[152:155], v[194:197], v[88:91]
	v_mfma_f32_16x16x32_bf16 v[80:83], v[166:169], v[194:197], v[80:83]
	v_mfma_f32_16x16x32_bf16 v[72:75], v[152:155], v[210:213], v[72:75]
	v_mfma_f32_16x16x32_bf16 v[64:67], v[166:169], v[210:213], v[64:67]
	v_mfma_f32_16x16x32_bf16 v[120:123], v[162:165], v[178:181], v[120:123]
	v_mfma_f32_16x16x32_bf16 v[112:115], v[170:173], v[178:181], v[112:115]
	v_mfma_f32_16x16x32_bf16 v[104:107], v[162:165], v[186:189], v[104:107]
	v_mfma_f32_16x16x32_bf16 v[96:99], v[170:173], v[186:189], v[96:99]
	v_mfma_f32_16x16x32_bf16 v[88:91], v[162:165], v[206:209], v[88:91]
	v_mfma_f32_16x16x32_bf16 v[80:83], v[170:173], v[206:209], v[80:83]
	v_mfma_f32_16x16x32_bf16 v[72:75], v[162:165], v[214:217], v[72:75]
	v_mfma_f32_16x16x32_bf16 v[64:67], v[170:173], v[214:217], v[64:67]
	s_setprio 0
	s_barrier
; #define PG8_STAGE(bufoff, gbase, voff) do { _Pragma("unroll") for (int _i = 0; _i < 2; ++_i) \
;         __builtin_amdgcn_global_load_lds((const unsigned*)((const char*)(gbase) + (voff)[_i]), (PG8_LAS unsigned*)(lds + (bufoff) + ldsw + _i * 8192), 16, 0, 0); } while (0)
; #define PG8_LDA(dst, b, h) do { _Pragma("unroll") for (int m = 0; m < 4; ++m) _Pragma("unroll") for (int k = 0; k < 2; ++k) dst[m][k] = *(const PG8_LAS bf16x8*)(lds + PG8_SA(b, h) + aoff + m * 2048 + k * 1024); } while (0)
; #define PG8_MMA(ai, bj, At, Bt) do { __builtin_amdgcn_s_setprio(1); _Pragma("unroll") for (int m = 0; m < 4; ++m) _Pragma("unroll") for (int n = 0; n < 2; ++n) _Pragma("unroll") for (int k = 0; k < 2; ++k) \
;         acc[ai][bj][m][n] = __builtin_amdgcn_mfma_f32_16x16x32_bf16(Bt[n][k], At[m][k], acc[ai][bj][m][n], 0, 0, 0); __builtin_amdgcn_s_setprio(0); } while (0)
; #define PG8_WAIT_V(n) asm volatile("s_waitcnt vmcnt(" #n ")" ::: "memory")
; #define PG8_WAIT_L(n) asm volatile("s_waitcnt lgkmcnt(" #n ")" ::: "memory")
; #define PG8_BAR __builtin_amdgcn_s_barrier()
; #define PG8_SCHED __builtin_amdgcn_sched_barrier(0)
; template <class Epi, class Sched, bool ALIGN_EPI = false, bool SP2 = false>
; __device__ __forceinline__ void gemm_phase(PG8_LAS unsigned char* lds, const Gemm g, const Sched& S, const Epi& E) {
;     ...
;             PG8_LDA(At, 1, 1); PG8_STAGE(PG8_SB(1, 0), b3, voffB); PG8_STAGE(PG8_SB(1, 1), b3 + hstep, voffB); PG8_STAGE(PG8_SA(1, 0), a3, voffA);
;             PG8_WAIT_V(8); PG8_WAIT_L(0); PG8_BAR; PG8_MMA(1, 0, At, B0); PG8_MMA(1, 1, At, B1); PG8_BAR; PG8_SCHED;
	s_add_i32 s0, s33, s28
	v_lshl_add_u64 v[158:159], v[158:159], 0, s[38:39]
	s_mov_b32 m0, s0
	ds_read_b128 v[174:177], v157 offset:49152
	ds_read_b128 v[178:181], v157 offset:50176
	ds_read_b128 v[182:185], v157 offset:51200
	ds_read_b128 v[186:189], v157 offset:52224
	ds_read_b128 v[194:197], v157 offset:53248
	ds_read_b128 v[206:209], v157 offset:54272
	ds_read_b128 v[210:213], v157 offset:55296
	ds_read_b128 v[214:217], v157 offset:56320
	global_load_lds_dwordx4 v[158:159], off
	v_lshl_add_u64 v[158:159], v[218:219], 0, s[38:39]
	s_add_i32 m0, s0, 0x2000
	s_add_i32 s0, s42, s28
	global_load_lds_dwordx4 v[158:159], off
	v_lshl_add_u64 v[158:159], v[220:221], 0, s[38:39]
	s_mov_b32 m0, s0
	s_nop 0
	global_load_lds_dwordx4 v[158:159], off
	v_lshl_add_u64 v[158:159], v[222:223], 0, s[38:39]
	s_add_i32 m0, s0, 0x2000
	s_nop 0
	global_load_lds_dwordx4 v[158:159], off
	v_lshl_add_u64 v[158:159], v[224:225], 0, s[38:39]
	s_mov_b32 m0, s36
	s_nop 0
	global_load_lds_dwordx4 v[158:159], off
	v_lshl_add_u64 v[158:159], v[226:227], 0, s[38:39]
	s_mov_b32 m0, s37
	s_nop 0
	global_load_lds_dwordx4 v[158:159], off
	s_waitcnt vmcnt(8)
	s_waitcnt lgkmcnt(0)
	s_barrier
	s_setprio 1
	v_mfma_f32_16x16x32_bf16 v[60:63], v[128:131], v[174:177], v[60:63]
	v_mfma_f32_16x16x32_bf16 v[52:55], v[144:147], v[174:177], v[52:55]
	v_mfma_f32_16x16x32_bf16 v[44:47], v[128:131], v[182:185], v[44:47]
	v_mfma_f32_16x16x32_bf16 v[36:39], v[144:147], v[182:185], v[36:39]
	v_mfma_f32_16x16x32_bf16 v[28:31], v[128:131], v[194:197], v[28:31]
	v_mfma_f32_16x16x32_bf16 v[20:23], v[144:147], v[194:197], v[20:23]
	v_mfma_f32_16x16x32_bf16 v[12:15], v[128:131], v[210:213], v[12:15]
	v_mfma_f32_16x16x32_bf16 v[4:7], v[144:147], v[210:213], v[4:7]
	v_mfma_f32_16x16x32_bf16 v[60:63], v[132:135], v[178:181], v[60:63]
	v_mfma_f32_16x16x32_bf16 v[52:55], v[148:151], v[178:181], v[52:55]
	v_mfma_f32_16x16x32_bf16 v[44:47], v[132:135], v[186:189], v[44:47]
	v_mfma_f32_16x16x32_bf16 v[36:39], v[148:151], v[186:189], v[36:39]
	v_mfma_f32_16x16x32_bf16 v[28:31], v[132:135], v[206:209], v[28:31]
	v_mfma_f32_16x16x32_bf16 v[20:23], v[148:151], v[206:209], v[20:23]
	v_mfma_f32_16x16x32_bf16 v[12:15], v[132:135], v[214:217], v[12:15]
	v_mfma_f32_16x16x32_bf16 v[4:7], v[148:151], v[214:217], v[4:7]
	s_setprio 0
	s_setprio 1
	v_mfma_f32_16x16x32_bf16 v[56:59], v[152:155], v[174:177], v[56:59]
	v_mfma_f32_16x16x32_bf16 v[48:51], v[166:169], v[174:177], v[48:51]
	v_mfma_f32_16x16x32_bf16 v[40:43], v[152:155], v[182:185], v[40:43]
	v_mfma_f32_16x16x32_bf16 v[32:35], v[166:169], v[182:185], v[32:35]
	v_mfma_f32_16x16x32_bf16 v[24:27], v[152:155], v[194:197], v[24:27]
	v_mfma_f32_16x16x32_bf16 v[16:19], v[166:169], v[194:197], v[16:19]
	v_mfma_f32_16x16x32_bf16 v[8:11], v[152:155], v[210:213], v[8:11]
	v_mfma_f32_16x16x32_bf16 v[0:3], v[166:169], v[210:213], v[0:3]
	v_mfma_f32_16x16x32_bf16 v[56:59], v[162:165], v[178:181], v[56:59]
	v_mfma_f32_16x16x32_bf16 v[48:51], v[170:173], v[178:181], v[48:51]
	v_mfma_f32_16x16x32_bf16 v[40:43], v[162:165], v[186:189], v[40:43]
	v_mfma_f32_16x16x32_bf16 v[32:35], v[170:173], v[186:189], v[32:35]
	v_mfma_f32_16x16x32_bf16 v[24:27], v[162:165], v[206:209], v[24:27]
	v_mfma_f32_16x16x32_bf16 v[16:19], v[170:173], v[206:209], v[16:19]
	v_mfma_f32_16x16x32_bf16 v[8:11], v[162:165], v[214:217], v[8:11]
	v_mfma_f32_16x16x32_bf16 v[0:3], v[170:173], v[214:217], v[0:3]
	s_setprio 0
	s_barrier
	s_cmp_ge_i32 s78, s35
	s_mov_b32 s0, s78
	s_cbranch_scc0 .LBB0_429

; #define PG8_STAGE(bufoff, gbase, voff) do { _Pragma("unroll") for (int _i = 0; _i < 2; ++_i) \
;         __builtin_amdgcn_global_load_lds((const unsigned*)((const char*)(gbase) + (voff)[_i]), (PG8_LAS unsigned*)(lds + (bufoff) + ldsw + _i * 8192), 16, 0, 0); } while (0)
; #define PG8_LDA(dst, b, h) do { _Pragma("unroll") for (int m = 0; m < 4; ++m) _Pragma("unroll") for (int k = 0; k < 2; ++k) dst[m][k] = *(const PG8_LAS bf16x8*)(lds + PG8_SA(b, h) + aoff + m * 2048 + k * 1024); } while (0)
; #define PG8_LDB(dst, b, h) do { _Pragma("unroll") for (int n = 0; n < 2; ++n) _Pragma("unroll") for (int k = 0; k < 2; ++k) dst[n][k] = *(const PG8_LAS bf16x8*)(lds + PG8_SB(b, h) + boff + n * 2048 + k * 1024); } while (0)
; #define PG8_MMA(ai, bj, At, Bt) do { __builtin_amdgcn_s_setprio(1); _Pragma("unroll") for (int m = 0; m < 4; ++m) _Pragma("unroll") for (int n = 0; n < 2; ++n) _Pragma("unroll") for (int k = 0; k < 2; ++k) \
;         acc[ai][bj][m][n] = __builtin_amdgcn_mfma_f32_16x16x32_bf16(Bt[n][k], At[m][k], acc[ai][bj][m][n], 0, 0, 0); __builtin_amdgcn_s_setprio(0); } while (0)
; #define PG8_WAIT_V(n) asm volatile("s_waitcnt vmcnt(" #n ")" ::: "memory")
; #define PG8_WAIT_L(n) asm volatile("s_waitcnt lgkmcnt(" #n ")" ::: "memory")
; template <class Epi, class Sched, bool ALIGN_EPI = false, bool SP2 = false>
; __device__ __forceinline__ void gemm_phase(PG8_LAS unsigned char* lds, const Gemm g, const Sched& S, const Epi& E) {
;     ...
;             const bool last = (t == nt - 2);
;             const char* a1 = cA + (size_t)(t + 1) * kstep;
;             const char* a2 = last ? nA : cA + (size_t)(t + 2) * kstep; const char* b2 = last ? nB : cB + (size_t)(t + 2) * kstep;
;             const char* a3 = a2 + kstep; const char* b3 = b2 + kstep;
;             if (last && has_next) S.a_ready(nxt);
;             if constexpr (SP2) {
;             PG8_LDB(B0, 0, 0); PG8_LDB(B1, 0, 1); PG8_SCHED; PG8_LDA(At, 0, 0); PG8_STAGE(PG8_SA(1, 1), a1 + hstep, voffA);
;             PG8_WAIT_V(8); PG8_WAIT_L(0); PG8_BAR; PG8_MMA(0, 0, At, B0); PG8_MMA(0, 1, At, B1); PG8_BAR; PG8_SCHED;
;             PG8_LDA(At, 0, 1); PG8_STAGE(PG8_SB(0, 0), b2, voffB); PG8_STAGE(PG8_SB(0, 1), b2 + hstep, voffB); PG8_STAGE(PG8_SA(0, 0), a2, voffA);
;             PG8_WAIT_V(8); PG8_WAIT_L(0); PG8_BAR; PG8_MMA(1, 0, At, B0); PG8_MMA(1, 1, At, B1); PG8_BAR; PG8_SCHED;
.LBB0_454:
	s_add_i32 s44, s22, 2
	s_add_u32 s45, s6, 0x80
	s_addc_u32 s23, s7, 0
	s_add_i32 s48, 0, 0x10000
	s_cmp_eq_u32 s40, s22
	s_cselect_b32 s23, s19, s23
	s_cselect_b32 s22, s18, s45
	v_add_u32_e32 v144, s48, v147
	s_cselect_b32 s47, s21, s25
	s_cselect_b32 s46, s20, s24
	s_add_i32 s45, 0, 0x14000
	ds_read_b128 v[140:143], v144
	ds_read_b128 v[150:153], v144 offset:1024
	ds_read_b128 v[154:157], v144 offset:2048
	ds_read_b128 v[162:165], v144 offset:3072
	v_add_u32_e32 v144, s45, v147
	ds_read_b128 v[166:169], v144
	ds_read_b128 v[170:173], v144 offset:1024
	ds_read_b128 v[174:177], v144 offset:2048
	ds_read_b128 v[178:181], v144 offset:3072
	v_lshl_add_u64 v[144:145], s[6:7], 0, v[136:137]
	s_add_i32 m0, s29, 0xc000
	ds_read_b128 v[182:185], v148
	ds_read_b128 v[186:189], v148 offset:1024
	ds_read_b128 v[194:197], v148 offset:2048
	ds_read_b128 v[206:209], v148 offset:3072
	ds_read_b128 v[210:213], v148 offset:4096
	ds_read_b128 v[214:217], v148 offset:5120
	ds_read_b128 v[218:221], v148 offset:6144
	ds_read_b128 v[222:225], v148 offset:7168
	global_load_lds_dwordx4 v[144:145], off
	v_lshl_add_u64 v[144:145], s[6:7], 0, v[138:139]
	s_add_i32 m0, s29, 0xe000
	s_nop 0
	global_load_lds_dwordx4 v[144:145], off
	s_waitcnt vmcnt(8)
	s_waitcnt lgkmcnt(0)
	s_barrier
	s_setprio 1
	v_mfma_f32_16x16x32_bf16 v[124:127], v[140:143], v[182:185], v[124:127]
	v_mfma_f32_16x16x32_bf16 v[116:119], v[154:157], v[182:185], v[116:119]
	v_mfma_f32_16x16x32_bf16 v[108:111], v[140:143], v[194:197], v[108:111]
	v_mfma_f32_16x16x32_bf16 v[100:103], v[154:157], v[194:197], v[100:103]
	v_mfma_f32_16x16x32_bf16 v[92:95], v[140:143], v[210:213], v[92:95]
	v_mfma_f32_16x16x32_bf16 v[84:87], v[154:157], v[210:213], v[84:87]
	v_mfma_f32_16x16x32_bf16 v[76:79], v[140:143], v[218:221], v[76:79]
	v_mfma_f32_16x16x32_bf16 v[68:71], v[154:157], v[218:221], v[68:71]
	v_mfma_f32_16x16x32_bf16 v[124:127], v[150:153], v[186:189], v[124:127]
	v_mfma_f32_16x16x32_bf16 v[116:119], v[162:165], v[186:189], v[116:119]
	v_mfma_f32_16x16x32_bf16 v[108:111], v[150:153], v[206:209], v[108:111]
	v_mfma_f32_16x16x32_bf16 v[100:103], v[162:165], v[206:209], v[100:103]
	v_mfma_f32_16x16x32_bf16 v[92:95], v[150:153], v[214:217], v[92:95]
	v_mfma_f32_16x16x32_bf16 v[84:87], v[162:165], v[214:217], v[84:87]
	v_mfma_f32_16x16x32_bf16 v[76:79], v[150:153], v[222:225], v[76:79]
	v_mfma_f32_16x16x32_bf16 v[68:71], v[162:165], v[222:225], v[68:71]
	s_setprio 0
	s_setprio 1
	v_mfma_f32_16x16x32_bf16 v[120:123], v[166:169], v[182:185], v[120:123]
	v_mfma_f32_16x16x32_bf16 v[112:115], v[174:177], v[182:185], v[112:115]
	v_mfma_f32_16x16x32_bf16 v[104:107], v[166:169], v[194:197], v[104:107]
	v_mfma_f32_16x16x32_bf16 v[96:99], v[174:177], v[194:197], v[96:99]
	v_mfma_f32_16x16x32_bf16 v[88:91], v[166:169], v[210:213], v[88:91]
	v_mfma_f32_16x16x32_bf16 v[80:83], v[174:177], v[210:213], v[80:83]
	v_mfma_f32_16x16x32_bf16 v[72:75], v[166:169], v[218:221], v[72:75]
	v_mfma_f32_16x16x32_bf16 v[64:67], v[174:177], v[218:221], v[64:67]
	v_mfma_f32_16x16x32_bf16 v[120:123], v[170:173], v[186:189], v[120:123]
	v_mfma_f32_16x16x32_bf16 v[112:115], v[178:181], v[186:189], v[112:115]
	v_mfma_f32_16x16x32_bf16 v[104:107], v[170:173], v[206:209], v[104:107]
	v_mfma_f32_16x16x32_bf16 v[96:99], v[178:181], v[206:209], v[96:99]
	v_mfma_f32_16x16x32_bf16 v[88:91], v[170:173], v[214:217], v[88:91]
	v_mfma_f32_16x16x32_bf16 v[80:83], v[178:181], v[214:217], v[80:83]
	v_mfma_f32_16x16x32_bf16 v[72:75], v[170:173], v[222:225], v[72:75]
	v_mfma_f32_16x16x32_bf16 v[64:67], v[178:181], v[222:225], v[64:67]
	s_setprio 0
	s_barrier
	s_add_i32 s48, s48, s28
	v_lshl_add_u64 v[144:145], s[46:47], 0, v[132:133]
	s_mov_b32 m0, s48
	ds_read_b128 v[182:185], v148 offset:16384
	ds_read_b128 v[186:189], v148 offset:17408
	ds_read_b128 v[194:197], v148 offset:18432
	ds_read_b128 v[206:209], v148 offset:19456
	ds_read_b128 v[210:213], v148 offset:20480
	ds_read_b128 v[214:217], v148 offset:21504
	ds_read_b128 v[218:221], v148 offset:22528
	ds_read_b128 v[222:225], v148 offset:23552
	global_load_lds_dwordx4 v[144:145], off
	s_add_i32 m0, s48, 0x2000
	v_lshl_add_u64 v[158:159], s[46:47], 0, v[128:129]
	s_add_u32 s46, s46, s2
	s_addc_u32 s47, s47, s3
	s_add_i32 s45, s45, s28
	global_load_lds_dwordx4 v[158:159], off
	v_lshl_add_u64 v[226:227], s[46:47], 0, v[132:133]
	s_mov_b32 m0, s45
	v_lshl_add_u64 v[228:229], s[46:47], 0, v[128:129]
	global_load_lds_dwordx4 v[226:227], off
	s_add_i32 m0, s45, 0x2000
	v_lshl_add_u64 v[230:231], s[22:23], 0, v[134:135]
	global_load_lds_dwordx4 v[228:229], off
	s_mov_b32 m0, s29
	v_lshl_add_u64 v[232:233], s[22:23], 0, v[130:131]
	global_load_lds_dwordx4 v[230:231], off
	s_mov_b32 m0, s30
	s_nop 0
	global_load_lds_dwordx4 v[232:233], off
	s_waitcnt vmcnt(8)
	s_waitcnt lgkmcnt(0)
	s_barrier
; #define PG8_STAGE(bufoff, gbase, voff) do { _Pragma("unroll") for (int _i = 0; _i < 2; ++_i) \
;         __builtin_amdgcn_global_load_lds((const unsigned*)((const char*)(gbase) + (voff)[_i]), (PG8_LAS unsigned*)(lds + (bufoff) + ldsw + _i * 8192), 16, 0, 0); } while (0)
; #define PG8_LDA(dst, b, h) do { _Pragma("unroll") for (int m = 0; m < 4; ++m) _Pragma("unroll") for (int k = 0; k < 2; ++k) dst[m][k] = *(const PG8_LAS bf16x8*)(lds + PG8_SA(b, h) + aoff + m * 2048 + k * 1024); } while (0)
; #define PG8_LDB(dst, b, h) do { _Pragma("unroll") for (int n = 0; n < 2; ++n) _Pragma("unroll") for (int k = 0; k < 2; ++k) dst[n][k] = *(const PG8_LAS bf16x8*)(lds + PG8_SB(b, h) + boff + n * 2048 + k * 1024); } while (0)
; #define PG8_MMA(ai, bj, At, Bt) do { __builtin_amdgcn_s_setprio(1); _Pragma("unroll") for (int m = 0; m < 4; ++m) _Pragma("unroll") for (int n = 0; n < 2; ++n) _Pragma("unroll") for (int k = 0; k < 2; ++k) \
;         acc[ai][bj][m][n] = __builtin_amdgcn_mfma_f32_16x16x32_bf16(Bt[n][k], At[m][k], acc[ai][bj][m][n], 0, 0, 0); __builtin_amdgcn_s_setprio(0); } while (0)
; #define PG8_WAIT_V(n) asm volatile("s_waitcnt vmcnt(" #n ")" ::: "memory")
; #define PG8_WAIT_L(n) asm volatile("s_waitcnt lgkmcnt(" #n ")" ::: "memory")
; #define PG8_BAR __builtin_amdgcn_s_barrier()
; #define PG8_SCHED __builtin_amdgcn_sched_barrier(0)
; template <class Epi, class Sched, bool ALIGN_EPI = false, bool SP2 = false>
; __device__ __forceinline__ void gemm_phase(PG8_LAS unsigned char* lds, const Gemm g, const Sched& S, const Epi& E) {
;     ...
;             PG8_WAIT_V(8); PG8_WAIT_L(0); PG8_BAR; PG8_MMA(1, 0, At, B0); PG8_MMA(1, 1, At, B1); PG8_BAR; PG8_SCHED;
;             PG8_LDB(B0, 1, 0); PG8_LDB(B1, 1, 1); PG8_SCHED; PG8_LDA(At, 1, 0); PG8_STAGE(PG8_SA(0, 1), a2 + hstep, voffA);
;             PG8_WAIT_V(8); PG8_WAIT_L(0); PG8_BAR; PG8_MMA(0, 0, At, B0); PG8_MMA(0, 1, At, B1); PG8_BAR; PG8_SCHED;
	s_setprio 1
	v_mfma_f32_16x16x32_bf16 v[60:63], v[140:143], v[182:185], v[60:63]
	v_mfma_f32_16x16x32_bf16 v[52:55], v[154:157], v[182:185], v[52:55]
	v_mfma_f32_16x16x32_bf16 v[44:47], v[140:143], v[194:197], v[44:47]
	v_mfma_f32_16x16x32_bf16 v[36:39], v[154:157], v[194:197], v[36:39]
	v_mfma_f32_16x16x32_bf16 v[28:31], v[140:143], v[210:213], v[28:31]
	v_mfma_f32_16x16x32_bf16 v[20:23], v[154:157], v[210:213], v[20:23]
	v_mfma_f32_16x16x32_bf16 v[12:15], v[140:143], v[218:221], v[12:15]
	v_mfma_f32_16x16x32_bf16 v[4:7], v[154:157], v[218:221], v[4:7]
	v_mfma_f32_16x16x32_bf16 v[60:63], v[150:153], v[186:189], v[60:63]
	v_mfma_f32_16x16x32_bf16 v[52:55], v[162:165], v[186:189], v[52:55]
	v_mfma_f32_16x16x32_bf16 v[44:47], v[150:153], v[206:209], v[44:47]
	v_mfma_f32_16x16x32_bf16 v[36:39], v[162:165], v[206:209], v[36:39]
	v_mfma_f32_16x16x32_bf16 v[28:31], v[150:153], v[214:217], v[28:31]
	v_mfma_f32_16x16x32_bf16 v[20:23], v[162:165], v[214:217], v[20:23]
	v_mfma_f32_16x16x32_bf16 v[12:15], v[150:153], v[222:225], v[12:15]
	v_mfma_f32_16x16x32_bf16 v[4:7], v[162:165], v[222:225], v[4:7]
	s_setprio 0
	s_setprio 1
	v_mfma_f32_16x16x32_bf16 v[56:59], v[166:169], v[182:185], v[56:59]
	v_mfma_f32_16x16x32_bf16 v[48:51], v[174:177], v[182:185], v[48:51]
	v_mfma_f32_16x16x32_bf16 v[40:43], v[166:169], v[194:197], v[40:43]
	v_mfma_f32_16x16x32_bf16 v[32:35], v[174:177], v[194:197], v[32:35]
	v_mfma_f32_16x16x32_bf16 v[24:27], v[166:169], v[210:213], v[24:27]
	v_mfma_f32_16x16x32_bf16 v[16:19], v[174:177], v[210:213], v[16:19]
	v_mfma_f32_16x16x32_bf16 v[8:11], v[166:169], v[218:221], v[8:11]
	v_mfma_f32_16x16x32_bf16 v[0:3], v[174:177], v[218:221], v[0:3]
	v_mfma_f32_16x16x32_bf16 v[56:59], v[170:173], v[186:189], v[56:59]
	v_mfma_f32_16x16x32_bf16 v[48:51], v[178:181], v[186:189], v[48:51]
	v_mfma_f32_16x16x32_bf16 v[40:43], v[170:173], v[206:209], v[40:43]
	v_mfma_f32_16x16x32_bf16 v[32:35], v[178:181], v[206:209], v[32:35]
	v_mfma_f32_16x16x32_bf16 v[24:27], v[170:173], v[214:217], v[24:27]
	v_mfma_f32_16x16x32_bf16 v[16:19], v[178:181], v[214:217], v[16:19]
	v_mfma_f32_16x16x32_bf16 v[8:11], v[170:173], v[222:225], v[8:11]
	v_mfma_f32_16x16x32_bf16 v[0:3], v[178:181], v[222:225], v[0:3]
	s_setprio 0
	s_barrier
	s_add_i32 s45, 0, 0x18000
	v_add_u32_e32 v146, s45, v147
	s_add_i32 s46, 0, 0x1c000
	ds_read_b128 v[140:143], v146
	ds_read_b128 v[150:153], v146 offset:1024
	ds_read_b128 v[154:157], v146 offset:2048
	ds_read_b128 v[162:165], v146 offset:3072
	v_add_u32_e32 v146, s46, v147
	ds_read_b128 v[166:169], v146
	ds_read_b128 v[170:173], v146 offset:1024
	ds_read_b128 v[174:177], v146 offset:2048
	ds_read_b128 v[178:181], v146 offset:3072
	s_add_u32 s22, s22, s2
	s_addc_u32 s23, s23, s3
	s_mov_b32 m0, s31
	v_lshl_add_u64 v[234:235], s[22:23], 0, v[134:135]
	ds_read_b128 v[182:185], v148 offset:32768
	ds_read_b128 v[186:189], v148 offset:33792
	ds_read_b128 v[194:197], v148 offset:34816
	ds_read_b128 v[206:209], v148 offset:35840
	ds_read_b128 v[210:213], v148 offset:36864
	ds_read_b128 v[214:217], v148 offset:37888
	ds_read_b128 v[218:221], v148 offset:38912
	ds_read_b128 v[222:225], v148 offset:39936
	global_load_lds_dwordx4 v[234:235], off
	v_lshl_add_u64 v[234:235], s[22:23], 0, v[130:131]
	s_mov_b32 m0, s34
	s_nop 0
	global_load_lds_dwordx4 v[234:235], off
	s_waitcnt vmcnt(8)
	s_waitcnt lgkmcnt(0)
	s_barrier
	s_setprio 1
	v_mfma_f32_16x16x32_bf16 v[124:127], v[140:143], v[182:185], v[124:127]
	v_mfma_f32_16x16x32_bf16 v[116:119], v[154:157], v[182:185], v[116:119]
	v_mfma_f32_16x16x32_bf16 v[108:111], v[140:143], v[194:197], v[108:111]
	v_mfma_f32_16x16x32_bf16 v[100:103], v[154:157], v[194:197], v[100:103]
	v_mfma_f32_16x16x32_bf16 v[92:95], v[140:143], v[210:213], v[92:95]
	v_mfma_f32_16x16x32_bf16 v[84:87], v[154:157], v[210:213], v[84:87]
	v_mfma_f32_16x16x32_bf16 v[76:79], v[140:143], v[218:221], v[76:79]
	v_mfma_f32_16x16x32_bf16 v[68:71], v[154:157], v[218:221], v[68:71]
	v_mfma_f32_16x16x32_bf16 v[124:127], v[150:153], v[186:189], v[124:127]
	v_mfma_f32_16x16x32_bf16 v[116:119], v[162:165], v[186:189], v[116:119]
	v_mfma_f32_16x16x32_bf16 v[108:111], v[150:153], v[206:209], v[108:111]
	v_mfma_f32_16x16x32_bf16 v[100:103], v[162:165], v[206:209], v[100:103]
	v_mfma_f32_16x16x32_bf16 v[92:95], v[150:153], v[214:217], v[92:95]
	v_mfma_f32_16x16x32_bf16 v[84:87], v[162:165], v[214:217], v[84:87]
	v_mfma_f32_16x16x32_bf16 v[76:79], v[150:153], v[222:225], v[76:79]
	v_mfma_f32_16x16x32_bf16 v[68:71], v[162:165], v[222:225], v[68:71]
	s_setprio 0
	s_setprio 1
	v_mfma_f32_16x16x32_bf16 v[120:123], v[166:169], v[182:185], v[120:123]
	v_mfma_f32_16x16x32_bf16 v[112:115], v[174:177], v[182:185], v[112:115]
	v_mfma_f32_16x16x32_bf16 v[104:107], v[166:169], v[194:197], v[104:107]
	v_mfma_f32_16x16x32_bf16 v[96:99], v[174:177], v[194:197], v[96:99]
	v_mfma_f32_16x16x32_bf16 v[88:91], v[166:169], v[210:213], v[88:91]
	v_mfma_f32_16x16x32_bf16 v[80:83], v[174:177], v[210:213], v[80:83]
	v_mfma_f32_16x16x32_bf16 v[72:75], v[166:169], v[218:221], v[72:75]
	v_mfma_f32_16x16x32_bf16 v[64:67], v[174:177], v[218:221], v[64:67]
	v_mfma_f32_16x16x32_bf16 v[120:123], v[170:173], v[186:189], v[120:123]
	v_mfma_f32_16x16x32_bf16 v[112:115], v[178:181], v[186:189], v[112:115]
	v_mfma_f32_16x16x32_bf16 v[104:107], v[170:173], v[206:209], v[104:107]
	v_mfma_f32_16x16x32_bf16 v[96:99], v[178:181], v[206:209], v[96:99]
	v_mfma_f32_16x16x32_bf16 v[88:91], v[170:173], v[214:217], v[88:91]
	v_mfma_f32_16x16x32_bf16 v[80:83], v[178:181], v[214:217], v[80:83]
	v_mfma_f32_16x16x32_bf16 v[72:75], v[170:173], v[222:225], v[72:75]
	v_mfma_f32_16x16x32_bf16 v[64:67], v[178:181], v[222:225], v[64:67]
	s_setprio 0
	s_barrier
; #define PG8_STAGE(bufoff, gbase, voff) do { _Pragma("unroll") for (int _i = 0; _i < 2; ++_i) \
;         __builtin_amdgcn_global_load_lds((const unsigned*)((const char*)(gbase) + (voff)[_i]), (PG8_LAS unsigned*)(lds + (bufoff) + ldsw + _i * 8192), 16, 0, 0); } while (0)
; #define PG8_LDA(dst, b, h) do { _Pragma("unroll") for (int m = 0; m < 4; ++m) _Pragma("unroll") for (int k = 0; k < 2; ++k) dst[m][k] = *(const PG8_LAS bf16x8*)(lds + PG8_SA(b, h) + aoff + m * 2048 + k * 1024); } while (0)
; #define PG8_MMA(ai, bj, At, Bt) do { __builtin_amdgcn_s_setprio(1); _Pragma("unroll") for (int m = 0; m < 4; ++m) _Pragma("unroll") for (int n = 0; n < 2; ++n) _Pragma("unroll") for (int k = 0; k < 2; ++k) \
;         acc[ai][bj][m][n] = __builtin_amdgcn_mfma_f32_16x16x32_bf16(Bt[n][k], At[m][k], acc[ai][bj][m][n], 0, 0, 0); __builtin_amdgcn_s_setprio(0); } while (0)
; #define PG8_WAIT_V(n) asm volatile("s_waitcnt vmcnt(" #n ")" ::: "memory")
; #define PG8_WAIT_L(n) asm volatile("s_waitcnt lgkmcnt(" #n ")" ::: "memory")
; #define PG8_BAR __builtin_amdgcn_s_barrier()
; #define PG8_SCHED __builtin_amdgcn_sched_barrier(0)
; template <class Epi, class Sched, bool ALIGN_EPI = false, bool SP2 = false>
; __device__ __forceinline__ void gemm_phase(PG8_LAS unsigned char* lds, const Gemm g, const Sched& S, const Epi& E) {
;     ...
;             PG8_LDA(At, 1, 1); PG8_STAGE(PG8_SB(1, 0), b3, voffB); PG8_STAGE(PG8_SB(1, 1), b3 + hstep, voffB); PG8_STAGE(PG8_SA(1, 0), a3, voffA);
;             PG8_WAIT_V(8); PG8_WAIT_L(0); PG8_BAR; PG8_MMA(1, 0, At, B0); PG8_MMA(1, 1, At, B1); PG8_BAR; PG8_SCHED;
	s_add_i32 s22, s45, s28
	v_lshl_add_u64 v[144:145], v[144:145], 0, s[38:39]
	s_mov_b32 m0, s22
	ds_read_b128 v[182:185], v148 offset:49152
	ds_read_b128 v[186:189], v148 offset:50176
	ds_read_b128 v[194:197], v148 offset:51200
	ds_read_b128 v[206:209], v148 offset:52224
	ds_read_b128 v[210:213], v148 offset:53248
	ds_read_b128 v[214:217], v148 offset:54272
	ds_read_b128 v[218:221], v148 offset:55296
	ds_read_b128 v[222:225], v148 offset:56320
	global_load_lds_dwordx4 v[144:145], off
	v_lshl_add_u64 v[144:145], v[158:159], 0, s[38:39]
	s_add_i32 m0, s22, 0x2000
	s_add_i32 s22, s46, s28
	global_load_lds_dwordx4 v[144:145], off
	v_lshl_add_u64 v[144:145], v[226:227], 0, s[38:39]
	s_mov_b32 m0, s22
	s_nop 0
	global_load_lds_dwordx4 v[144:145], off
	v_lshl_add_u64 v[144:145], v[228:229], 0, s[38:39]
	s_add_i32 m0, s22, 0x2000
	s_nop 0
	global_load_lds_dwordx4 v[144:145], off
	v_lshl_add_u64 v[144:145], v[230:231], 0, s[38:39]
	s_mov_b32 m0, s35
	s_nop 0
	global_load_lds_dwordx4 v[144:145], off
	v_lshl_add_u64 v[144:145], v[232:233], 0, s[38:39]
	s_mov_b32 m0, s36
	s_nop 0
	global_load_lds_dwordx4 v[144:145], off
	s_waitcnt vmcnt(8)
	s_waitcnt lgkmcnt(0)
	s_barrier
	s_setprio 1
	v_mfma_f32_16x16x32_bf16 v[60:63], v[140:143], v[182:185], v[60:63]
	v_mfma_f32_16x16x32_bf16 v[52:55], v[154:157], v[182:185], v[52:55]
	v_mfma_f32_16x16x32_bf16 v[44:47], v[140:143], v[194:197], v[44:47]
	v_mfma_f32_16x16x32_bf16 v[36:39], v[154:157], v[194:197], v[36:39]
	v_mfma_f32_16x16x32_bf16 v[28:31], v[140:143], v[210:213], v[28:31]
	v_mfma_f32_16x16x32_bf16 v[20:23], v[154:157], v[210:213], v[20:23]
	v_mfma_f32_16x16x32_bf16 v[12:15], v[140:143], v[218:221], v[12:15]
	v_mfma_f32_16x16x32_bf16 v[4:7], v[154:157], v[218:221], v[4:7]
	v_mfma_f32_16x16x32_bf16 v[60:63], v[150:153], v[186:189], v[60:63]
	v_mfma_f32_16x16x32_bf16 v[52:55], v[162:165], v[186:189], v[52:55]
	v_mfma_f32_16x16x32_bf16 v[44:47], v[150:153], v[206:209], v[44:47]
	v_mfma_f32_16x16x32_bf16 v[36:39], v[162:165], v[206:209], v[36:39]
	v_mfma_f32_16x16x32_bf16 v[28:31], v[150:153], v[214:217], v[28:31]
	v_mfma_f32_16x16x32_bf16 v[20:23], v[162:165], v[214:217], v[20:23]
	v_mfma_f32_16x16x32_bf16 v[12:15], v[150:153], v[222:225], v[12:15]
	v_mfma_f32_16x16x32_bf16 v[4:7], v[162:165], v[222:225], v[4:7]
	s_setprio 0
	s_setprio 1
	v_mfma_f32_16x16x32_bf16 v[56:59], v[166:169], v[182:185], v[56:59]
	v_mfma_f32_16x16x32_bf16 v[48:51], v[174:177], v[182:185], v[48:51]
	v_mfma_f32_16x16x32_bf16 v[40:43], v[166:169], v[194:197], v[40:43]
	v_mfma_f32_16x16x32_bf16 v[32:35], v[174:177], v[194:197], v[32:35]
	v_mfma_f32_16x16x32_bf16 v[24:27], v[166:169], v[210:213], v[24:27]
	v_mfma_f32_16x16x32_bf16 v[16:19], v[174:177], v[210:213], v[16:19]
	v_mfma_f32_16x16x32_bf16 v[8:11], v[166:169], v[218:221], v[8:11]
	v_mfma_f32_16x16x32_bf16 v[0:3], v[174:177], v[218:221], v[0:3]
	v_mfma_f32_16x16x32_bf16 v[56:59], v[170:173], v[186:189], v[56:59]
	v_mfma_f32_16x16x32_bf16 v[48:51], v[178:181], v[186:189], v[48:51]
	v_mfma_f32_16x16x32_bf16 v[40:43], v[170:173], v[206:209], v[40:43]
	v_mfma_f32_16x16x32_bf16 v[32:35], v[178:181], v[206:209], v[32:35]
	v_mfma_f32_16x16x32_bf16 v[24:27], v[170:173], v[214:217], v[24:27]
	v_mfma_f32_16x16x32_bf16 v[16:19], v[178:181], v[214:217], v[16:19]
	v_mfma_f32_16x16x32_bf16 v[8:11], v[170:173], v[222:225], v[8:11]
	v_mfma_f32_16x16x32_bf16 v[0:3], v[178:181], v[222:225], v[0:3]
	s_setprio 0
	s_barrier
	s_add_u32 s6, s6, 0x100
	s_addc_u32 s7, s7, 0
	s_add_u32 s24, s24, 0x100
	s_addc_u32 s25, s25, 0
	s_cmp_ge_i32 s44, s37
	s_mov_b32 s22, s44
	s_cbranch_scc0 .LBB0_454

; #define PG8_STAGE(bufoff, gbase, voff) do { _Pragma("unroll") for (int _i = 0; _i < 2; ++_i) \
;         __builtin_amdgcn_global_load_lds((const unsigned*)((const char*)(gbase) + (voff)[_i]), (PG8_LAS unsigned*)(lds + (bufoff) + ldsw + _i * 8192), 16, 0, 0); } while (0)
; #define PG8_LDA(dst, b, h) do { _Pragma("unroll") for (int m = 0; m < 4; ++m) _Pragma("unroll") for (int k = 0; k < 2; ++k) dst[m][k] = *(const PG8_LAS bf16x8*)(lds + PG8_SA(b, h) + aoff + m * 2048 + k * 1024); } while (0)
; #define PG8_LDB(dst, b, h) do { _Pragma("unroll") for (int n = 0; n < 2; ++n) _Pragma("unroll") for (int k = 0; k < 2; ++k) dst[n][k] = *(const PG8_LAS bf16x8*)(lds + PG8_SB(b, h) + boff + n * 2048 + k * 1024); } while (0)
; #define PG8_MMA(ai, bj, At, Bt) do { __builtin_amdgcn_s_setprio(1); _Pragma("unroll") for (int m = 0; m < 4; ++m) _Pragma("unroll") for (int n = 0; n < 2; ++n) _Pragma("unroll") for (int k = 0; k < 2; ++k) \
;         acc[ai][bj][m][n] = __builtin_amdgcn_mfma_f32_16x16x32_bf16(Bt[n][k], At[m][k], acc[ai][bj][m][n], 0, 0, 0); __builtin_amdgcn_s_setprio(0); } while (0)
; #define PG8_WAIT_V(n) asm volatile("s_waitcnt vmcnt(" #n ")" ::: "memory")
; #define PG8_WAIT_L(n) asm volatile("s_waitcnt lgkmcnt(" #n ")" ::: "memory")
; template <class Epi, class Sched, bool ALIGN_EPI = false, bool SP2 = false>
; __device__ __forceinline__ void gemm_phase(PG8_LAS unsigned char* lds, const Gemm g, const Sched& S, const Epi& E) {
;     ...
;             const bool last = (t == nt - 2);
;             const char* a1 = cA + (size_t)(t + 1) * kstep;
;             const char* a2 = last ? nA : cA + (size_t)(t + 2) * kstep; const char* b2 = last ? nB : cB + (size_t)(t + 2) * kstep;
;             const char* a3 = a2 + kstep; const char* b3 = b2 + kstep;
;             if (last && has_next) S.a_ready(nxt);
;             if constexpr (SP2) {
;             PG8_LDB(B0, 0, 0); PG8_LDB(B1, 0, 1); PG8_SCHED; PG8_LDA(At, 0, 0); PG8_STAGE(PG8_SA(1, 1), a1 + hstep, voffA);
;             PG8_WAIT_V(8); PG8_WAIT_L(0); PG8_BAR; PG8_MMA(0, 0, At, B0); PG8_MMA(0, 1, At, B1); PG8_BAR; PG8_SCHED;
;             PG8_LDA(At, 0, 1); PG8_STAGE(PG8_SB(0, 0), b2, voffB); PG8_STAGE(PG8_SB(0, 1), b2 + hstep, voffB); PG8_STAGE(PG8_SA(0, 0), a2, voffA);
;             PG8_WAIT_V(8); PG8_WAIT_L(0); PG8_BAR; PG8_MMA(1, 0, At, B0); PG8_MMA(1, 1, At, B1); PG8_BAR; PG8_SCHED;
.LBB0_945:
	s_add_u32 s6, s4, 0xfffc0080
	s_addc_u32 s7, s5, -1
	s_add_i32 s49, 0, 0x10000
	s_cmp_eq_u32 s48, 12
	s_cselect_b32 s23, s15, s7
	s_cselect_b32 s22, s44, s6
	s_cselect_b32 s7, s17, s47
	s_cselect_b32 s6, s45, s46
	s_add_i32 s52, 0, 0x14000
	v_add_u32_e32 v56, s49, v205
	v_add_u32_e32 v158, s52, v205
	ds_read_b128 v[40:43], v56
	ds_read_b128 v[44:47], v56 offset:1024
	ds_read_b128 v[52:55], v56 offset:2048
	ds_read_b128 v[56:59], v56 offset:3072
	ds_read_b128 v[144:147], v158
	ds_read_b128 v[162:165], v158 offset:1024
	ds_read_b128 v[166:169], v158 offset:2048
	ds_read_b128 v[170:173], v158 offset:3072
	v_lshl_add_u64 v[158:159], s[4:5], 0, v[154:155]
	s_add_i32 m0, s29, 0xc000
	ds_read_b128 v[174:177], v206
	ds_read_b128 v[178:181], v206 offset:1024
	ds_read_b128 v[182:185], v206 offset:2048
	ds_read_b128 v[186:189], v206 offset:3072
	ds_read_b128 v[194:197], v206 offset:4096
	ds_read_b128 v[208:211], v206 offset:5120
	ds_read_b128 v[212:215], v206 offset:6144
	ds_read_b128 v[216:219], v206 offset:7168
	global_load_lds_dwordx4 v[158:159], off
	v_lshl_add_u64 v[158:159], s[4:5], 0, v[156:157]
	s_add_i32 m0, s29, 0xe000
	s_nop 0
	global_load_lds_dwordx4 v[158:159], off
	s_waitcnt vmcnt(8)
	s_waitcnt lgkmcnt(0)
	s_barrier
	s_setprio 1
	v_mfma_f32_16x16x32_bf16 v[140:143], v[40:43], v[174:177], v[140:143]
	v_mfma_f32_16x16x32_bf16 v[136:139], v[52:55], v[174:177], v[136:139]
	v_mfma_f32_16x16x32_bf16 v[124:127], v[40:43], v[182:185], v[124:127]
	v_mfma_f32_16x16x32_bf16 v[120:123], v[52:55], v[182:185], v[120:123]
	v_mfma_f32_16x16x32_bf16 v[108:111], v[40:43], v[194:197], v[108:111]
	v_mfma_f32_16x16x32_bf16 v[104:107], v[52:55], v[194:197], v[104:107]
	v_mfma_f32_16x16x32_bf16 v[92:95], v[40:43], v[212:215], v[92:95]
	v_mfma_f32_16x16x32_bf16 v[88:91], v[52:55], v[212:215], v[88:91]
	v_mfma_f32_16x16x32_bf16 v[140:143], v[44:47], v[178:181], v[140:143]
	v_mfma_f32_16x16x32_bf16 v[136:139], v[56:59], v[178:181], v[136:139]
	v_mfma_f32_16x16x32_bf16 v[124:127], v[44:47], v[186:189], v[124:127]
	v_mfma_f32_16x16x32_bf16 v[120:123], v[56:59], v[186:189], v[120:123]
	v_mfma_f32_16x16x32_bf16 v[108:111], v[44:47], v[208:211], v[108:111]
	v_mfma_f32_16x16x32_bf16 v[104:107], v[56:59], v[208:211], v[104:107]
	v_mfma_f32_16x16x32_bf16 v[92:95], v[44:47], v[216:219], v[92:95]
	v_mfma_f32_16x16x32_bf16 v[88:91], v[56:59], v[216:219], v[88:91]
	s_setprio 0
	s_setprio 1
	v_mfma_f32_16x16x32_bf16 v[132:135], v[144:147], v[174:177], v[132:135]
	v_mfma_f32_16x16x32_bf16 v[128:131], v[166:169], v[174:177], v[128:131]
	v_mfma_f32_16x16x32_bf16 v[116:119], v[144:147], v[182:185], v[116:119]
	v_mfma_f32_16x16x32_bf16 v[112:115], v[166:169], v[182:185], v[112:115]
	v_mfma_f32_16x16x32_bf16 v[100:103], v[144:147], v[194:197], v[100:103]
	v_mfma_f32_16x16x32_bf16 v[96:99], v[166:169], v[194:197], v[96:99]
	v_mfma_f32_16x16x32_bf16 v[84:87], v[144:147], v[212:215], v[84:87]
	v_mfma_f32_16x16x32_bf16 v[80:83], v[166:169], v[212:215], v[80:83]
	v_mfma_f32_16x16x32_bf16 v[132:135], v[162:165], v[178:181], v[132:135]
	v_mfma_f32_16x16x32_bf16 v[128:131], v[170:173], v[178:181], v[128:131]
	v_mfma_f32_16x16x32_bf16 v[116:119], v[162:165], v[186:189], v[116:119]
	v_mfma_f32_16x16x32_bf16 v[112:115], v[170:173], v[186:189], v[112:115]
	v_mfma_f32_16x16x32_bf16 v[100:103], v[162:165], v[208:211], v[100:103]
	v_mfma_f32_16x16x32_bf16 v[96:99], v[170:173], v[208:211], v[96:99]
	v_mfma_f32_16x16x32_bf16 v[84:87], v[162:165], v[216:219], v[84:87]
	v_mfma_f32_16x16x32_bf16 v[80:83], v[170:173], v[216:219], v[80:83]
	s_setprio 0
	s_barrier
	s_add_i32 s49, s49, s28
	v_lshl_add_u64 v[158:159], s[6:7], 0, v[160:161]
	s_mov_b32 m0, s49
	ds_read_b128 v[174:177], v206 offset:16384
	ds_read_b128 v[178:181], v206 offset:17408
	ds_read_b128 v[182:185], v206 offset:18432
	ds_read_b128 v[186:189], v206 offset:19456
	ds_read_b128 v[194:197], v206 offset:20480
	ds_read_b128 v[208:211], v206 offset:21504
	ds_read_b128 v[212:215], v206 offset:22528
	ds_read_b128 v[216:219], v206 offset:23552
	global_load_lds_dwordx4 v[158:159], off
	s_add_i32 m0, s49, 0x2000
	s_add_u32 s50, s6, 0x40000
	v_lshl_add_u64 v[220:221], s[6:7], 0, v[148:149]
	s_addc_u32 s51, s7, 0
	s_add_i32 s49, s52, s28
	global_load_lds_dwordx4 v[220:221], off
	v_lshl_add_u64 v[222:223], s[50:51], 0, v[160:161]
	s_mov_b32 m0, s49
	v_lshl_add_u64 v[224:225], s[22:23], 0, v[150:151]
	global_load_lds_dwordx4 v[222:223], off
	v_lshl_add_u64 v[222:223], s[50:51], 0, v[148:149]
	s_add_i32 m0, s49, 0x2000
	s_nop 0
	global_load_lds_dwordx4 v[222:223], off
	v_lshl_add_u64 v[222:223], s[22:23], 0, v[152:153]
	s_mov_b32 m0, s29
	s_nop 0
	global_load_lds_dwordx4 v[222:223], off
	s_mov_b32 m0, s30
	s_nop 0
	global_load_lds_dwordx4 v[224:225], off
	s_waitcnt vmcnt(8)
	s_waitcnt lgkmcnt(0)
	s_barrier
; #define PG8_STAGE(bufoff, gbase, voff) do { _Pragma("unroll") for (int _i = 0; _i < 2; ++_i) \
;         __builtin_amdgcn_global_load_lds((const unsigned*)((const char*)(gbase) + (voff)[_i]), (PG8_LAS unsigned*)(lds + (bufoff) + ldsw + _i * 8192), 16, 0, 0); } while (0)
; #define PG8_LDA(dst, b, h) do { _Pragma("unroll") for (int m = 0; m < 4; ++m) _Pragma("unroll") for (int k = 0; k < 2; ++k) dst[m][k] = *(const PG8_LAS bf16x8*)(lds + PG8_SA(b, h) + aoff + m * 2048 + k * 1024); } while (0)
; #define PG8_LDB(dst, b, h) do { _Pragma("unroll") for (int n = 0; n < 2; ++n) _Pragma("unroll") for (int k = 0; k < 2; ++k) dst[n][k] = *(const PG8_LAS bf16x8*)(lds + PG8_SB(b, h) + boff + n * 2048 + k * 1024); } while (0)
; #define PG8_MMA(ai, bj, At, Bt) do { __builtin_amdgcn_s_setprio(1); _Pragma("unroll") for (int m = 0; m < 4; ++m) _Pragma("unroll") for (int n = 0; n < 2; ++n) _Pragma("unroll") for (int k = 0; k < 2; ++k) \
;         acc[ai][bj][m][n] = __builtin_amdgcn_mfma_f32_16x16x32_bf16(Bt[n][k], At[m][k], acc[ai][bj][m][n], 0, 0, 0); __builtin_amdgcn_s_setprio(0); } while (0)
; #define PG8_WAIT_V(n) asm volatile("s_waitcnt vmcnt(" #n ")" ::: "memory")
; #define PG8_WAIT_L(n) asm volatile("s_waitcnt lgkmcnt(" #n ")" ::: "memory")
; #define PG8_BAR __builtin_amdgcn_s_barrier()
; #define PG8_SCHED __builtin_amdgcn_sched_barrier(0)
; template <class Epi, class Sched, bool ALIGN_EPI = false, bool SP2 = false>
; __device__ __forceinline__ void gemm_phase(PG8_LAS unsigned char* lds, const Gemm g, const Sched& S, const Epi& E) {
;     ...
;             PG8_WAIT_V(8); PG8_WAIT_L(0); PG8_BAR; PG8_MMA(1, 0, At, B0); PG8_MMA(1, 1, At, B1); PG8_BAR; PG8_SCHED;
;             PG8_LDB(B0, 1, 0); PG8_LDB(B1, 1, 1); PG8_SCHED; PG8_LDA(At, 1, 0); PG8_STAGE(PG8_SA(0, 1), a2 + hstep, voffA);
;             PG8_WAIT_V(8); PG8_WAIT_L(0); PG8_BAR; PG8_MMA(0, 0, At, B0); PG8_MMA(0, 1, At, B1); PG8_BAR; PG8_SCHED;
	s_setprio 1
	v_mfma_f32_16x16x32_bf16 v[76:79], v[40:43], v[174:177], v[76:79]
	v_mfma_f32_16x16x32_bf16 v[72:75], v[52:55], v[174:177], v[72:75]
	v_mfma_f32_16x16x32_bf16 v[60:63], v[40:43], v[182:185], v[60:63]
	v_mfma_f32_16x16x32_bf16 v[48:51], v[52:55], v[182:185], v[48:51]
	v_mfma_f32_16x16x32_bf16 v[28:31], v[40:43], v[194:197], v[28:31]
	v_mfma_f32_16x16x32_bf16 v[24:27], v[52:55], v[194:197], v[24:27]
	v_mfma_f32_16x16x32_bf16 v[12:15], v[40:43], v[212:215], v[12:15]
	v_mfma_f32_16x16x32_bf16 v[8:11], v[52:55], v[212:215], v[8:11]
	v_mfma_f32_16x16x32_bf16 v[76:79], v[44:47], v[178:181], v[76:79]
	v_mfma_f32_16x16x32_bf16 v[72:75], v[56:59], v[178:181], v[72:75]
	v_mfma_f32_16x16x32_bf16 v[60:63], v[44:47], v[186:189], v[60:63]
	v_mfma_f32_16x16x32_bf16 v[48:51], v[56:59], v[186:189], v[48:51]
	v_mfma_f32_16x16x32_bf16 v[28:31], v[44:47], v[208:211], v[28:31]
	v_mfma_f32_16x16x32_bf16 v[24:27], v[56:59], v[208:211], v[24:27]
	v_mfma_f32_16x16x32_bf16 v[12:15], v[44:47], v[216:219], v[12:15]
	v_mfma_f32_16x16x32_bf16 v[8:11], v[56:59], v[216:219], v[8:11]
	s_setprio 0
	s_setprio 1
	v_mfma_f32_16x16x32_bf16 v[36:39], v[144:147], v[182:185], v[36:39]
	v_mfma_f32_16x16x32_bf16 v[32:35], v[166:169], v[182:185], v[32:35]
	v_mfma_f32_16x16x32_bf16 v[20:23], v[144:147], v[194:197], v[20:23]
	v_mfma_f32_16x16x32_bf16 v[16:19], v[166:169], v[194:197], v[16:19]
	v_mfma_f32_16x16x32_bf16 v[4:7], v[144:147], v[212:215], v[4:7]
	v_mfma_f32_16x16x32_bf16 v[0:3], v[166:169], v[212:215], v[0:3]
	v_mfma_f32_16x16x32_bf16 v[40:43], v[144:147], v[174:177], v[68:71]
	v_mfma_f32_16x16x32_bf16 v[44:47], v[166:169], v[174:177], v[64:67]
	v_mfma_f32_16x16x32_bf16 v[36:39], v[162:165], v[186:189], v[36:39]
	v_mfma_f32_16x16x32_bf16 v[32:35], v[170:173], v[186:189], v[32:35]
	v_mfma_f32_16x16x32_bf16 v[20:23], v[162:165], v[208:211], v[20:23]
	v_mfma_f32_16x16x32_bf16 v[16:19], v[170:173], v[208:211], v[16:19]
	v_mfma_f32_16x16x32_bf16 v[4:7], v[162:165], v[216:219], v[4:7]
	v_mfma_f32_16x16x32_bf16 v[0:3], v[170:173], v[216:219], v[0:3]
	v_mfma_f32_16x16x32_bf16 v[40:43], v[162:165], v[178:181], v[40:43]
	v_mfma_f32_16x16x32_bf16 v[44:47], v[170:173], v[178:181], v[44:47]
	s_setprio 0
	s_barrier
	s_add_i32 s49, 0, 0x18000
	s_add_i32 s50, 0, 0x1c000
	v_add_u32_e32 v68, s49, v205
	v_add_u32_e32 v170, s50, v205
	ds_read_b128 v[52:55], v68
	ds_read_b128 v[56:59], v68 offset:1024
	ds_read_b128 v[64:67], v68 offset:2048
	ds_read_b128 v[68:71], v68 offset:3072
	ds_read_b128 v[144:147], v170
	ds_read_b128 v[162:165], v170 offset:1024
	ds_read_b128 v[166:169], v170 offset:2048
	ds_read_b128 v[170:173], v170 offset:3072
	s_add_u32 s22, s22, 0x40000
	s_addc_u32 s23, s23, 0
	s_mov_b32 m0, s31
	v_lshl_add_u64 v[226:227], s[22:23], 0, v[152:153]
	ds_read_b128 v[174:177], v206 offset:32768
	ds_read_b128 v[178:181], v206 offset:33792
	ds_read_b128 v[182:185], v206 offset:34816
	ds_read_b128 v[186:189], v206 offset:35840
	ds_read_b128 v[194:197], v206 offset:36864
	ds_read_b128 v[208:211], v206 offset:37888
	ds_read_b128 v[212:215], v206 offset:38912
	ds_read_b128 v[216:219], v206 offset:39936
	global_load_lds_dwordx4 v[226:227], off
	v_lshl_add_u64 v[226:227], s[22:23], 0, v[150:151]
	s_mov_b32 m0, s34
	s_nop 0
	global_load_lds_dwordx4 v[226:227], off
	s_waitcnt vmcnt(8)
	s_waitcnt lgkmcnt(0)
	s_barrier
	s_setprio 1
	v_mfma_f32_16x16x32_bf16 v[140:143], v[52:55], v[174:177], v[140:143]
	v_mfma_f32_16x16x32_bf16 v[136:139], v[64:67], v[174:177], v[136:139]
	v_mfma_f32_16x16x32_bf16 v[124:127], v[52:55], v[182:185], v[124:127]
	v_mfma_f32_16x16x32_bf16 v[120:123], v[64:67], v[182:185], v[120:123]
	v_mfma_f32_16x16x32_bf16 v[108:111], v[52:55], v[194:197], v[108:111]
	v_mfma_f32_16x16x32_bf16 v[104:107], v[64:67], v[194:197], v[104:107]
	v_mfma_f32_16x16x32_bf16 v[92:95], v[52:55], v[212:215], v[92:95]
	v_mfma_f32_16x16x32_bf16 v[88:91], v[64:67], v[212:215], v[88:91]
	v_mfma_f32_16x16x32_bf16 v[140:143], v[56:59], v[178:181], v[140:143]
	v_mfma_f32_16x16x32_bf16 v[136:139], v[68:71], v[178:181], v[136:139]
	v_mfma_f32_16x16x32_bf16 v[124:127], v[56:59], v[186:189], v[124:127]
	v_mfma_f32_16x16x32_bf16 v[120:123], v[68:71], v[186:189], v[120:123]
	v_mfma_f32_16x16x32_bf16 v[108:111], v[56:59], v[208:211], v[108:111]
	v_mfma_f32_16x16x32_bf16 v[104:107], v[68:71], v[208:211], v[104:107]
	v_mfma_f32_16x16x32_bf16 v[92:95], v[56:59], v[216:219], v[92:95]
	v_mfma_f32_16x16x32_bf16 v[88:91], v[68:71], v[216:219], v[88:91]
	s_setprio 0
	s_setprio 1
	v_mfma_f32_16x16x32_bf16 v[132:135], v[144:147], v[174:177], v[132:135]
	v_mfma_f32_16x16x32_bf16 v[128:131], v[166:169], v[174:177], v[128:131]
	v_mfma_f32_16x16x32_bf16 v[116:119], v[144:147], v[182:185], v[116:119]
	v_mfma_f32_16x16x32_bf16 v[112:115], v[166:169], v[182:185], v[112:115]
	v_mfma_f32_16x16x32_bf16 v[100:103], v[144:147], v[194:197], v[100:103]
	v_mfma_f32_16x16x32_bf16 v[96:99], v[166:169], v[194:197], v[96:99]
	v_mfma_f32_16x16x32_bf16 v[84:87], v[144:147], v[212:215], v[84:87]
	v_mfma_f32_16x16x32_bf16 v[80:83], v[166:169], v[212:215], v[80:83]
	v_mfma_f32_16x16x32_bf16 v[132:135], v[162:165], v[178:181], v[132:135]
	v_mfma_f32_16x16x32_bf16 v[128:131], v[170:173], v[178:181], v[128:131]
	v_mfma_f32_16x16x32_bf16 v[116:119], v[162:165], v[186:189], v[116:119]
	v_mfma_f32_16x16x32_bf16 v[112:115], v[170:173], v[186:189], v[112:115]
	v_mfma_f32_16x16x32_bf16 v[100:103], v[162:165], v[208:211], v[100:103]
	v_mfma_f32_16x16x32_bf16 v[96:99], v[170:173], v[208:211], v[96:99]
	v_mfma_f32_16x16x32_bf16 v[84:87], v[162:165], v[216:219], v[84:87]
	v_mfma_f32_16x16x32_bf16 v[80:83], v[170:173], v[216:219], v[80:83]
	s_setprio 0
	s_barrier
; #define PG8_STAGE(bufoff, gbase, voff) do { _Pragma("unroll") for (int _i = 0; _i < 2; ++_i) \
;         __builtin_amdgcn_global_load_lds((const unsigned*)((const char*)(gbase) + (voff)[_i]), (PG8_LAS unsigned*)(lds + (bufoff) + ldsw + _i * 8192), 16, 0, 0); } while (0)
; #define PG8_LDA(dst, b, h) do { _Pragma("unroll") for (int m = 0; m < 4; ++m) _Pragma("unroll") for (int k = 0; k < 2; ++k) dst[m][k] = *(const PG8_LAS bf16x8*)(lds + PG8_SA(b, h) + aoff + m * 2048 + k * 1024); } while (0)
; #define PG8_MMA(ai, bj, At, Bt) do { __builtin_amdgcn_s_setprio(1); _Pragma("unroll") for (int m = 0; m < 4; ++m) _Pragma("unroll") for (int n = 0; n < 2; ++n) _Pragma("unroll") for (int k = 0; k < 2; ++k) \
;         acc[ai][bj][m][n] = __builtin_amdgcn_mfma_f32_16x16x32_bf16(Bt[n][k], At[m][k], acc[ai][bj][m][n], 0, 0, 0); __builtin_amdgcn_s_setprio(0); } while (0)
; #define PG8_WAIT_V(n) asm volatile("s_waitcnt vmcnt(" #n ")" ::: "memory")
; #define PG8_WAIT_L(n) asm volatile("s_waitcnt lgkmcnt(" #n ")" ::: "memory")
; #define PG8_BAR __builtin_amdgcn_s_barrier()
; #define PG8_SCHED __builtin_amdgcn_sched_barrier(0)
; template <class Epi, class Sched, bool ALIGN_EPI = false, bool SP2 = false>
; __device__ __forceinline__ void gemm_phase(PG8_LAS unsigned char* lds, const Gemm g, const Sched& S, const Epi& E) {
;     ...
;         for (int t = 0; t < nt; t += 2) {
;             const bool last = (t == nt - 2);
;             const char* a1 = cA + (size_t)(t + 1) * kstep;
;             const char* a2 = last ? nA : cA + (size_t)(t + 2) * kstep; const char* b2 = last ? nB : cB + (size_t)(t + 2) * kstep;
;     ...
;             PG8_LDA(At, 1, 1); PG8_STAGE(PG8_SB(1, 0), b3, voffB); PG8_STAGE(PG8_SB(1, 1), b3 + hstep, voffB); PG8_STAGE(PG8_SA(1, 0), a3, voffA);
;             PG8_WAIT_V(8); PG8_WAIT_L(0); PG8_BAR; PG8_MMA(1, 0, At, B0); PG8_MMA(1, 1, At, B1); PG8_BAR; PG8_SCHED;
	s_add_i32 s22, s49, s28
	v_lshl_add_u64 v[158:159], v[158:159], 0, s[38:39]
	s_mov_b32 m0, s22
	ds_read_b128 v[174:177], v206 offset:49152
	ds_read_b128 v[178:181], v206 offset:50176
	ds_read_b128 v[182:185], v206 offset:51200
	ds_read_b128 v[186:189], v206 offset:52224
	ds_read_b128 v[194:197], v206 offset:53248
	ds_read_b128 v[208:211], v206 offset:54272
	ds_read_b128 v[212:215], v206 offset:55296
	ds_read_b128 v[216:219], v206 offset:56320
	global_load_lds_dwordx4 v[158:159], off
	s_add_i32 m0, s22, 0x2000
	s_add_u32 s6, s6, 0x40080
	v_lshl_add_u64 v[158:159], v[220:221], 0, s[38:39]
	s_addc_u32 s7, s7, 0
	s_add_i32 s22, s50, s28
	global_load_lds_dwordx4 v[158:159], off
	v_lshl_add_u64 v[158:159], s[6:7], 0, v[160:161]
	s_mov_b32 m0, s22
	s_nop 0
	global_load_lds_dwordx4 v[158:159], off
	v_lshl_add_u64 v[158:159], s[6:7], 0, v[148:149]
	s_add_i32 m0, s22, 0x2000
	s_nop 0
	global_load_lds_dwordx4 v[158:159], off
	v_lshl_add_u64 v[158:159], v[222:223], 0, s[38:39]
	s_mov_b32 m0, s41
	s_nop 0
	global_load_lds_dwordx4 v[158:159], off
	v_lshl_add_u64 v[158:159], v[224:225], 0, s[38:39]
	s_mov_b32 m0, s42
	s_nop 0
	global_load_lds_dwordx4 v[158:159], off
	s_waitcnt vmcnt(8)
	s_waitcnt lgkmcnt(0)
	s_barrier
	s_setprio 1
	v_mfma_f32_16x16x32_bf16 v[76:79], v[52:55], v[174:177], v[76:79]
	v_mfma_f32_16x16x32_bf16 v[72:75], v[64:67], v[174:177], v[72:75]
	v_mfma_f32_16x16x32_bf16 v[60:63], v[52:55], v[182:185], v[60:63]
	v_mfma_f32_16x16x32_bf16 v[48:51], v[64:67], v[182:185], v[48:51]
	v_mfma_f32_16x16x32_bf16 v[28:31], v[52:55], v[194:197], v[28:31]
	v_mfma_f32_16x16x32_bf16 v[24:27], v[64:67], v[194:197], v[24:27]
	v_mfma_f32_16x16x32_bf16 v[12:15], v[52:55], v[212:215], v[12:15]
	v_mfma_f32_16x16x32_bf16 v[8:11], v[64:67], v[212:215], v[8:11]
	v_mfma_f32_16x16x32_bf16 v[76:79], v[56:59], v[178:181], v[76:79]
	v_mfma_f32_16x16x32_bf16 v[72:75], v[68:71], v[178:181], v[72:75]
	v_mfma_f32_16x16x32_bf16 v[60:63], v[56:59], v[186:189], v[60:63]
	v_mfma_f32_16x16x32_bf16 v[48:51], v[68:71], v[186:189], v[48:51]
	v_mfma_f32_16x16x32_bf16 v[28:31], v[56:59], v[208:211], v[28:31]
	v_mfma_f32_16x16x32_bf16 v[24:27], v[68:71], v[208:211], v[24:27]
	v_mfma_f32_16x16x32_bf16 v[12:15], v[56:59], v[216:219], v[12:15]
	v_mfma_f32_16x16x32_bf16 v[8:11], v[68:71], v[216:219], v[8:11]
	s_setprio 0
	s_setprio 1
	v_mfma_f32_16x16x32_bf16 v[40:43], v[144:147], v[174:177], v[40:43]
	v_mfma_f32_16x16x32_bf16 v[68:71], v[162:165], v[178:181], v[40:43]
	v_mfma_f32_16x16x32_bf16 v[40:43], v[166:169], v[174:177], v[44:47]
	v_mfma_f32_16x16x32_bf16 v[36:39], v[144:147], v[182:185], v[36:39]
	v_mfma_f32_16x16x32_bf16 v[32:35], v[166:169], v[182:185], v[32:35]
	v_mfma_f32_16x16x32_bf16 v[20:23], v[144:147], v[194:197], v[20:23]
	v_mfma_f32_16x16x32_bf16 v[16:19], v[166:169], v[194:197], v[16:19]
	v_mfma_f32_16x16x32_bf16 v[4:7], v[144:147], v[212:215], v[4:7]
	v_mfma_f32_16x16x32_bf16 v[0:3], v[166:169], v[212:215], v[0:3]
	v_mfma_f32_16x16x32_bf16 v[64:67], v[170:173], v[178:181], v[40:43]
	v_mfma_f32_16x16x32_bf16 v[36:39], v[162:165], v[186:189], v[36:39]
	v_mfma_f32_16x16x32_bf16 v[32:35], v[170:173], v[186:189], v[32:35]
	v_mfma_f32_16x16x32_bf16 v[20:23], v[162:165], v[208:211], v[20:23]
	v_mfma_f32_16x16x32_bf16 v[16:19], v[170:173], v[208:211], v[16:19]
	v_mfma_f32_16x16x32_bf16 v[4:7], v[162:165], v[216:219], v[4:7]
	v_mfma_f32_16x16x32_bf16 v[0:3], v[170:173], v[216:219], v[0:3]
	s_setprio 0
	s_barrier
	s_add_i32 s48, s48, 2
	s_add_u32 s4, s4, 0x100
	s_addc_u32 s5, s5, 0
	s_add_u32 s46, s46, 0x100
	s_addc_u32 s47, s47, 0
	s_cmp_gt_u32 s48, 13
	s_cbranch_scc0 .LBB0_945
	s_and_b64 vcc, exec, s[12:13]
	s_cbranch_vccz .LBB0_948
	s_barrier

; #define PG8_STAGE(bufoff, gbase, voff) do { _Pragma("unroll") for (int _i = 0; _i < 2; ++_i) \
;         __builtin_amdgcn_global_load_lds((const unsigned*)((const char*)(gbase) + (voff)[_i]), (PG8_LAS unsigned*)(lds + (bufoff) + ldsw + _i * 8192), 16, 0, 0); } while (0)
; #define PG8_LDA(dst, b, h) do { _Pragma("unroll") for (int m = 0; m < 4; ++m) _Pragma("unroll") for (int k = 0; k < 2; ++k) dst[m][k] = *(const PG8_LAS bf16x8*)(lds + PG8_SA(b, h) + aoff + m * 2048 + k * 1024); } while (0)
; #define PG8_LDB(dst, b, h) do { _Pragma("unroll") for (int n = 0; n < 2; ++n) _Pragma("unroll") for (int k = 0; k < 2; ++k) dst[n][k] = *(const PG8_LAS bf16x8*)(lds + PG8_SB(b, h) + boff + n * 2048 + k * 1024); } while (0)
; #define PG8_MMA(ai, bj, At, Bt) do { __builtin_amdgcn_s_setprio(1); _Pragma("unroll") for (int m = 0; m < 4; ++m) _Pragma("unroll") for (int n = 0; n < 2; ++n) _Pragma("unroll") for (int k = 0; k < 2; ++k) \
;         acc[ai][bj][m][n] = __builtin_amdgcn_mfma_f32_16x16x32_bf16(Bt[n][k], At[m][k], acc[ai][bj][m][n], 0, 0, 0); __builtin_amdgcn_s_setprio(0); } while (0)
; #define PG8_WAIT_V(n) asm volatile("s_waitcnt vmcnt(" #n ")" ::: "memory")
; #define PG8_WAIT_L(n) asm volatile("s_waitcnt lgkmcnt(" #n ")" ::: "memory")
; template <class Epi, class Sched, bool ALIGN_EPI = false, bool SP2 = false>
; __device__ __forceinline__ void gemm_phase(PG8_LAS unsigned char* lds, const Gemm g, const Sched& S, const Epi& E) {
;     ...
;             const bool last = (t == nt - 2);
;             const char* a1 = cA + (size_t)(t + 1) * kstep;
;             const char* a2 = last ? nA : cA + (size_t)(t + 2) * kstep; const char* b2 = last ? nB : cB + (size_t)(t + 2) * kstep;
;             const char* a3 = a2 + kstep; const char* b3 = b2 + kstep;
;             if (last && has_next) S.a_ready(nxt);
;             if constexpr (SP2) {
;             PG8_LDB(B0, 0, 0); PG8_LDB(B1, 0, 1); PG8_SCHED; PG8_LDA(At, 0, 0); PG8_STAGE(PG8_SA(1, 1), a1 + hstep, voffA);
;             PG8_WAIT_V(8); PG8_WAIT_L(0); PG8_BAR; PG8_MMA(0, 0, At, B0); PG8_MMA(0, 1, At, B1); PG8_BAR; PG8_SCHED;
;             PG8_LDA(At, 0, 1); PG8_STAGE(PG8_SB(0, 0), b2, voffB); PG8_STAGE(PG8_SB(0, 1), b2 + hstep, voffB); PG8_STAGE(PG8_SA(0, 0), a2, voffA);
;             PG8_WAIT_V(8); PG8_WAIT_L(0); PG8_BAR; PG8_MMA(1, 0, At, B0); PG8_MMA(1, 1, At, B1); PG8_BAR; PG8_SCHED;
.LBB0_1135:
	s_add_u32 s18, s4, 0xfffc0080
	s_addc_u32 s19, s5, -1
	s_add_i32 s45, 0, 0x10000
	s_cmp_eq_u32 s44, 12
	s_cselect_b32 s21, s11, s19
	s_cselect_b32 s20, s40, s18
	s_cselect_b32 s19, s13, s43
	s_cselect_b32 s18, s41, s42
	s_add_i32 s48, 0, 0x14000
	v_add_u32_e32 v68, s45, v169
	v_add_u32_e32 v158, s48, v169
	ds_read_b128 v[56:59], v68
	ds_read_b128 v[60:63], v68 offset:1024
	ds_read_b128 v[64:67], v68 offset:2048
	ds_read_b128 v[68:71], v68 offset:3072
	ds_read_b128 v[154:157], v158
	ds_read_b128 v[162:165], v158 offset:1024
	ds_read_b128 v[172:175], v158 offset:2048
	ds_read_b128 v[176:179], v158 offset:3072
	v_lshl_add_u64 v[158:159], s[4:5], 0, v[150:151]
	s_add_i32 m0, s27, 0xc000
	ds_read_b128 v[180:183], v171
	ds_read_b128 v[184:187], v171 offset:1024
	ds_read_b128 v[194:197], v171 offset:2048
	ds_read_b128 v[206:209], v171 offset:3072
	ds_read_b128 v[210:213], v171 offset:4096
	ds_read_b128 v[214:217], v171 offset:5120
	ds_read_b128 v[218:221], v171 offset:6144
	ds_read_b128 v[222:225], v171 offset:7168
	global_load_lds_dwordx4 v[158:159], off
	v_lshl_add_u64 v[158:159], s[4:5], 0, v[152:153]
	s_add_i32 m0, s27, 0xe000
	s_nop 0
	global_load_lds_dwordx4 v[158:159], off
	s_waitcnt vmcnt(8)
	s_waitcnt lgkmcnt(0)
	s_barrier
	s_setprio 1
	v_mfma_f32_16x16x32_bf16 v[140:143], v[56:59], v[180:183], v[140:143]
	v_mfma_f32_16x16x32_bf16 v[136:139], v[64:67], v[180:183], v[136:139]
	v_mfma_f32_16x16x32_bf16 v[124:127], v[56:59], v[194:197], v[124:127]
	v_mfma_f32_16x16x32_bf16 v[120:123], v[64:67], v[194:197], v[120:123]
	v_mfma_f32_16x16x32_bf16 v[108:111], v[56:59], v[210:213], v[108:111]
	v_mfma_f32_16x16x32_bf16 v[104:107], v[64:67], v[210:213], v[104:107]
	v_mfma_f32_16x16x32_bf16 v[92:95], v[56:59], v[218:221], v[92:95]
	v_mfma_f32_16x16x32_bf16 v[88:91], v[64:67], v[218:221], v[88:91]
	v_mfma_f32_16x16x32_bf16 v[140:143], v[60:63], v[184:187], v[140:143]
	v_mfma_f32_16x16x32_bf16 v[136:139], v[68:71], v[184:187], v[136:139]
	v_mfma_f32_16x16x32_bf16 v[124:127], v[60:63], v[206:209], v[124:127]
	v_mfma_f32_16x16x32_bf16 v[120:123], v[68:71], v[206:209], v[120:123]
	v_mfma_f32_16x16x32_bf16 v[108:111], v[60:63], v[214:217], v[108:111]
	v_mfma_f32_16x16x32_bf16 v[104:107], v[68:71], v[214:217], v[104:107]
	v_mfma_f32_16x16x32_bf16 v[92:95], v[60:63], v[222:225], v[92:95]
	v_mfma_f32_16x16x32_bf16 v[88:91], v[68:71], v[222:225], v[88:91]
	s_setprio 0
	s_setprio 1
	v_mfma_f32_16x16x32_bf16 v[132:135], v[154:157], v[180:183], v[132:135]
	v_mfma_f32_16x16x32_bf16 v[128:131], v[172:175], v[180:183], v[128:131]
	v_mfma_f32_16x16x32_bf16 v[116:119], v[154:157], v[194:197], v[116:119]
	v_mfma_f32_16x16x32_bf16 v[112:115], v[172:175], v[194:197], v[112:115]
	v_mfma_f32_16x16x32_bf16 v[100:103], v[154:157], v[210:213], v[100:103]
	v_mfma_f32_16x16x32_bf16 v[96:99], v[172:175], v[210:213], v[96:99]
	v_mfma_f32_16x16x32_bf16 v[84:87], v[154:157], v[218:221], v[84:87]
	v_mfma_f32_16x16x32_bf16 v[80:83], v[172:175], v[218:221], v[80:83]
	v_mfma_f32_16x16x32_bf16 v[132:135], v[162:165], v[184:187], v[132:135]
	v_mfma_f32_16x16x32_bf16 v[128:131], v[176:179], v[184:187], v[128:131]
	v_mfma_f32_16x16x32_bf16 v[116:119], v[162:165], v[206:209], v[116:119]
	v_mfma_f32_16x16x32_bf16 v[112:115], v[176:179], v[206:209], v[112:115]
	v_mfma_f32_16x16x32_bf16 v[100:103], v[162:165], v[214:217], v[100:103]
	v_mfma_f32_16x16x32_bf16 v[96:99], v[176:179], v[214:217], v[96:99]
	v_mfma_f32_16x16x32_bf16 v[84:87], v[162:165], v[222:225], v[84:87]
	v_mfma_f32_16x16x32_bf16 v[80:83], v[176:179], v[222:225], v[80:83]
	s_setprio 0
	s_barrier
	s_add_i32 s45, s45, s26
	v_lshl_add_u64 v[158:159], s[18:19], 0, v[160:161]
	s_mov_b32 m0, s45
	ds_read_b128 v[180:183], v171 offset:16384
	ds_read_b128 v[184:187], v171 offset:17408
	ds_read_b128 v[194:197], v171 offset:18432
	ds_read_b128 v[206:209], v171 offset:19456
	ds_read_b128 v[210:213], v171 offset:20480
	ds_read_b128 v[214:217], v171 offset:21504
	ds_read_b128 v[218:221], v171 offset:22528
	ds_read_b128 v[222:225], v171 offset:23552
	global_load_lds_dwordx4 v[158:159], off
	s_add_i32 m0, s45, 0x2000
	s_add_u32 s46, s18, 0x40000
	v_lshl_add_u64 v[166:167], s[18:19], 0, v[144:145]
	s_addc_u32 s47, s19, 0
	s_add_i32 s45, s48, s26
	global_load_lds_dwordx4 v[166:167], off
	v_lshl_add_u64 v[188:189], s[46:47], 0, v[160:161]
	s_mov_b32 m0, s45
	v_lshl_add_u64 v[226:227], s[20:21], 0, v[146:147]
	global_load_lds_dwordx4 v[188:189], off
	v_lshl_add_u64 v[188:189], s[46:47], 0, v[144:145]
	s_add_i32 m0, s45, 0x2000
	s_nop 0
	global_load_lds_dwordx4 v[188:189], off
	v_lshl_add_u64 v[188:189], s[20:21], 0, v[148:149]
	s_mov_b32 m0, s27
	s_nop 0
	global_load_lds_dwordx4 v[188:189], off
	s_mov_b32 m0, s28
	s_nop 0
	global_load_lds_dwordx4 v[226:227], off
	s_waitcnt vmcnt(8)
	s_waitcnt lgkmcnt(0)
	s_barrier
; #define PG8_STAGE(bufoff, gbase, voff) do { _Pragma("unroll") for (int _i = 0; _i < 2; ++_i) \
;         __builtin_amdgcn_global_load_lds((const unsigned*)((const char*)(gbase) + (voff)[_i]), (PG8_LAS unsigned*)(lds + (bufoff) + ldsw + _i * 8192), 16, 0, 0); } while (0)
; #define PG8_LDA(dst, b, h) do { _Pragma("unroll") for (int m = 0; m < 4; ++m) _Pragma("unroll") for (int k = 0; k < 2; ++k) dst[m][k] = *(const PG8_LAS bf16x8*)(lds + PG8_SA(b, h) + aoff + m * 2048 + k * 1024); } while (0)
; #define PG8_LDB(dst, b, h) do { _Pragma("unroll") for (int n = 0; n < 2; ++n) _Pragma("unroll") for (int k = 0; k < 2; ++k) dst[n][k] = *(const PG8_LAS bf16x8*)(lds + PG8_SB(b, h) + boff + n * 2048 + k * 1024); } while (0)
; #define PG8_MMA(ai, bj, At, Bt) do { __builtin_amdgcn_s_setprio(1); _Pragma("unroll") for (int m = 0; m < 4; ++m) _Pragma("unroll") for (int n = 0; n < 2; ++n) _Pragma("unroll") for (int k = 0; k < 2; ++k) \
;         acc[ai][bj][m][n] = __builtin_amdgcn_mfma_f32_16x16x32_bf16(Bt[n][k], At[m][k], acc[ai][bj][m][n], 0, 0, 0); __builtin_amdgcn_s_setprio(0); } while (0)
; #define PG8_WAIT_V(n) asm volatile("s_waitcnt vmcnt(" #n ")" ::: "memory")
; #define PG8_WAIT_L(n) asm volatile("s_waitcnt lgkmcnt(" #n ")" ::: "memory")
; #define PG8_BAR __builtin_amdgcn_s_barrier()
; #define PG8_SCHED __builtin_amdgcn_sched_barrier(0)
; template <class Epi, class Sched, bool ALIGN_EPI = false, bool SP2 = false>
; __device__ __forceinline__ void gemm_phase(PG8_LAS unsigned char* lds, const Gemm g, const Sched& S, const Epi& E) {
;     ...
;             PG8_WAIT_V(8); PG8_WAIT_L(0); PG8_BAR; PG8_MMA(1, 0, At, B0); PG8_MMA(1, 1, At, B1); PG8_BAR; PG8_SCHED;
;             PG8_LDB(B0, 1, 0); PG8_LDB(B1, 1, 1); PG8_SCHED; PG8_LDA(At, 1, 0); PG8_STAGE(PG8_SA(0, 1), a2 + hstep, voffA);
;             PG8_WAIT_V(8); PG8_WAIT_L(0); PG8_BAR; PG8_MMA(0, 0, At, B0); PG8_MMA(0, 1, At, B1); PG8_BAR; PG8_SCHED;
	s_setprio 1
	v_mfma_f32_16x16x32_bf16 v[76:79], v[56:59], v[180:183], v[76:79]
	v_mfma_f32_16x16x32_bf16 v[72:75], v[64:67], v[180:183], v[72:75]
	v_mfma_f32_16x16x32_bf16 v[44:47], v[56:59], v[194:197], v[44:47]
	v_mfma_f32_16x16x32_bf16 v[40:43], v[64:67], v[194:197], v[40:43]
	v_mfma_f32_16x16x32_bf16 v[28:31], v[56:59], v[210:213], v[28:31]
	v_mfma_f32_16x16x32_bf16 v[24:27], v[64:67], v[210:213], v[24:27]
	v_mfma_f32_16x16x32_bf16 v[12:15], v[56:59], v[218:221], v[12:15]
	v_mfma_f32_16x16x32_bf16 v[8:11], v[64:67], v[218:221], v[8:11]
	v_mfma_f32_16x16x32_bf16 v[76:79], v[60:63], v[184:187], v[76:79]
	v_mfma_f32_16x16x32_bf16 v[72:75], v[68:71], v[184:187], v[72:75]
	v_mfma_f32_16x16x32_bf16 v[44:47], v[60:63], v[206:209], v[44:47]
	v_mfma_f32_16x16x32_bf16 v[40:43], v[68:71], v[206:209], v[40:43]
	v_mfma_f32_16x16x32_bf16 v[28:31], v[60:63], v[214:217], v[28:31]
	v_mfma_f32_16x16x32_bf16 v[24:27], v[68:71], v[214:217], v[24:27]
	v_mfma_f32_16x16x32_bf16 v[12:15], v[60:63], v[222:225], v[12:15]
	v_mfma_f32_16x16x32_bf16 v[8:11], v[68:71], v[222:225], v[8:11]
	s_setprio 0
	s_setprio 1
	v_mfma_f32_16x16x32_bf16 v[52:55], v[154:157], v[180:183], v[52:55]
	v_mfma_f32_16x16x32_bf16 v[48:51], v[172:175], v[180:183], v[48:51]
	v_mfma_f32_16x16x32_bf16 v[36:39], v[154:157], v[194:197], v[36:39]
	v_mfma_f32_16x16x32_bf16 v[32:35], v[172:175], v[194:197], v[32:35]
	v_mfma_f32_16x16x32_bf16 v[20:23], v[154:157], v[210:213], v[20:23]
	v_mfma_f32_16x16x32_bf16 v[16:19], v[172:175], v[210:213], v[16:19]
	v_mfma_f32_16x16x32_bf16 v[4:7], v[154:157], v[218:221], v[4:7]
	v_mfma_f32_16x16x32_bf16 v[0:3], v[172:175], v[218:221], v[0:3]
	v_mfma_f32_16x16x32_bf16 v[52:55], v[162:165], v[184:187], v[52:55]
	v_mfma_f32_16x16x32_bf16 v[48:51], v[176:179], v[184:187], v[48:51]
	v_mfma_f32_16x16x32_bf16 v[36:39], v[162:165], v[206:209], v[36:39]
	v_mfma_f32_16x16x32_bf16 v[32:35], v[176:179], v[206:209], v[32:35]
	v_mfma_f32_16x16x32_bf16 v[20:23], v[162:165], v[214:217], v[20:23]
	v_mfma_f32_16x16x32_bf16 v[16:19], v[176:179], v[214:217], v[16:19]
	v_mfma_f32_16x16x32_bf16 v[4:7], v[162:165], v[222:225], v[4:7]
	v_mfma_f32_16x16x32_bf16 v[0:3], v[176:179], v[222:225], v[0:3]
	s_setprio 0
	s_barrier
	s_add_i32 s45, 0, 0x18000
	s_add_i32 s46, 0, 0x1c000
	v_add_u32_e32 v68, s45, v169
	v_add_u32_e32 v176, s46, v169
	ds_read_b128 v[56:59], v68
	ds_read_b128 v[60:63], v68 offset:1024
	ds_read_b128 v[64:67], v68 offset:2048
	ds_read_b128 v[68:71], v68 offset:3072
	ds_read_b128 v[154:157], v176
	ds_read_b128 v[162:165], v176 offset:1024
	ds_read_b128 v[172:175], v176 offset:2048
	ds_read_b128 v[176:179], v176 offset:3072
	s_add_u32 s20, s20, 0x40000
	s_addc_u32 s21, s21, 0
	s_mov_b32 m0, s29
	v_lshl_add_u64 v[228:229], s[20:21], 0, v[148:149]
	ds_read_b128 v[180:183], v171 offset:32768
	ds_read_b128 v[184:187], v171 offset:33792
	ds_read_b128 v[194:197], v171 offset:34816
	ds_read_b128 v[206:209], v171 offset:35840
	ds_read_b128 v[210:213], v171 offset:36864
	ds_read_b128 v[214:217], v171 offset:37888
	ds_read_b128 v[218:221], v171 offset:38912
	ds_read_b128 v[222:225], v171 offset:39936
	global_load_lds_dwordx4 v[228:229], off
	v_lshl_add_u64 v[228:229], s[20:21], 0, v[146:147]
	s_mov_b32 m0, s30
	s_nop 0
	global_load_lds_dwordx4 v[228:229], off
	s_waitcnt vmcnt(8)
	s_waitcnt lgkmcnt(0)
	s_barrier
	s_setprio 1
	v_mfma_f32_16x16x32_bf16 v[140:143], v[56:59], v[180:183], v[140:143]
	v_mfma_f32_16x16x32_bf16 v[136:139], v[64:67], v[180:183], v[136:139]
	v_mfma_f32_16x16x32_bf16 v[124:127], v[56:59], v[194:197], v[124:127]
	v_mfma_f32_16x16x32_bf16 v[120:123], v[64:67], v[194:197], v[120:123]
	v_mfma_f32_16x16x32_bf16 v[108:111], v[56:59], v[210:213], v[108:111]
	v_mfma_f32_16x16x32_bf16 v[104:107], v[64:67], v[210:213], v[104:107]
	v_mfma_f32_16x16x32_bf16 v[92:95], v[56:59], v[218:221], v[92:95]
	v_mfma_f32_16x16x32_bf16 v[88:91], v[64:67], v[218:221], v[88:91]
	v_mfma_f32_16x16x32_bf16 v[140:143], v[60:63], v[184:187], v[140:143]
	v_mfma_f32_16x16x32_bf16 v[136:139], v[68:71], v[184:187], v[136:139]
	v_mfma_f32_16x16x32_bf16 v[124:127], v[60:63], v[206:209], v[124:127]
	v_mfma_f32_16x16x32_bf16 v[120:123], v[68:71], v[206:209], v[120:123]
	v_mfma_f32_16x16x32_bf16 v[108:111], v[60:63], v[214:217], v[108:111]
	v_mfma_f32_16x16x32_bf16 v[104:107], v[68:71], v[214:217], v[104:107]
	v_mfma_f32_16x16x32_bf16 v[92:95], v[60:63], v[222:225], v[92:95]
	v_mfma_f32_16x16x32_bf16 v[88:91], v[68:71], v[222:225], v[88:91]
	s_setprio 0
	s_setprio 1
	v_mfma_f32_16x16x32_bf16 v[132:135], v[154:157], v[180:183], v[132:135]
	v_mfma_f32_16x16x32_bf16 v[128:131], v[172:175], v[180:183], v[128:131]
	v_mfma_f32_16x16x32_bf16 v[116:119], v[154:157], v[194:197], v[116:119]
	v_mfma_f32_16x16x32_bf16 v[112:115], v[172:175], v[194:197], v[112:115]
	v_mfma_f32_16x16x32_bf16 v[100:103], v[154:157], v[210:213], v[100:103]
	v_mfma_f32_16x16x32_bf16 v[96:99], v[172:175], v[210:213], v[96:99]
	v_mfma_f32_16x16x32_bf16 v[84:87], v[154:157], v[218:221], v[84:87]
	v_mfma_f32_16x16x32_bf16 v[80:83], v[172:175], v[218:221], v[80:83]
	v_mfma_f32_16x16x32_bf16 v[132:135], v[162:165], v[184:187], v[132:135]
	v_mfma_f32_16x16x32_bf16 v[128:131], v[176:179], v[184:187], v[128:131]
	v_mfma_f32_16x16x32_bf16 v[116:119], v[162:165], v[206:209], v[116:119]
	v_mfma_f32_16x16x32_bf16 v[112:115], v[176:179], v[206:209], v[112:115]
	v_mfma_f32_16x16x32_bf16 v[100:103], v[162:165], v[214:217], v[100:103]
	v_mfma_f32_16x16x32_bf16 v[96:99], v[176:179], v[214:217], v[96:99]
	v_mfma_f32_16x16x32_bf16 v[84:87], v[162:165], v[222:225], v[84:87]
	v_mfma_f32_16x16x32_bf16 v[80:83], v[176:179], v[222:225], v[80:83]
	s_setprio 0
	s_barrier
; #define PG8_STAGE(bufoff, gbase, voff) do { _Pragma("unroll") for (int _i = 0; _i < 2; ++_i) \
;         __builtin_amdgcn_global_load_lds((const unsigned*)((const char*)(gbase) + (voff)[_i]), (PG8_LAS unsigned*)(lds + (bufoff) + ldsw + _i * 8192), 16, 0, 0); } while (0)
; #define PG8_LDA(dst, b, h) do { _Pragma("unroll") for (int m = 0; m < 4; ++m) _Pragma("unroll") for (int k = 0; k < 2; ++k) dst[m][k] = *(const PG8_LAS bf16x8*)(lds + PG8_SA(b, h) + aoff + m * 2048 + k * 1024); } while (0)
; #define PG8_MMA(ai, bj, At, Bt) do { __builtin_amdgcn_s_setprio(1); _Pragma("unroll") for (int m = 0; m < 4; ++m) _Pragma("unroll") for (int n = 0; n < 2; ++n) _Pragma("unroll") for (int k = 0; k < 2; ++k) \
;         acc[ai][bj][m][n] = __builtin_amdgcn_mfma_f32_16x16x32_bf16(Bt[n][k], At[m][k], acc[ai][bj][m][n], 0, 0, 0); __builtin_amdgcn_s_setprio(0); } while (0)
; #define PG8_WAIT_V(n) asm volatile("s_waitcnt vmcnt(" #n ")" ::: "memory")
; #define PG8_WAIT_L(n) asm volatile("s_waitcnt lgkmcnt(" #n ")" ::: "memory")
; #define PG8_BAR __builtin_amdgcn_s_barrier()
; #define PG8_SCHED __builtin_amdgcn_sched_barrier(0)
; template <class Epi, class Sched, bool ALIGN_EPI = false, bool SP2 = false>
; __device__ __forceinline__ void gemm_phase(PG8_LAS unsigned char* lds, const Gemm g, const Sched& S, const Epi& E) {
;     ...
;         for (int t = 0; t < nt; t += 2) {
;             const bool last = (t == nt - 2);
;             const char* a1 = cA + (size_t)(t + 1) * kstep;
;             const char* a2 = last ? nA : cA + (size_t)(t + 2) * kstep; const char* b2 = last ? nB : cB + (size_t)(t + 2) * kstep;
;     ...
;             PG8_LDA(At, 1, 1); PG8_STAGE(PG8_SB(1, 0), b3, voffB); PG8_STAGE(PG8_SB(1, 1), b3 + hstep, voffB); PG8_STAGE(PG8_SA(1, 0), a3, voffA);
;             PG8_WAIT_V(8); PG8_WAIT_L(0); PG8_BAR; PG8_MMA(1, 0, At, B0); PG8_MMA(1, 1, At, B1); PG8_BAR; PG8_SCHED;
	s_add_i32 s20, s45, s26
	v_lshl_add_u64 v[158:159], v[158:159], 0, s[38:39]
	s_mov_b32 m0, s20
	ds_read_b128 v[180:183], v171 offset:49152
	ds_read_b128 v[184:187], v171 offset:50176
	ds_read_b128 v[194:197], v171 offset:51200
	ds_read_b128 v[206:209], v171 offset:52224
	ds_read_b128 v[210:213], v171 offset:53248
	ds_read_b128 v[214:217], v171 offset:54272
	ds_read_b128 v[218:221], v171 offset:55296
	ds_read_b128 v[222:225], v171 offset:56320
	global_load_lds_dwordx4 v[158:159], off
	s_add_i32 m0, s20, 0x2000
	s_add_u32 s18, s18, 0x40080
	v_lshl_add_u64 v[158:159], v[166:167], 0, s[38:39]
	s_addc_u32 s19, s19, 0
	s_add_i32 s20, s46, s26
	global_load_lds_dwordx4 v[158:159], off
	v_lshl_add_u64 v[158:159], s[18:19], 0, v[160:161]
	s_mov_b32 m0, s20
	s_nop 0
	global_load_lds_dwordx4 v[158:159], off
	v_lshl_add_u64 v[158:159], s[18:19], 0, v[144:145]
	s_add_i32 m0, s20, 0x2000
	s_nop 0
	global_load_lds_dwordx4 v[158:159], off
	v_lshl_add_u64 v[158:159], v[188:189], 0, s[38:39]
	s_mov_b32 m0, s35
	s_nop 0
	global_load_lds_dwordx4 v[158:159], off
	v_lshl_add_u64 v[158:159], v[226:227], 0, s[38:39]
	s_mov_b32 m0, s36
	s_nop 0
	global_load_lds_dwordx4 v[158:159], off
	s_waitcnt vmcnt(8)
	s_waitcnt lgkmcnt(0)
	s_barrier
	s_setprio 1
	v_mfma_f32_16x16x32_bf16 v[76:79], v[56:59], v[180:183], v[76:79]
	v_mfma_f32_16x16x32_bf16 v[72:75], v[64:67], v[180:183], v[72:75]
	v_mfma_f32_16x16x32_bf16 v[44:47], v[56:59], v[194:197], v[44:47]
	v_mfma_f32_16x16x32_bf16 v[40:43], v[64:67], v[194:197], v[40:43]
	v_mfma_f32_16x16x32_bf16 v[28:31], v[56:59], v[210:213], v[28:31]
	v_mfma_f32_16x16x32_bf16 v[24:27], v[64:67], v[210:213], v[24:27]
	v_mfma_f32_16x16x32_bf16 v[12:15], v[56:59], v[218:221], v[12:15]
	v_mfma_f32_16x16x32_bf16 v[8:11], v[64:67], v[218:221], v[8:11]
	v_mfma_f32_16x16x32_bf16 v[76:79], v[60:63], v[184:187], v[76:79]
	v_mfma_f32_16x16x32_bf16 v[72:75], v[68:71], v[184:187], v[72:75]
	v_mfma_f32_16x16x32_bf16 v[44:47], v[60:63], v[206:209], v[44:47]
	v_mfma_f32_16x16x32_bf16 v[40:43], v[68:71], v[206:209], v[40:43]
	v_mfma_f32_16x16x32_bf16 v[28:31], v[60:63], v[214:217], v[28:31]
	v_mfma_f32_16x16x32_bf16 v[24:27], v[68:71], v[214:217], v[24:27]
	v_mfma_f32_16x16x32_bf16 v[12:15], v[60:63], v[222:225], v[12:15]
	v_mfma_f32_16x16x32_bf16 v[8:11], v[68:71], v[222:225], v[8:11]
	s_setprio 0
	s_setprio 1
	v_mfma_f32_16x16x32_bf16 v[52:55], v[154:157], v[180:183], v[52:55]
	v_mfma_f32_16x16x32_bf16 v[48:51], v[172:175], v[180:183], v[48:51]
	v_mfma_f32_16x16x32_bf16 v[36:39], v[154:157], v[194:197], v[36:39]
	v_mfma_f32_16x16x32_bf16 v[32:35], v[172:175], v[194:197], v[32:35]
	v_mfma_f32_16x16x32_bf16 v[20:23], v[154:157], v[210:213], v[20:23]
	v_mfma_f32_16x16x32_bf16 v[16:19], v[172:175], v[210:213], v[16:19]
	v_mfma_f32_16x16x32_bf16 v[4:7], v[154:157], v[218:221], v[4:7]
	v_mfma_f32_16x16x32_bf16 v[0:3], v[172:175], v[218:221], v[0:3]
	v_mfma_f32_16x16x32_bf16 v[52:55], v[162:165], v[184:187], v[52:55]
	v_mfma_f32_16x16x32_bf16 v[48:51], v[176:179], v[184:187], v[48:51]
	v_mfma_f32_16x16x32_bf16 v[36:39], v[162:165], v[206:209], v[36:39]
	v_mfma_f32_16x16x32_bf16 v[32:35], v[176:179], v[206:209], v[32:35]
	v_mfma_f32_16x16x32_bf16 v[20:23], v[162:165], v[214:217], v[20:23]
	v_mfma_f32_16x16x32_bf16 v[16:19], v[176:179], v[214:217], v[16:19]
	v_mfma_f32_16x16x32_bf16 v[4:7], v[162:165], v[222:225], v[4:7]
	v_mfma_f32_16x16x32_bf16 v[0:3], v[176:179], v[222:225], v[0:3]
	s_setprio 0
	s_barrier
	s_add_i32 s44, s44, 2
	s_add_u32 s4, s4, 0x100
	s_addc_u32 s5, s5, 0
	s_add_u32 s42, s42, 0x100
	s_addc_u32 s43, s43, 0
	s_cmp_gt_u32 s44, 13
	s_cbranch_scc0 .LBB0_1135
	s_and_b64 vcc, exec, s[6:7]
	s_cbranch_vccz .LBB0_1138
	s_barrier

; #define PG8_STAGE(bufoff, gbase, voff) do { _Pragma("unroll") for (int _i = 0; _i < 2; ++_i) \
;         __builtin_amdgcn_global_load_lds((const unsigned*)((const char*)(gbase) + (voff)[_i]), (PG8_LAS unsigned*)(lds + (bufoff) + ldsw + _i * 8192), 16, 0, 0); } while (0)
; #define PG8_LDA(dst, b, h) do { _Pragma("unroll") for (int m = 0; m < 4; ++m) _Pragma("unroll") for (int k = 0; k < 2; ++k) dst[m][k] = *(const PG8_LAS bf16x8*)(lds + PG8_SA(b, h) + aoff + m * 2048 + k * 1024); } while (0)
; #define PG8_LDB(dst, b, h) do { _Pragma("unroll") for (int n = 0; n < 2; ++n) _Pragma("unroll") for (int k = 0; k < 2; ++k) dst[n][k] = *(const PG8_LAS bf16x8*)(lds + PG8_SB(b, h) + boff + n * 2048 + k * 1024); } while (0)
; #define PG8_MMA(ai, bj, At, Bt) do { __builtin_amdgcn_s_setprio(1); _Pragma("unroll") for (int m = 0; m < 4; ++m) _Pragma("unroll") for (int n = 0; n < 2; ++n) _Pragma("unroll") for (int k = 0; k < 2; ++k) \
;         acc[ai][bj][m][n] = __builtin_amdgcn_mfma_f32_16x16x32_bf16(Bt[n][k], At[m][k], acc[ai][bj][m][n], 0, 0, 0); __builtin_amdgcn_s_setprio(0); } while (0)
; #define PG8_WAIT_V(n) asm volatile("s_waitcnt vmcnt(" #n ")" ::: "memory")
; #define PG8_WAIT_L(n) asm volatile("s_waitcnt lgkmcnt(" #n ")" ::: "memory")
; template <class Epi, class Sched, bool ALIGN_EPI = false, bool SP2 = false>
; __device__ __forceinline__ void gemm_phase(PG8_LAS unsigned char* lds, const Gemm g, const Sched& S, const Epi& E) {
;     ...
;             const bool last = (t == nt - 2);
;             const char* a1 = cA + (size_t)(t + 1) * kstep;
;             const char* a2 = last ? nA : cA + (size_t)(t + 2) * kstep; const char* b2 = last ? nB : cB + (size_t)(t + 2) * kstep;
;             const char* a3 = a2 + kstep; const char* b3 = b2 + kstep;
;             if (last && has_next) S.a_ready(nxt);
;             if constexpr (SP2) {
;             PG8_LDB(B0, 0, 0); PG8_LDB(B1, 0, 1); PG8_SCHED; PG8_LDA(At, 0, 0); PG8_STAGE(PG8_SA(1, 1), a1 + hstep, voffA);
;             PG8_WAIT_V(8); PG8_WAIT_L(0); PG8_BAR; PG8_MMA(0, 0, At, B0); PG8_MMA(0, 1, At, B1); PG8_BAR; PG8_SCHED;
;             PG8_LDA(At, 0, 1); PG8_STAGE(PG8_SB(0, 0), b2, voffB); PG8_STAGE(PG8_SB(0, 1), b2 + hstep, voffB); PG8_STAGE(PG8_SA(0, 0), a2, voffA);
;             PG8_WAIT_V(8); PG8_WAIT_L(0); PG8_BAR; PG8_MMA(1, 0, At, B0); PG8_MMA(1, 1, At, B1); PG8_BAR; PG8_SCHED;
.LBB0_1215:
	s_add_u32 s4, s2, 0xfff00080
	s_addc_u32 s5, s3, -1
	s_add_i32 s47, 0, 0x10000
	s_cmp_eq_u32 s46, 60
	s_cselect_b32 s23, s15, s5
	s_cselect_b32 s22, s42, s4
	s_cselect_b32 s5, s17, s45
	s_cselect_b32 s4, s43, s44
	s_add_i32 s50, 0, 0x14000
	v_add_u32_e32 v76, s47, v188
	v_add_u32_e32 v158, s50, v188
	ds_read_b128 v[56:59], v76
	ds_read_b128 v[60:63], v76 offset:1024
	ds_read_b128 v[68:71], v76 offset:2048
	ds_read_b128 v[76:79], v76 offset:3072
	ds_read_b128 v[144:147], v158
	ds_read_b128 v[162:165], v158 offset:1024
	ds_read_b128 v[166:169], v158 offset:2048
	ds_read_b128 v[170:173], v158 offset:3072
	v_lshl_add_u64 v[158:159], s[2:3], 0, v[154:155]
	s_add_i32 m0, s29, 0xc000
	ds_read_b128 v[174:177], v189
	ds_read_b128 v[178:181], v189 offset:1024
	ds_read_b128 v[182:185], v189 offset:2048
	ds_read_b128 v[194:197], v189 offset:3072
	ds_read_b128 v[206:209], v189 offset:4096
	ds_read_b128 v[210:213], v189 offset:5120
	ds_read_b128 v[214:217], v189 offset:6144
	ds_read_b128 v[218:221], v189 offset:7168
	global_load_lds_dwordx4 v[158:159], off
	v_lshl_add_u64 v[158:159], s[2:3], 0, v[156:157]
	s_add_i32 m0, s29, 0xe000
	s_nop 0
	global_load_lds_dwordx4 v[158:159], off
	s_waitcnt vmcnt(8)
	s_waitcnt lgkmcnt(0)
	s_barrier
	s_setprio 1
	v_mfma_f32_16x16x32_bf16 v[64:67], v[56:59], v[174:177], v[64:67]
	v_mfma_f32_16x16x32_bf16 v[140:143], v[68:71], v[174:177], v[140:143]
	v_mfma_f32_16x16x32_bf16 v[128:131], v[56:59], v[182:185], v[128:131]
	v_mfma_f32_16x16x32_bf16 v[124:127], v[68:71], v[182:185], v[124:127]
	v_mfma_f32_16x16x32_bf16 v[112:115], v[56:59], v[206:209], v[112:115]
	v_mfma_f32_16x16x32_bf16 v[108:111], v[68:71], v[206:209], v[108:111]
	v_mfma_f32_16x16x32_bf16 v[96:99], v[56:59], v[214:217], v[96:99]
	v_mfma_f32_16x16x32_bf16 v[92:95], v[68:71], v[214:217], v[92:95]
	v_mfma_f32_16x16x32_bf16 v[64:67], v[60:63], v[178:181], v[64:67]
	v_mfma_f32_16x16x32_bf16 v[140:143], v[76:79], v[178:181], v[140:143]
	v_mfma_f32_16x16x32_bf16 v[128:131], v[60:63], v[194:197], v[128:131]
	v_mfma_f32_16x16x32_bf16 v[124:127], v[76:79], v[194:197], v[124:127]
	v_mfma_f32_16x16x32_bf16 v[112:115], v[60:63], v[210:213], v[112:115]
	v_mfma_f32_16x16x32_bf16 v[108:111], v[76:79], v[210:213], v[108:111]
	v_mfma_f32_16x16x32_bf16 v[96:99], v[60:63], v[218:221], v[96:99]
	v_mfma_f32_16x16x32_bf16 v[92:95], v[76:79], v[218:221], v[92:95]
	s_setprio 0
	s_setprio 1
	v_mfma_f32_16x16x32_bf16 v[136:139], v[144:147], v[174:177], v[136:139]
	v_mfma_f32_16x16x32_bf16 v[132:135], v[166:169], v[174:177], v[132:135]
	v_mfma_f32_16x16x32_bf16 v[120:123], v[144:147], v[182:185], v[120:123]
	v_mfma_f32_16x16x32_bf16 v[116:119], v[166:169], v[182:185], v[116:119]
	v_mfma_f32_16x16x32_bf16 v[104:107], v[144:147], v[206:209], v[104:107]
	v_mfma_f32_16x16x32_bf16 v[100:103], v[166:169], v[206:209], v[100:103]
	v_mfma_f32_16x16x32_bf16 v[88:91], v[144:147], v[214:217], v[88:91]
	v_mfma_f32_16x16x32_bf16 v[84:87], v[166:169], v[214:217], v[84:87]
	v_mfma_f32_16x16x32_bf16 v[136:139], v[162:165], v[178:181], v[136:139]
	v_mfma_f32_16x16x32_bf16 v[132:135], v[170:173], v[178:181], v[132:135]
	v_mfma_f32_16x16x32_bf16 v[120:123], v[162:165], v[194:197], v[120:123]
	v_mfma_f32_16x16x32_bf16 v[116:119], v[170:173], v[194:197], v[116:119]
	v_mfma_f32_16x16x32_bf16 v[104:107], v[162:165], v[210:213], v[104:107]
	v_mfma_f32_16x16x32_bf16 v[100:103], v[170:173], v[210:213], v[100:103]
	v_mfma_f32_16x16x32_bf16 v[88:91], v[162:165], v[218:221], v[88:91]
	v_mfma_f32_16x16x32_bf16 v[84:87], v[170:173], v[218:221], v[84:87]
	s_setprio 0
	s_barrier
	s_add_i32 s47, s47, s28
	v_lshl_add_u64 v[158:159], s[4:5], 0, v[160:161]
	s_mov_b32 m0, s47
	ds_read_b128 v[174:177], v189 offset:16384
	ds_read_b128 v[178:181], v189 offset:17408
	ds_read_b128 v[182:185], v189 offset:18432
	ds_read_b128 v[194:197], v189 offset:19456
	ds_read_b128 v[206:209], v189 offset:20480
	ds_read_b128 v[210:213], v189 offset:21504
	ds_read_b128 v[214:217], v189 offset:22528
	ds_read_b128 v[218:221], v189 offset:23552
	global_load_lds_dwordx4 v[158:159], off
	s_add_i32 m0, s47, 0x2000
	s_add_u32 s48, s4, 0x100000
	v_lshl_add_u64 v[186:187], s[4:5], 0, v[148:149]
	s_addc_u32 s49, s5, 0
	s_add_i32 s47, s50, s28
	global_load_lds_dwordx4 v[186:187], off
	v_lshl_add_u64 v[222:223], s[48:49], 0, v[160:161]
	s_mov_b32 m0, s47
	v_lshl_add_u64 v[224:225], s[22:23], 0, v[150:151]
	global_load_lds_dwordx4 v[222:223], off
	v_lshl_add_u64 v[222:223], s[48:49], 0, v[148:149]
	s_add_i32 m0, s47, 0x2000
	s_nop 0
	global_load_lds_dwordx4 v[222:223], off
	v_lshl_add_u64 v[222:223], s[22:23], 0, v[152:153]
	s_mov_b32 m0, s29
	s_nop 0
	global_load_lds_dwordx4 v[222:223], off
	s_mov_b32 m0, s30
	s_nop 0
	global_load_lds_dwordx4 v[224:225], off
	s_waitcnt vmcnt(8)
	s_waitcnt lgkmcnt(0)
	s_barrier
; #define PG8_STAGE(bufoff, gbase, voff) do { _Pragma("unroll") for (int _i = 0; _i < 2; ++_i) \
;         __builtin_amdgcn_global_load_lds((const unsigned*)((const char*)(gbase) + (voff)[_i]), (PG8_LAS unsigned*)(lds + (bufoff) + ldsw + _i * 8192), 16, 0, 0); } while (0)
; #define PG8_LDA(dst, b, h) do { _Pragma("unroll") for (int m = 0; m < 4; ++m) _Pragma("unroll") for (int k = 0; k < 2; ++k) dst[m][k] = *(const PG8_LAS bf16x8*)(lds + PG8_SA(b, h) + aoff + m * 2048 + k * 1024); } while (0)
; #define PG8_LDB(dst, b, h) do { _Pragma("unroll") for (int n = 0; n < 2; ++n) _Pragma("unroll") for (int k = 0; k < 2; ++k) dst[n][k] = *(const PG8_LAS bf16x8*)(lds + PG8_SB(b, h) + boff + n * 2048 + k * 1024); } while (0)
; #define PG8_MMA(ai, bj, At, Bt) do { __builtin_amdgcn_s_setprio(1); _Pragma("unroll") for (int m = 0; m < 4; ++m) _Pragma("unroll") for (int n = 0; n < 2; ++n) _Pragma("unroll") for (int k = 0; k < 2; ++k) \
;         acc[ai][bj][m][n] = __builtin_amdgcn_mfma_f32_16x16x32_bf16(Bt[n][k], At[m][k], acc[ai][bj][m][n], 0, 0, 0); __builtin_amdgcn_s_setprio(0); } while (0)
; #define PG8_WAIT_V(n) asm volatile("s_waitcnt vmcnt(" #n ")" ::: "memory")
; #define PG8_WAIT_L(n) asm volatile("s_waitcnt lgkmcnt(" #n ")" ::: "memory")
; #define PG8_BAR __builtin_amdgcn_s_barrier()
; #define PG8_SCHED __builtin_amdgcn_sched_barrier(0)
; template <class Epi, class Sched, bool ALIGN_EPI = false, bool SP2 = false>
; __device__ __forceinline__ void gemm_phase(PG8_LAS unsigned char* lds, const Gemm g, const Sched& S, const Epi& E) {
;     ...
;             PG8_WAIT_V(8); PG8_WAIT_L(0); PG8_BAR; PG8_MMA(1, 0, At, B0); PG8_MMA(1, 1, At, B1); PG8_BAR; PG8_SCHED;
;             PG8_LDB(B0, 1, 0); PG8_LDB(B1, 1, 1); PG8_SCHED; PG8_LDA(At, 1, 0); PG8_STAGE(PG8_SA(0, 1), a2 + hstep, voffA);
;             PG8_WAIT_V(8); PG8_WAIT_L(0); PG8_BAR; PG8_MMA(0, 0, At, B0); PG8_MMA(0, 1, At, B1); PG8_BAR; PG8_SCHED;
	s_setprio 1
	v_mfma_f32_16x16x32_bf16 v[80:83], v[56:59], v[174:177], v[80:83]
	v_mfma_f32_16x16x32_bf16 v[72:75], v[68:71], v[174:177], v[72:75]
	v_mfma_f32_16x16x32_bf16 v[44:47], v[56:59], v[182:185], v[44:47]
	v_mfma_f32_16x16x32_bf16 v[40:43], v[68:71], v[182:185], v[40:43]
	v_mfma_f32_16x16x32_bf16 v[28:31], v[56:59], v[206:209], v[28:31]
	v_mfma_f32_16x16x32_bf16 v[24:27], v[68:71], v[206:209], v[24:27]
	v_mfma_f32_16x16x32_bf16 v[12:15], v[56:59], v[214:217], v[12:15]
	v_mfma_f32_16x16x32_bf16 v[8:11], v[68:71], v[214:217], v[8:11]
	v_mfma_f32_16x16x32_bf16 v[80:83], v[60:63], v[178:181], v[80:83]
	v_mfma_f32_16x16x32_bf16 v[72:75], v[76:79], v[178:181], v[72:75]
	v_mfma_f32_16x16x32_bf16 v[44:47], v[60:63], v[194:197], v[44:47]
	v_mfma_f32_16x16x32_bf16 v[40:43], v[76:79], v[194:197], v[40:43]
	v_mfma_f32_16x16x32_bf16 v[28:31], v[60:63], v[210:213], v[28:31]
	v_mfma_f32_16x16x32_bf16 v[24:27], v[76:79], v[210:213], v[24:27]
	v_mfma_f32_16x16x32_bf16 v[12:15], v[60:63], v[218:221], v[12:15]
	v_mfma_f32_16x16x32_bf16 v[8:11], v[76:79], v[218:221], v[8:11]
	s_setprio 0
	s_setprio 1
	v_mfma_f32_16x16x32_bf16 v[52:55], v[144:147], v[174:177], v[52:55]
	v_mfma_f32_16x16x32_bf16 v[48:51], v[166:169], v[174:177], v[48:51]
	v_mfma_f32_16x16x32_bf16 v[36:39], v[144:147], v[182:185], v[36:39]
	v_mfma_f32_16x16x32_bf16 v[32:35], v[166:169], v[182:185], v[32:35]
	v_mfma_f32_16x16x32_bf16 v[20:23], v[144:147], v[206:209], v[20:23]
	v_mfma_f32_16x16x32_bf16 v[16:19], v[166:169], v[206:209], v[16:19]
	v_mfma_f32_16x16x32_bf16 v[4:7], v[144:147], v[214:217], v[4:7]
	v_mfma_f32_16x16x32_bf16 v[0:3], v[166:169], v[214:217], v[0:3]
	v_mfma_f32_16x16x32_bf16 v[52:55], v[162:165], v[178:181], v[52:55]
	v_mfma_f32_16x16x32_bf16 v[48:51], v[170:173], v[178:181], v[48:51]
	v_mfma_f32_16x16x32_bf16 v[36:39], v[162:165], v[194:197], v[36:39]
	v_mfma_f32_16x16x32_bf16 v[32:35], v[170:173], v[194:197], v[32:35]
	v_mfma_f32_16x16x32_bf16 v[20:23], v[162:165], v[210:213], v[20:23]
	v_mfma_f32_16x16x32_bf16 v[16:19], v[170:173], v[210:213], v[16:19]
	v_mfma_f32_16x16x32_bf16 v[4:7], v[162:165], v[218:221], v[4:7]
	v_mfma_f32_16x16x32_bf16 v[0:3], v[170:173], v[218:221], v[0:3]
	s_setprio 0
	s_barrier
	s_add_i32 s47, 0, 0x18000
	s_add_i32 s48, 0, 0x1c000
	v_add_u32_e32 v76, s47, v188
	v_add_u32_e32 v170, s48, v188
	ds_read_b128 v[56:59], v76
	ds_read_b128 v[60:63], v76 offset:1024
	ds_read_b128 v[68:71], v76 offset:2048
	ds_read_b128 v[76:79], v76 offset:3072
	ds_read_b128 v[144:147], v170
	ds_read_b128 v[162:165], v170 offset:1024
	ds_read_b128 v[166:169], v170 offset:2048
	ds_read_b128 v[170:173], v170 offset:3072
	s_add_u32 s22, s22, 0x100000
	s_addc_u32 s23, s23, 0
	s_mov_b32 m0, s31
	v_lshl_add_u64 v[226:227], s[22:23], 0, v[152:153]
	ds_read_b128 v[174:177], v189 offset:32768
	ds_read_b128 v[178:181], v189 offset:33792
	ds_read_b128 v[182:185], v189 offset:34816
	ds_read_b128 v[194:197], v189 offset:35840
	ds_read_b128 v[206:209], v189 offset:36864
	ds_read_b128 v[210:213], v189 offset:37888
	ds_read_b128 v[214:217], v189 offset:38912
	ds_read_b128 v[218:221], v189 offset:39936
	global_load_lds_dwordx4 v[226:227], off
	v_lshl_add_u64 v[226:227], s[22:23], 0, v[150:151]
	s_mov_b32 m0, s34
	s_nop 0
	global_load_lds_dwordx4 v[226:227], off
	s_waitcnt vmcnt(8)
	s_waitcnt lgkmcnt(0)
	s_barrier
	s_setprio 1
	v_mfma_f32_16x16x32_bf16 v[64:67], v[56:59], v[174:177], v[64:67]
	v_mfma_f32_16x16x32_bf16 v[140:143], v[68:71], v[174:177], v[140:143]
	v_mfma_f32_16x16x32_bf16 v[128:131], v[56:59], v[182:185], v[128:131]
	v_mfma_f32_16x16x32_bf16 v[124:127], v[68:71], v[182:185], v[124:127]
	v_mfma_f32_16x16x32_bf16 v[112:115], v[56:59], v[206:209], v[112:115]
	v_mfma_f32_16x16x32_bf16 v[108:111], v[68:71], v[206:209], v[108:111]
	v_mfma_f32_16x16x32_bf16 v[96:99], v[56:59], v[214:217], v[96:99]
	v_mfma_f32_16x16x32_bf16 v[92:95], v[68:71], v[214:217], v[92:95]
	v_mfma_f32_16x16x32_bf16 v[64:67], v[60:63], v[178:181], v[64:67]
	v_mfma_f32_16x16x32_bf16 v[140:143], v[76:79], v[178:181], v[140:143]
	v_mfma_f32_16x16x32_bf16 v[128:131], v[60:63], v[194:197], v[128:131]
	v_mfma_f32_16x16x32_bf16 v[124:127], v[76:79], v[194:197], v[124:127]
	v_mfma_f32_16x16x32_bf16 v[112:115], v[60:63], v[210:213], v[112:115]
	v_mfma_f32_16x16x32_bf16 v[108:111], v[76:79], v[210:213], v[108:111]
	v_mfma_f32_16x16x32_bf16 v[96:99], v[60:63], v[218:221], v[96:99]
	v_mfma_f32_16x16x32_bf16 v[92:95], v[76:79], v[218:221], v[92:95]
	s_setprio 0
	s_setprio 1
	v_mfma_f32_16x16x32_bf16 v[136:139], v[144:147], v[174:177], v[136:139]
	v_mfma_f32_16x16x32_bf16 v[132:135], v[166:169], v[174:177], v[132:135]
	v_mfma_f32_16x16x32_bf16 v[120:123], v[144:147], v[182:185], v[120:123]
	v_mfma_f32_16x16x32_bf16 v[116:119], v[166:169], v[182:185], v[116:119]
	v_mfma_f32_16x16x32_bf16 v[104:107], v[144:147], v[206:209], v[104:107]
	v_mfma_f32_16x16x32_bf16 v[100:103], v[166:169], v[206:209], v[100:103]
	v_mfma_f32_16x16x32_bf16 v[88:91], v[144:147], v[214:217], v[88:91]
	v_mfma_f32_16x16x32_bf16 v[84:87], v[166:169], v[214:217], v[84:87]
	v_mfma_f32_16x16x32_bf16 v[136:139], v[162:165], v[178:181], v[136:139]
	v_mfma_f32_16x16x32_bf16 v[132:135], v[170:173], v[178:181], v[132:135]
	v_mfma_f32_16x16x32_bf16 v[120:123], v[162:165], v[194:197], v[120:123]
	v_mfma_f32_16x16x32_bf16 v[116:119], v[170:173], v[194:197], v[116:119]
	v_mfma_f32_16x16x32_bf16 v[104:107], v[162:165], v[210:213], v[104:107]
	v_mfma_f32_16x16x32_bf16 v[100:103], v[170:173], v[210:213], v[100:103]
	v_mfma_f32_16x16x32_bf16 v[88:91], v[162:165], v[218:221], v[88:91]
	v_mfma_f32_16x16x32_bf16 v[84:87], v[170:173], v[218:221], v[84:87]
	s_setprio 0
	s_barrier
; #define PG8_STAGE(bufoff, gbase, voff) do { _Pragma("unroll") for (int _i = 0; _i < 2; ++_i) \
;         __builtin_amdgcn_global_load_lds((const unsigned*)((const char*)(gbase) + (voff)[_i]), (PG8_LAS unsigned*)(lds + (bufoff) + ldsw + _i * 8192), 16, 0, 0); } while (0)
; #define PG8_LDA(dst, b, h) do { _Pragma("unroll") for (int m = 0; m < 4; ++m) _Pragma("unroll") for (int k = 0; k < 2; ++k) dst[m][k] = *(const PG8_LAS bf16x8*)(lds + PG8_SA(b, h) + aoff + m * 2048 + k * 1024); } while (0)
; #define PG8_MMA(ai, bj, At, Bt) do { __builtin_amdgcn_s_setprio(1); _Pragma("unroll") for (int m = 0; m < 4; ++m) _Pragma("unroll") for (int n = 0; n < 2; ++n) _Pragma("unroll") for (int k = 0; k < 2; ++k) \
;         acc[ai][bj][m][n] = __builtin_amdgcn_mfma_f32_16x16x32_bf16(Bt[n][k], At[m][k], acc[ai][bj][m][n], 0, 0, 0); __builtin_amdgcn_s_setprio(0); } while (0)
; #define PG8_WAIT_V(n) asm volatile("s_waitcnt vmcnt(" #n ")" ::: "memory")
; #define PG8_WAIT_L(n) asm volatile("s_waitcnt lgkmcnt(" #n ")" ::: "memory")
; #define PG8_BAR __builtin_amdgcn_s_barrier()
; #define PG8_SCHED __builtin_amdgcn_sched_barrier(0)
; template <class Epi, class Sched, bool ALIGN_EPI = false, bool SP2 = false>
; __device__ __forceinline__ void gemm_phase(PG8_LAS unsigned char* lds, const Gemm g, const Sched& S, const Epi& E) {
;     ...
;         for (int t = 0; t < nt; t += 2) {
;             const bool last = (t == nt - 2);
;             const char* a1 = cA + (size_t)(t + 1) * kstep;
;             const char* a2 = last ? nA : cA + (size_t)(t + 2) * kstep; const char* b2 = last ? nB : cB + (size_t)(t + 2) * kstep;
;     ...
;             PG8_LDA(At, 1, 1); PG8_STAGE(PG8_SB(1, 0), b3, voffB); PG8_STAGE(PG8_SB(1, 1), b3 + hstep, voffB); PG8_STAGE(PG8_SA(1, 0), a3, voffA);
;             PG8_WAIT_V(8); PG8_WAIT_L(0); PG8_BAR; PG8_MMA(1, 0, At, B0); PG8_MMA(1, 1, At, B1); PG8_BAR; PG8_SCHED;
	s_add_i32 s22, s47, s28
	v_lshl_add_u64 v[158:159], v[158:159], 0, s[38:39]
	s_mov_b32 m0, s22
	ds_read_b128 v[174:177], v189 offset:49152
	ds_read_b128 v[178:181], v189 offset:50176
	ds_read_b128 v[182:185], v189 offset:51200
	ds_read_b128 v[194:197], v189 offset:52224
	ds_read_b128 v[206:209], v189 offset:53248
	ds_read_b128 v[210:213], v189 offset:54272
	ds_read_b128 v[214:217], v189 offset:55296
	ds_read_b128 v[218:221], v189 offset:56320
	global_load_lds_dwordx4 v[158:159], off
	s_add_i32 m0, s22, 0x2000
	s_add_u32 s4, s4, 0x100080
	v_lshl_add_u64 v[158:159], v[186:187], 0, s[38:39]
	s_addc_u32 s5, s5, 0
	s_add_i32 s22, s48, s28
	global_load_lds_dwordx4 v[158:159], off
	v_lshl_add_u64 v[158:159], s[4:5], 0, v[160:161]
	s_mov_b32 m0, s22
	s_nop 0
	global_load_lds_dwordx4 v[158:159], off
	v_lshl_add_u64 v[158:159], s[4:5], 0, v[148:149]
	s_add_i32 m0, s22, 0x2000
	s_nop 0
	global_load_lds_dwordx4 v[158:159], off
	v_lshl_add_u64 v[158:159], v[222:223], 0, s[38:39]
	s_mov_b32 m0, s37
	s_nop 0
	global_load_lds_dwordx4 v[158:159], off
	v_lshl_add_u64 v[158:159], v[224:225], 0, s[38:39]
	s_mov_b32 m0, s40
	s_nop 0
	global_load_lds_dwordx4 v[158:159], off
	s_waitcnt vmcnt(8)
	s_waitcnt lgkmcnt(0)
	s_barrier
	s_setprio 1
	v_mfma_f32_16x16x32_bf16 v[80:83], v[56:59], v[174:177], v[80:83]
	v_mfma_f32_16x16x32_bf16 v[72:75], v[68:71], v[174:177], v[72:75]
	v_mfma_f32_16x16x32_bf16 v[44:47], v[56:59], v[182:185], v[44:47]
	v_mfma_f32_16x16x32_bf16 v[40:43], v[68:71], v[182:185], v[40:43]
	v_mfma_f32_16x16x32_bf16 v[28:31], v[56:59], v[206:209], v[28:31]
	v_mfma_f32_16x16x32_bf16 v[24:27], v[68:71], v[206:209], v[24:27]
	v_mfma_f32_16x16x32_bf16 v[12:15], v[56:59], v[214:217], v[12:15]
	v_mfma_f32_16x16x32_bf16 v[8:11], v[68:71], v[214:217], v[8:11]
	v_mfma_f32_16x16x32_bf16 v[80:83], v[60:63], v[178:181], v[80:83]
	v_mfma_f32_16x16x32_bf16 v[72:75], v[76:79], v[178:181], v[72:75]
	v_mfma_f32_16x16x32_bf16 v[44:47], v[60:63], v[194:197], v[44:47]
	v_mfma_f32_16x16x32_bf16 v[40:43], v[76:79], v[194:197], v[40:43]
	v_mfma_f32_16x16x32_bf16 v[28:31], v[60:63], v[210:213], v[28:31]
	v_mfma_f32_16x16x32_bf16 v[24:27], v[76:79], v[210:213], v[24:27]
	v_mfma_f32_16x16x32_bf16 v[12:15], v[60:63], v[218:221], v[12:15]
	v_mfma_f32_16x16x32_bf16 v[8:11], v[76:79], v[218:221], v[8:11]
	s_setprio 0
	s_setprio 1
	v_mfma_f32_16x16x32_bf16 v[52:55], v[144:147], v[174:177], v[52:55]
	v_mfma_f32_16x16x32_bf16 v[48:51], v[166:169], v[174:177], v[48:51]
	v_mfma_f32_16x16x32_bf16 v[36:39], v[144:147], v[182:185], v[36:39]
	v_mfma_f32_16x16x32_bf16 v[32:35], v[166:169], v[182:185], v[32:35]
	v_mfma_f32_16x16x32_bf16 v[20:23], v[144:147], v[206:209], v[20:23]
	v_mfma_f32_16x16x32_bf16 v[16:19], v[166:169], v[206:209], v[16:19]
	v_mfma_f32_16x16x32_bf16 v[4:7], v[144:147], v[214:217], v[4:7]
	v_mfma_f32_16x16x32_bf16 v[0:3], v[166:169], v[214:217], v[0:3]
	v_mfma_f32_16x16x32_bf16 v[52:55], v[162:165], v[178:181], v[52:55]
	v_mfma_f32_16x16x32_bf16 v[48:51], v[170:173], v[178:181], v[48:51]
	v_mfma_f32_16x16x32_bf16 v[36:39], v[162:165], v[194:197], v[36:39]
	v_mfma_f32_16x16x32_bf16 v[32:35], v[170:173], v[194:197], v[32:35]
	v_mfma_f32_16x16x32_bf16 v[20:23], v[162:165], v[210:213], v[20:23]
	v_mfma_f32_16x16x32_bf16 v[16:19], v[170:173], v[210:213], v[16:19]
	v_mfma_f32_16x16x32_bf16 v[4:7], v[162:165], v[218:221], v[4:7]
	v_mfma_f32_16x16x32_bf16 v[0:3], v[170:173], v[218:221], v[0:3]
	s_setprio 0
	s_barrier
	s_add_i32 s46, s46, 2
	s_add_u32 s2, s2, 0x100
	s_addc_u32 s3, s3, 0
	s_add_u32 s44, s44, 0x100
	s_addc_u32 s45, s45, 0
	s_cmp_gt_u32 s46, 61
	s_cbranch_scc0 .LBB0_1215
	s_and_b64 vcc, exec, s[10:11]
	s_cbranch_vccz .LBB0_1218
	s_barrier
